# v11: v8 + hand-written rows_bf16_to_i8 pre-passes of G_OUT and G_PP with 3 rows of loads in flight (derived vmcnt)
# baseline (speedup 1.0000x reference)
; __device__ __forceinline__ unsigned q8(float x) { return (unsigned)(int)__builtin_rintf(x) & 0xffu; }
; __device__ __forceinline__ void rows_bf16_to_i8(Frame& F, const bf16* XBp, const unsigned* rmax, unsigned* X8, float* sx, int pitch4 = D / 4) {
;     const int gw = F.vcu * NWAVES + F.wave, NGW = F.G * NWAVES, lane = F.lane;
;     v4u w[8], wn[8]; unsigned rb = 0, rbn = 0;
;     int m = gw;
;     if (m < M) { const v4u* src = (const v4u*)(XBp + (size_t)m * D) + lane; rb = rmax[m];
; #pragma unroll
;         for (int j = 0; j < 8; ++j) w[j] = src[64 * j]; }
;     for (; m < M; m += NGW) {
;         const int mn = m + NGW;
;         if (mn < M) { const v4u* src = (const v4u*)(XBp + (size_t)mn * D) + lane; rbn = rmax[mn];
; #pragma unroll
;             for (int j = 0; j < 8; ++j) wn[j] = src[64 * j]; }
;         const float mx = __builtin_bit_cast(float, rb), inv = mx > 0.f ? 127.0f / mx : 0.f;
;         v2u* dst = (v2u*)(X8 + (size_t)m * pitch4) + lane;
; #pragma unroll
;         for (int j = 0; j < 8; ++j) { v2u o;
;             o.x = q8(blo(w[j].x) * inv) | (q8(bhi(w[j].x) * inv) << 8) | (q8(blo(w[j].y) * inv) << 16) | (q8(bhi(w[j].y) * inv) << 24);
;             o.y = q8(blo(w[j].z) * inv) | (q8(bhi(w[j].z) * inv) << 8) | (q8(blo(w[j].w) * inv) << 16) | (q8(bhi(w[j].w) * inv) << 24);
;             dst[64 * j] = o; }
;         if (lane == 0) sx[m] = mx * (1.0f / 127.0f);
; #pragma unroll
;         for (int j = 0; j < 8; ++j) w[j] = wn[j];
;         rb = rbn;
;     }
; }
; __global__ void __launch_bounds__(NWAVES * 64, 2) mk_fwd(Args args) {
;     ...
;     if (IN(G_OUT)) {
;         rows_bf16_to_i8(F, (const bf16*)(ws + WS_MERGED), (const unsigned*)(ws + CTL_RMAX3), (unsigned*)(ws + WS_X8C), (float*)(ws + WS_SX3));
.LBB0_1642:
	s_cmp_lt_i32 s72, 10
	s_cselect_b64 s[0:1], -1, 0
	s_cmp_gt_i32 s73, 9
	s_cselect_b64 s[2:3], -1, 0
	s_and_b64 s[0:1], s[0:1], s[2:3]
	s_andn2_b64 vcc, exec, s[0:1]
	s_cbranch_vccnz .LBB0_1846
	v_readlane_b32 s0, v254, 6
	s_cmp_lg_u32 s0, 0x100
	s_cbranch_scc1 .Lrows3_fb_gout
	v_readlane_b32 s0, v254, 5
	v_readlane_b32 s1, v254, 39
	s_lshl_b32 s0, s0, 3
	s_add_i32 s0, s0, s1
	s_waitcnt vmcnt(0) lgkmcnt(0)
	s_add_u32 s4, s96, 0x1e400000
	s_addc_u32 s5, s97, 0
	s_lshl_b32 s2, s0, 13
	s_add_u32 s4, s4, s2
	s_addc_u32 s5, s5, 0
	s_lshl_b32 s2, s0, 2
	s_add_u32 s6, s96, s2
	s_addc_u32 s7, s97, 0
	s_add_u32 s8, s6, 0x4d4b0000
	s_addc_u32 s9, s7, 0
	s_add_u32 s6, s6, 0xc0000
	s_addc_u32 s7, s7, 0
	s_lshl_b32 s2, s0, 12
	s_add_u32 s10, s96, s2
	s_addc_u32 s11, s97, 0
	s_add_u32 s10, s10, 0x15400000
	s_addc_u32 s11, s11, 0
	v_and_b32_e32 v133, 63, v0
	v_lshlrev_b32_e32 v134, 4, v133
	v_add_u32_e32 v135, 0x1000, v134
	v_lshlrev_b32_e32 v136, 3, v133
	v_mov_b32_e32 v137, 0
	v_cmp_eq_u32_e64 s[12:13], 0, v133
	s_mov_b32 s3, 0x42fe0000
	s_mov_b32 s16, 0xc0c0400
	s_mov_b32 s17, 0x4000c0c
	global_load_dword v98, v137, s[6:7]
	global_load_dwordx4 v[2:5], v134, s[4:5] offset:0
	global_load_dwordx4 v[6:9], v134, s[4:5] offset:1024
	global_load_dwordx4 v[10:13], v134, s[4:5] offset:2048
	global_load_dwordx4 v[14:17], v134, s[4:5] offset:3072
	global_load_dwordx4 v[18:21], v135, s[4:5] offset:0
	global_load_dwordx4 v[22:25], v135, s[4:5] offset:1024
	global_load_dwordx4 v[26:29], v135, s[4:5] offset:2048
	global_load_dwordx4 v[30:33], v135, s[4:5] offset:3072
	s_add_u32 s4, s4, 0x1000000
	s_addc_u32 s5, s5, 0
	s_add_u32 s6, s6, 0x2000
	s_addc_u32 s7, s7, 0
	global_load_dword v99, v137, s[6:7]
	global_load_dwordx4 v[34:37], v134, s[4:5] offset:0
	global_load_dwordx4 v[38:41], v134, s[4:5] offset:1024
	global_load_dwordx4 v[42:45], v134, s[4:5] offset:2048
	global_load_dwordx4 v[46:49], v134, s[4:5] offset:3072
	global_load_dwordx4 v[50:53], v135, s[4:5] offset:0
	global_load_dwordx4 v[54:57], v135, s[4:5] offset:1024
	global_load_dwordx4 v[58:61], v135, s[4:5] offset:2048
	global_load_dwordx4 v[62:65], v135, s[4:5] offset:3072
	s_add_u32 s4, s4, 0x1000000
	s_addc_u32 s5, s5, 0
	s_add_u32 s6, s6, 0x2000
	s_addc_u32 s7, s7, 0
	global_load_dword v100, v137, s[6:7]
	global_load_dwordx4 v[66:69], v134, s[4:5] offset:0
	global_load_dwordx4 v[70:73], v134, s[4:5] offset:1024
	global_load_dwordx4 v[74:77], v134, s[4:5] offset:2048
	global_load_dwordx4 v[78:81], v134, s[4:5] offset:3072
	global_load_dwordx4 v[82:85], v135, s[4:5] offset:0
	global_load_dwordx4 v[86:89], v135, s[4:5] offset:1024
	global_load_dwordx4 v[90:93], v135, s[4:5] offset:2048
	global_load_dwordx4 v[94:97], v135, s[4:5] offset:3072
	s_add_u32 s4, s4, 0x1000000
	s_addc_u32 s5, s5, 0
	s_add_u32 s6, s6, 0x2000
	s_addc_u32 s7, s7, 0
	s_waitcnt vmcnt(26)
	v_div_scale_f32 v128, s[14:15], v98, v98, s3
	v_rcp_f32_e32 v129, v128
	v_div_scale_f32 v130, vcc, s3, v98, s3
	v_fma_f32 v131, -v128, v129, 1.0
	v_fmac_f32_e32 v129, v131, v129
	v_mul_f32_e32 v131, v130, v129
	v_fma_f32 v132, -v128, v131, v130
	v_fmac_f32_e32 v131, v132, v129
	v_fma_f32 v128, -v128, v131, v130
	v_div_fmas_f32 v128, v128, v129, v131
	v_div_fixup_f32 v128, v128, v98, s3
	v_cmp_lt_f32_e32 vcc, 0, v98
	v_mul_f32_e32 v138, 0x3c010204, v98
	v_cndmask_b32_e32 v126, 0, v128, vcc
	v_mov_b32_e32 v127, v126
	s_waitcnt vmcnt(25)
	v_lshlrev_b32_e32 v118, 16, v2
	v_and_b32_e32 v119, 0xffff0000, v2
	v_lshlrev_b32_e32 v120, 16, v3
	v_and_b32_e32 v121, 0xffff0000, v3
	v_pk_mul_f32 v[118:119], v[126:127], v[118:119]
	v_pk_mul_f32 v[120:121], v[126:127], v[120:121]
	v_rndne_f32_e32 v118, v118
	v_rndne_f32_e32 v119, v119
	v_rndne_f32_e32 v120, v120
	v_rndne_f32_e32 v121, v121
	v_cvt_i32_f32_e32 v118, v118
	v_cvt_i32_f32_e32 v119, v119
	v_cvt_i32_f32_e32 v120, v120
	v_cvt_i32_f32_e32 v121, v121
	v_perm_b32 v118, v119, v118, s16
	v_perm_b32 v120, v121, v120, s17
	v_or_b32_e32 v102, v118, v120
	v_lshlrev_b32_e32 v118, 16, v4
	v_and_b32_e32 v119, 0xffff0000, v4
	v_lshlrev_b32_e32 v120, 16, v5
	v_and_b32_e32 v121, 0xffff0000, v5
	v_pk_mul_f32 v[118:119], v[126:127], v[118:119]
	v_pk_mul_f32 v[120:121], v[126:127], v[120:121]
	v_rndne_f32_e32 v118, v118
	v_rndne_f32_e32 v119, v119
	v_rndne_f32_e32 v120, v120
	v_rndne_f32_e32 v121, v121
	v_cvt_i32_f32_e32 v118, v118
	v_cvt_i32_f32_e32 v119, v119
	v_cvt_i32_f32_e32 v120, v120
	v_cvt_i32_f32_e32 v121, v121
	v_perm_b32 v118, v119, v118, s16
	v_perm_b32 v120, v121, v120, s17
	v_or_b32_e32 v103, v118, v120
	global_store_dwordx2 v136, v[102:103], s[10:11] offset:0
	s_waitcnt vmcnt(25)
	v_lshlrev_b32_e32 v118, 16, v6
	v_and_b32_e32 v119, 0xffff0000, v6
	v_lshlrev_b32_e32 v120, 16, v7
	v_and_b32_e32 v121, 0xffff0000, v7
	v_pk_mul_f32 v[118:119], v[126:127], v[118:119]
	v_pk_mul_f32 v[120:121], v[126:127], v[120:121]
	v_rndne_f32_e32 v118, v118
	v_rndne_f32_e32 v119, v119
	v_rndne_f32_e32 v120, v120
	v_rndne_f32_e32 v121, v121
	v_cvt_i32_f32_e32 v118, v118
	v_cvt_i32_f32_e32 v119, v119
	v_cvt_i32_f32_e32 v120, v120
	v_cvt_i32_f32_e32 v121, v121
	v_perm_b32 v118, v119, v118, s16
	v_perm_b32 v120, v121, v120, s17
	v_or_b32_e32 v104, v118, v120
	v_lshlrev_b32_e32 v118, 16, v8
	v_and_b32_e32 v119, 0xffff0000, v8
	v_lshlrev_b32_e32 v120, 16, v9
	v_and_b32_e32 v121, 0xffff0000, v9
	v_pk_mul_f32 v[118:119], v[126:127], v[118:119]
	v_pk_mul_f32 v[120:121], v[126:127], v[120:121]
	v_rndne_f32_e32 v118, v118
	v_rndne_f32_e32 v119, v119
	v_rndne_f32_e32 v120, v120
	v_rndne_f32_e32 v121, v121
	v_cvt_i32_f32_e32 v118, v118
	v_cvt_i32_f32_e32 v119, v119
	v_cvt_i32_f32_e32 v120, v120
	v_cvt_i32_f32_e32 v121, v121
	v_perm_b32 v118, v119, v118, s16
	v_perm_b32 v120, v121, v120, s17
	v_or_b32_e32 v105, v118, v120
	global_store_dwordx2 v136, v[104:105], s[10:11] offset:512
	s_waitcnt vmcnt(25)
; __device__ __forceinline__ unsigned q8(float x) { return (unsigned)(int)__builtin_rintf(x) & 0xffu; }
; __device__ __forceinline__ void rows_bf16_to_i8(Frame& F, const bf16* XBp, const unsigned* rmax, unsigned* X8, float* sx, int pitch4 = D / 4) {
;     ...
; #pragma unroll
;         for (int j = 0; j < 8; ++j) { v2u o;
;             o.x = q8(blo(w[j].x) * inv) | (q8(bhi(w[j].x) * inv) << 8) | (q8(blo(w[j].y) * inv) << 16) | (q8(bhi(w[j].y) * inv) << 24);
;             o.y = q8(blo(w[j].z) * inv) | (q8(bhi(w[j].z) * inv) << 8) | (q8(blo(w[j].w) * inv) << 16) | (q8(bhi(w[j].w) * inv) << 24);
;             dst[64 * j] = o; }
	v_lshlrev_b32_e32 v118, 16, v10
	v_and_b32_e32 v119, 0xffff0000, v10
	v_lshlrev_b32_e32 v120, 16, v11
	v_and_b32_e32 v121, 0xffff0000, v11
	v_pk_mul_f32 v[118:119], v[126:127], v[118:119]
	v_pk_mul_f32 v[120:121], v[126:127], v[120:121]
	v_rndne_f32_e32 v118, v118
	v_rndne_f32_e32 v119, v119
	v_rndne_f32_e32 v120, v120
	v_rndne_f32_e32 v121, v121
	v_cvt_i32_f32_e32 v118, v118
	v_cvt_i32_f32_e32 v119, v119
	v_cvt_i32_f32_e32 v120, v120
	v_cvt_i32_f32_e32 v121, v121
	v_perm_b32 v118, v119, v118, s16
	v_perm_b32 v120, v121, v120, s17
	v_or_b32_e32 v106, v118, v120
	v_lshlrev_b32_e32 v118, 16, v12
	v_and_b32_e32 v119, 0xffff0000, v12
	v_lshlrev_b32_e32 v120, 16, v13
	v_and_b32_e32 v121, 0xffff0000, v13
	v_pk_mul_f32 v[118:119], v[126:127], v[118:119]
	v_pk_mul_f32 v[120:121], v[126:127], v[120:121]
	v_rndne_f32_e32 v118, v118
	v_rndne_f32_e32 v119, v119
	v_rndne_f32_e32 v120, v120
	v_rndne_f32_e32 v121, v121
	v_cvt_i32_f32_e32 v118, v118
	v_cvt_i32_f32_e32 v119, v119
	v_cvt_i32_f32_e32 v120, v120
	v_cvt_i32_f32_e32 v121, v121
	v_perm_b32 v118, v119, v118, s16
	v_perm_b32 v120, v121, v120, s17
	v_or_b32_e32 v107, v118, v120
	global_store_dwordx2 v136, v[106:107], s[10:11] offset:1024
	s_waitcnt vmcnt(25)
	v_lshlrev_b32_e32 v118, 16, v14
	v_and_b32_e32 v119, 0xffff0000, v14
	v_lshlrev_b32_e32 v120, 16, v15
	v_and_b32_e32 v121, 0xffff0000, v15
	v_pk_mul_f32 v[118:119], v[126:127], v[118:119]
	v_pk_mul_f32 v[120:121], v[126:127], v[120:121]
	v_rndne_f32_e32 v118, v118
	v_rndne_f32_e32 v119, v119
	v_rndne_f32_e32 v120, v120
	v_rndne_f32_e32 v121, v121
	v_cvt_i32_f32_e32 v118, v118
	v_cvt_i32_f32_e32 v119, v119
	v_cvt_i32_f32_e32 v120, v120
	v_cvt_i32_f32_e32 v121, v121
	v_perm_b32 v118, v119, v118, s16
	v_perm_b32 v120, v121, v120, s17
	v_or_b32_e32 v108, v118, v120
	v_lshlrev_b32_e32 v118, 16, v16
	v_and_b32_e32 v119, 0xffff0000, v16
	v_lshlrev_b32_e32 v120, 16, v17
	v_and_b32_e32 v121, 0xffff0000, v17
	v_pk_mul_f32 v[118:119], v[126:127], v[118:119]
	v_pk_mul_f32 v[120:121], v[126:127], v[120:121]
	v_rndne_f32_e32 v118, v118
	v_rndne_f32_e32 v119, v119
	v_rndne_f32_e32 v120, v120
	v_rndne_f32_e32 v121, v121
	v_cvt_i32_f32_e32 v118, v118
	v_cvt_i32_f32_e32 v119, v119
	v_cvt_i32_f32_e32 v120, v120
	v_cvt_i32_f32_e32 v121, v121
	v_perm_b32 v118, v119, v118, s16
	v_perm_b32 v120, v121, v120, s17
	v_or_b32_e32 v109, v118, v120
	global_store_dwordx2 v136, v[108:109], s[10:11] offset:1536
	s_waitcnt vmcnt(25)
	v_lshlrev_b32_e32 v118, 16, v18
	v_and_b32_e32 v119, 0xffff0000, v18
	v_lshlrev_b32_e32 v120, 16, v19
	v_and_b32_e32 v121, 0xffff0000, v19
	v_pk_mul_f32 v[118:119], v[126:127], v[118:119]
	v_pk_mul_f32 v[120:121], v[126:127], v[120:121]
	v_rndne_f32_e32 v118, v118
	v_rndne_f32_e32 v119, v119
	v_rndne_f32_e32 v120, v120
	v_rndne_f32_e32 v121, v121
	v_cvt_i32_f32_e32 v118, v118
	v_cvt_i32_f32_e32 v119, v119
	v_cvt_i32_f32_e32 v120, v120
	v_cvt_i32_f32_e32 v121, v121
	v_perm_b32 v118, v119, v118, s16
	v_perm_b32 v120, v121, v120, s17
	v_or_b32_e32 v110, v118, v120
	v_lshlrev_b32_e32 v118, 16, v20
	v_and_b32_e32 v119, 0xffff0000, v20
	v_lshlrev_b32_e32 v120, 16, v21
	v_and_b32_e32 v121, 0xffff0000, v21
	v_pk_mul_f32 v[118:119], v[126:127], v[118:119]
	v_pk_mul_f32 v[120:121], v[126:127], v[120:121]
	v_rndne_f32_e32 v118, v118
	v_rndne_f32_e32 v119, v119
	v_rndne_f32_e32 v120, v120
	v_rndne_f32_e32 v121, v121
	v_cvt_i32_f32_e32 v118, v118
	v_cvt_i32_f32_e32 v119, v119
	v_cvt_i32_f32_e32 v120, v120
	v_cvt_i32_f32_e32 v121, v121
	v_perm_b32 v118, v119, v118, s16
	v_perm_b32 v120, v121, v120, s17
	v_or_b32_e32 v111, v118, v120
	global_store_dwordx2 v136, v[110:111], s[10:11] offset:2048
	s_waitcnt vmcnt(25)
	v_lshlrev_b32_e32 v118, 16, v22
	v_and_b32_e32 v119, 0xffff0000, v22
	v_lshlrev_b32_e32 v120, 16, v23
	v_and_b32_e32 v121, 0xffff0000, v23
	v_pk_mul_f32 v[118:119], v[126:127], v[118:119]
	v_pk_mul_f32 v[120:121], v[126:127], v[120:121]
	v_rndne_f32_e32 v118, v118
	v_rndne_f32_e32 v119, v119
	v_rndne_f32_e32 v120, v120
	v_rndne_f32_e32 v121, v121
	v_cvt_i32_f32_e32 v118, v118
	v_cvt_i32_f32_e32 v119, v119
	v_cvt_i32_f32_e32 v120, v120
	v_cvt_i32_f32_e32 v121, v121
	v_perm_b32 v118, v119, v118, s16
	v_perm_b32 v120, v121, v120, s17
	v_or_b32_e32 v112, v118, v120
	v_lshlrev_b32_e32 v118, 16, v24
	v_and_b32_e32 v119, 0xffff0000, v24
	v_lshlrev_b32_e32 v120, 16, v25
	v_and_b32_e32 v121, 0xffff0000, v25
	v_pk_mul_f32 v[118:119], v[126:127], v[118:119]
	v_pk_mul_f32 v[120:121], v[126:127], v[120:121]
	v_rndne_f32_e32 v118, v118
	v_rndne_f32_e32 v119, v119
	v_rndne_f32_e32 v120, v120
	v_rndne_f32_e32 v121, v121
	v_cvt_i32_f32_e32 v118, v118
	v_cvt_i32_f32_e32 v119, v119
	v_cvt_i32_f32_e32 v120, v120
	v_cvt_i32_f32_e32 v121, v121
	v_perm_b32 v118, v119, v118, s16
	v_perm_b32 v120, v121, v120, s17
	v_or_b32_e32 v113, v118, v120
	global_store_dwordx2 v136, v[112:113], s[10:11] offset:2560
	s_waitcnt vmcnt(25)
	v_lshlrev_b32_e32 v118, 16, v26
	v_and_b32_e32 v119, 0xffff0000, v26
	v_lshlrev_b32_e32 v120, 16, v27
	v_and_b32_e32 v121, 0xffff0000, v27
	v_pk_mul_f32 v[118:119], v[126:127], v[118:119]
	v_pk_mul_f32 v[120:121], v[126:127], v[120:121]
	v_rndne_f32_e32 v118, v118
	v_rndne_f32_e32 v119, v119
	v_rndne_f32_e32 v120, v120
	v_rndne_f32_e32 v121, v121
	v_cvt_i32_f32_e32 v118, v118
	v_cvt_i32_f32_e32 v119, v119
	v_cvt_i32_f32_e32 v120, v120
	v_cvt_i32_f32_e32 v121, v121
	v_perm_b32 v118, v119, v118, s16
	v_perm_b32 v120, v121, v120, s17
	v_or_b32_e32 v114, v118, v120
	v_lshlrev_b32_e32 v118, 16, v28
	v_and_b32_e32 v119, 0xffff0000, v28
	v_lshlrev_b32_e32 v120, 16, v29
	v_and_b32_e32 v121, 0xffff0000, v29
	v_pk_mul_f32 v[118:119], v[126:127], v[118:119]
	v_pk_mul_f32 v[120:121], v[126:127], v[120:121]
	v_rndne_f32_e32 v118, v118
	v_rndne_f32_e32 v119, v119
	v_rndne_f32_e32 v120, v120
	v_rndne_f32_e32 v121, v121
	v_cvt_i32_f32_e32 v118, v118
	v_cvt_i32_f32_e32 v119, v119
	v_cvt_i32_f32_e32 v120, v120
	v_cvt_i32_f32_e32 v121, v121
	v_perm_b32 v118, v119, v118, s16
	v_perm_b32 v120, v121, v120, s17
	v_or_b32_e32 v115, v118, v120
	global_store_dwordx2 v136, v[114:115], s[10:11] offset:3072
	s_waitcnt vmcnt(25)
; __device__ __forceinline__ unsigned q8(float x) { return (unsigned)(int)__builtin_rintf(x) & 0xffu; }
; __device__ __forceinline__ void rows_bf16_to_i8(Frame& F, const bf16* XBp, const unsigned* rmax, unsigned* X8, float* sx, int pitch4 = D / 4) {
;     ...
;         const float mx = __builtin_bit_cast(float, rb), inv = mx > 0.f ? 127.0f / mx : 0.f;
;         v2u* dst = (v2u*)(X8 + (size_t)m * pitch4) + lane;
; #pragma unroll
;         for (int j = 0; j < 8; ++j) { v2u o;
;             o.x = q8(blo(w[j].x) * inv) | (q8(bhi(w[j].x) * inv) << 8) | (q8(blo(w[j].y) * inv) << 16) | (q8(bhi(w[j].y) * inv) << 24);
;             o.y = q8(blo(w[j].z) * inv) | (q8(bhi(w[j].z) * inv) << 8) | (q8(blo(w[j].w) * inv) << 16) | (q8(bhi(w[j].w) * inv) << 24);
;             dst[64 * j] = o; }
;         if (lane == 0) sx[m] = mx * (1.0f / 127.0f);
; #pragma unroll
;         for (int j = 0; j < 8; ++j) w[j] = wn[j];
;         rb = rbn;
	v_lshlrev_b32_e32 v118, 16, v30
	v_and_b32_e32 v119, 0xffff0000, v30
	v_lshlrev_b32_e32 v120, 16, v31
	v_and_b32_e32 v121, 0xffff0000, v31
	v_pk_mul_f32 v[118:119], v[126:127], v[118:119]
	v_pk_mul_f32 v[120:121], v[126:127], v[120:121]
	v_rndne_f32_e32 v118, v118
	v_rndne_f32_e32 v119, v119
	v_rndne_f32_e32 v120, v120
	v_rndne_f32_e32 v121, v121
	v_cvt_i32_f32_e32 v118, v118
	v_cvt_i32_f32_e32 v119, v119
	v_cvt_i32_f32_e32 v120, v120
	v_cvt_i32_f32_e32 v121, v121
	v_perm_b32 v118, v119, v118, s16
	v_perm_b32 v120, v121, v120, s17
	v_or_b32_e32 v116, v118, v120
	v_lshlrev_b32_e32 v118, 16, v32
	v_and_b32_e32 v119, 0xffff0000, v32
	v_lshlrev_b32_e32 v120, 16, v33
	v_and_b32_e32 v121, 0xffff0000, v33
	v_pk_mul_f32 v[118:119], v[126:127], v[118:119]
	v_pk_mul_f32 v[120:121], v[126:127], v[120:121]
	v_rndne_f32_e32 v118, v118
	v_rndne_f32_e32 v119, v119
	v_rndne_f32_e32 v120, v120
	v_rndne_f32_e32 v121, v121
	v_cvt_i32_f32_e32 v118, v118
	v_cvt_i32_f32_e32 v119, v119
	v_cvt_i32_f32_e32 v120, v120
	v_cvt_i32_f32_e32 v121, v121
	v_perm_b32 v118, v119, v118, s16
	v_perm_b32 v120, v121, v120, s17
	v_or_b32_e32 v117, v118, v120
	global_store_dwordx2 v136, v[116:117], s[10:11] offset:3584
	s_mov_b64 exec, s[12:13]
	global_store_dword v137, v138, s[8:9]
	s_mov_b64 exec, -1
	s_add_u32 s10, s10, 0x800000
	s_addc_u32 s11, s11, 0
	s_add_u32 s8, s8, 0x2000
	s_addc_u32 s9, s9, 0
	global_load_dword v98, v137, s[6:7]
	global_load_dwordx4 v[2:5], v134, s[4:5] offset:0
	global_load_dwordx4 v[6:9], v134, s[4:5] offset:1024
	global_load_dwordx4 v[10:13], v134, s[4:5] offset:2048
	global_load_dwordx4 v[14:17], v134, s[4:5] offset:3072
	global_load_dwordx4 v[18:21], v135, s[4:5] offset:0
	global_load_dwordx4 v[22:25], v135, s[4:5] offset:1024
	global_load_dwordx4 v[26:29], v135, s[4:5] offset:2048
	global_load_dwordx4 v[30:33], v135, s[4:5] offset:3072
	s_add_u32 s4, s4, 0x1000000
	s_addc_u32 s5, s5, 0
	s_add_u32 s6, s6, 0x2000
	s_addc_u32 s7, s7, 0
	s_waitcnt vmcnt(35)
	v_div_scale_f32 v128, s[14:15], v99, v99, s3
	v_rcp_f32_e32 v129, v128
	v_div_scale_f32 v130, vcc, s3, v99, s3
	v_fma_f32 v131, -v128, v129, 1.0
	v_fmac_f32_e32 v129, v131, v129
	v_mul_f32_e32 v131, v130, v129
	v_fma_f32 v132, -v128, v131, v130
	v_fmac_f32_e32 v131, v132, v129
	v_fma_f32 v128, -v128, v131, v130
	v_div_fmas_f32 v128, v128, v129, v131
	v_div_fixup_f32 v128, v128, v99, s3
	v_cmp_lt_f32_e32 vcc, 0, v99
	v_mul_f32_e32 v138, 0x3c010204, v99
	v_cndmask_b32_e32 v126, 0, v128, vcc
	v_mov_b32_e32 v127, v126
	s_waitcnt vmcnt(34)
	v_lshlrev_b32_e32 v118, 16, v34
	v_and_b32_e32 v119, 0xffff0000, v34
	v_lshlrev_b32_e32 v120, 16, v35
	v_and_b32_e32 v121, 0xffff0000, v35
	v_pk_mul_f32 v[118:119], v[126:127], v[118:119]
	v_pk_mul_f32 v[120:121], v[126:127], v[120:121]
	v_rndne_f32_e32 v118, v118
	v_rndne_f32_e32 v119, v119
	v_rndne_f32_e32 v120, v120
	v_rndne_f32_e32 v121, v121
	v_cvt_i32_f32_e32 v118, v118
	v_cvt_i32_f32_e32 v119, v119
	v_cvt_i32_f32_e32 v120, v120
	v_cvt_i32_f32_e32 v121, v121
	v_perm_b32 v118, v119, v118, s16
	v_perm_b32 v120, v121, v120, s17
	v_or_b32_e32 v102, v118, v120
	v_lshlrev_b32_e32 v118, 16, v36
	v_and_b32_e32 v119, 0xffff0000, v36
	v_lshlrev_b32_e32 v120, 16, v37
	v_and_b32_e32 v121, 0xffff0000, v37
	v_pk_mul_f32 v[118:119], v[126:127], v[118:119]
	v_pk_mul_f32 v[120:121], v[126:127], v[120:121]
	v_rndne_f32_e32 v118, v118
	v_rndne_f32_e32 v119, v119
	v_rndne_f32_e32 v120, v120
	v_rndne_f32_e32 v121, v121
	v_cvt_i32_f32_e32 v118, v118
	v_cvt_i32_f32_e32 v119, v119
	v_cvt_i32_f32_e32 v120, v120
	v_cvt_i32_f32_e32 v121, v121
	v_perm_b32 v118, v119, v118, s16
	v_perm_b32 v120, v121, v120, s17
	v_or_b32_e32 v103, v118, v120
	global_store_dwordx2 v136, v[102:103], s[10:11] offset:0
	s_waitcnt vmcnt(34)
	v_lshlrev_b32_e32 v118, 16, v38
	v_and_b32_e32 v119, 0xffff0000, v38
	v_lshlrev_b32_e32 v120, 16, v39
	v_and_b32_e32 v121, 0xffff0000, v39
	v_pk_mul_f32 v[118:119], v[126:127], v[118:119]
	v_pk_mul_f32 v[120:121], v[126:127], v[120:121]
	v_rndne_f32_e32 v118, v118
	v_rndne_f32_e32 v119, v119
	v_rndne_f32_e32 v120, v120
	v_rndne_f32_e32 v121, v121
	v_cvt_i32_f32_e32 v118, v118
	v_cvt_i32_f32_e32 v119, v119
	v_cvt_i32_f32_e32 v120, v120
	v_cvt_i32_f32_e32 v121, v121
	v_perm_b32 v118, v119, v118, s16
	v_perm_b32 v120, v121, v120, s17
	v_or_b32_e32 v104, v118, v120
	v_lshlrev_b32_e32 v118, 16, v40
	v_and_b32_e32 v119, 0xffff0000, v40
	v_lshlrev_b32_e32 v120, 16, v41
	v_and_b32_e32 v121, 0xffff0000, v41
	v_pk_mul_f32 v[118:119], v[126:127], v[118:119]
	v_pk_mul_f32 v[120:121], v[126:127], v[120:121]
	v_rndne_f32_e32 v118, v118
	v_rndne_f32_e32 v119, v119
	v_rndne_f32_e32 v120, v120
	v_rndne_f32_e32 v121, v121
	v_cvt_i32_f32_e32 v118, v118
	v_cvt_i32_f32_e32 v119, v119
	v_cvt_i32_f32_e32 v120, v120
	v_cvt_i32_f32_e32 v121, v121
	v_perm_b32 v118, v119, v118, s16
	v_perm_b32 v120, v121, v120, s17
	v_or_b32_e32 v105, v118, v120
	global_store_dwordx2 v136, v[104:105], s[10:11] offset:512
	s_waitcnt vmcnt(34)
	v_lshlrev_b32_e32 v118, 16, v42
	v_and_b32_e32 v119, 0xffff0000, v42
	v_lshlrev_b32_e32 v120, 16, v43
	v_and_b32_e32 v121, 0xffff0000, v43
	v_pk_mul_f32 v[118:119], v[126:127], v[118:119]
	v_pk_mul_f32 v[120:121], v[126:127], v[120:121]
	v_rndne_f32_e32 v118, v118
	v_rndne_f32_e32 v119, v119
	v_rndne_f32_e32 v120, v120
	v_rndne_f32_e32 v121, v121
	v_cvt_i32_f32_e32 v118, v118
	v_cvt_i32_f32_e32 v119, v119
	v_cvt_i32_f32_e32 v120, v120
	v_cvt_i32_f32_e32 v121, v121
	v_perm_b32 v118, v119, v118, s16
	v_perm_b32 v120, v121, v120, s17
	v_or_b32_e32 v106, v118, v120
	v_lshlrev_b32_e32 v118, 16, v44
	v_and_b32_e32 v119, 0xffff0000, v44
	v_lshlrev_b32_e32 v120, 16, v45
	v_and_b32_e32 v121, 0xffff0000, v45
	v_pk_mul_f32 v[118:119], v[126:127], v[118:119]
	v_pk_mul_f32 v[120:121], v[126:127], v[120:121]
	v_rndne_f32_e32 v118, v118
	v_rndne_f32_e32 v119, v119
	v_rndne_f32_e32 v120, v120
	v_rndne_f32_e32 v121, v121
	v_cvt_i32_f32_e32 v118, v118
	v_cvt_i32_f32_e32 v119, v119
	v_cvt_i32_f32_e32 v120, v120
	v_cvt_i32_f32_e32 v121, v121
	v_perm_b32 v118, v119, v118, s16
	v_perm_b32 v120, v121, v120, s17
	v_or_b32_e32 v107, v118, v120
	global_store_dwordx2 v136, v[106:107], s[10:11] offset:1024
	s_waitcnt vmcnt(34)
; __device__ __forceinline__ unsigned q8(float x) { return (unsigned)(int)__builtin_rintf(x) & 0xffu; }
; __device__ __forceinline__ void rows_bf16_to_i8(Frame& F, const bf16* XBp, const unsigned* rmax, unsigned* X8, float* sx, int pitch4 = D / 4) {
;     ...
; #pragma unroll
;         for (int j = 0; j < 8; ++j) { v2u o;
;             o.x = q8(blo(w[j].x) * inv) | (q8(bhi(w[j].x) * inv) << 8) | (q8(blo(w[j].y) * inv) << 16) | (q8(bhi(w[j].y) * inv) << 24);
;             o.y = q8(blo(w[j].z) * inv) | (q8(bhi(w[j].z) * inv) << 8) | (q8(blo(w[j].w) * inv) << 16) | (q8(bhi(w[j].w) * inv) << 24);
;             dst[64 * j] = o; }
	v_lshlrev_b32_e32 v118, 16, v46
	v_and_b32_e32 v119, 0xffff0000, v46
	v_lshlrev_b32_e32 v120, 16, v47
	v_and_b32_e32 v121, 0xffff0000, v47
	v_pk_mul_f32 v[118:119], v[126:127], v[118:119]
	v_pk_mul_f32 v[120:121], v[126:127], v[120:121]
	v_rndne_f32_e32 v118, v118
	v_rndne_f32_e32 v119, v119
	v_rndne_f32_e32 v120, v120
	v_rndne_f32_e32 v121, v121
	v_cvt_i32_f32_e32 v118, v118
	v_cvt_i32_f32_e32 v119, v119
	v_cvt_i32_f32_e32 v120, v120
	v_cvt_i32_f32_e32 v121, v121
	v_perm_b32 v118, v119, v118, s16
	v_perm_b32 v120, v121, v120, s17
	v_or_b32_e32 v108, v118, v120
	v_lshlrev_b32_e32 v118, 16, v48
	v_and_b32_e32 v119, 0xffff0000, v48
	v_lshlrev_b32_e32 v120, 16, v49
	v_and_b32_e32 v121, 0xffff0000, v49
	v_pk_mul_f32 v[118:119], v[126:127], v[118:119]
	v_pk_mul_f32 v[120:121], v[126:127], v[120:121]
	v_rndne_f32_e32 v118, v118
	v_rndne_f32_e32 v119, v119
	v_rndne_f32_e32 v120, v120
	v_rndne_f32_e32 v121, v121
	v_cvt_i32_f32_e32 v118, v118
	v_cvt_i32_f32_e32 v119, v119
	v_cvt_i32_f32_e32 v120, v120
	v_cvt_i32_f32_e32 v121, v121
	v_perm_b32 v118, v119, v118, s16
	v_perm_b32 v120, v121, v120, s17
	v_or_b32_e32 v109, v118, v120
	global_store_dwordx2 v136, v[108:109], s[10:11] offset:1536
	s_waitcnt vmcnt(34)
	v_lshlrev_b32_e32 v118, 16, v50
	v_and_b32_e32 v119, 0xffff0000, v50
	v_lshlrev_b32_e32 v120, 16, v51
	v_and_b32_e32 v121, 0xffff0000, v51
	v_pk_mul_f32 v[118:119], v[126:127], v[118:119]
	v_pk_mul_f32 v[120:121], v[126:127], v[120:121]
	v_rndne_f32_e32 v118, v118
	v_rndne_f32_e32 v119, v119
	v_rndne_f32_e32 v120, v120
	v_rndne_f32_e32 v121, v121
	v_cvt_i32_f32_e32 v118, v118
	v_cvt_i32_f32_e32 v119, v119
	v_cvt_i32_f32_e32 v120, v120
	v_cvt_i32_f32_e32 v121, v121
	v_perm_b32 v118, v119, v118, s16
	v_perm_b32 v120, v121, v120, s17
	v_or_b32_e32 v110, v118, v120
	v_lshlrev_b32_e32 v118, 16, v52
	v_and_b32_e32 v119, 0xffff0000, v52
	v_lshlrev_b32_e32 v120, 16, v53
	v_and_b32_e32 v121, 0xffff0000, v53
	v_pk_mul_f32 v[118:119], v[126:127], v[118:119]
	v_pk_mul_f32 v[120:121], v[126:127], v[120:121]
	v_rndne_f32_e32 v118, v118
	v_rndne_f32_e32 v119, v119
	v_rndne_f32_e32 v120, v120
	v_rndne_f32_e32 v121, v121
	v_cvt_i32_f32_e32 v118, v118
	v_cvt_i32_f32_e32 v119, v119
	v_cvt_i32_f32_e32 v120, v120
	v_cvt_i32_f32_e32 v121, v121
	v_perm_b32 v118, v119, v118, s16
	v_perm_b32 v120, v121, v120, s17
	v_or_b32_e32 v111, v118, v120
	global_store_dwordx2 v136, v[110:111], s[10:11] offset:2048
	s_waitcnt vmcnt(34)
	v_lshlrev_b32_e32 v118, 16, v54
	v_and_b32_e32 v119, 0xffff0000, v54
	v_lshlrev_b32_e32 v120, 16, v55
	v_and_b32_e32 v121, 0xffff0000, v55
	v_pk_mul_f32 v[118:119], v[126:127], v[118:119]
	v_pk_mul_f32 v[120:121], v[126:127], v[120:121]
	v_rndne_f32_e32 v118, v118
	v_rndne_f32_e32 v119, v119
	v_rndne_f32_e32 v120, v120
	v_rndne_f32_e32 v121, v121
	v_cvt_i32_f32_e32 v118, v118
	v_cvt_i32_f32_e32 v119, v119
	v_cvt_i32_f32_e32 v120, v120
	v_cvt_i32_f32_e32 v121, v121
	v_perm_b32 v118, v119, v118, s16
	v_perm_b32 v120, v121, v120, s17
	v_or_b32_e32 v112, v118, v120
	v_lshlrev_b32_e32 v118, 16, v56
	v_and_b32_e32 v119, 0xffff0000, v56
	v_lshlrev_b32_e32 v120, 16, v57
	v_and_b32_e32 v121, 0xffff0000, v57
	v_pk_mul_f32 v[118:119], v[126:127], v[118:119]
	v_pk_mul_f32 v[120:121], v[126:127], v[120:121]
	v_rndne_f32_e32 v118, v118
	v_rndne_f32_e32 v119, v119
	v_rndne_f32_e32 v120, v120
	v_rndne_f32_e32 v121, v121
	v_cvt_i32_f32_e32 v118, v118
	v_cvt_i32_f32_e32 v119, v119
	v_cvt_i32_f32_e32 v120, v120
	v_cvt_i32_f32_e32 v121, v121
	v_perm_b32 v118, v119, v118, s16
	v_perm_b32 v120, v121, v120, s17
	v_or_b32_e32 v113, v118, v120
	global_store_dwordx2 v136, v[112:113], s[10:11] offset:2560
	s_waitcnt vmcnt(34)
	v_lshlrev_b32_e32 v118, 16, v58
	v_and_b32_e32 v119, 0xffff0000, v58
	v_lshlrev_b32_e32 v120, 16, v59
	v_and_b32_e32 v121, 0xffff0000, v59
	v_pk_mul_f32 v[118:119], v[126:127], v[118:119]
	v_pk_mul_f32 v[120:121], v[126:127], v[120:121]
	v_rndne_f32_e32 v118, v118
	v_rndne_f32_e32 v119, v119
	v_rndne_f32_e32 v120, v120
	v_rndne_f32_e32 v121, v121
	v_cvt_i32_f32_e32 v118, v118
	v_cvt_i32_f32_e32 v119, v119
	v_cvt_i32_f32_e32 v120, v120
	v_cvt_i32_f32_e32 v121, v121
	v_perm_b32 v118, v119, v118, s16
	v_perm_b32 v120, v121, v120, s17
	v_or_b32_e32 v114, v118, v120
	v_lshlrev_b32_e32 v118, 16, v60
	v_and_b32_e32 v119, 0xffff0000, v60
	v_lshlrev_b32_e32 v120, 16, v61
	v_and_b32_e32 v121, 0xffff0000, v61
	v_pk_mul_f32 v[118:119], v[126:127], v[118:119]
	v_pk_mul_f32 v[120:121], v[126:127], v[120:121]
	v_rndne_f32_e32 v118, v118
	v_rndne_f32_e32 v119, v119
	v_rndne_f32_e32 v120, v120
	v_rndne_f32_e32 v121, v121
	v_cvt_i32_f32_e32 v118, v118
	v_cvt_i32_f32_e32 v119, v119
	v_cvt_i32_f32_e32 v120, v120
	v_cvt_i32_f32_e32 v121, v121
	v_perm_b32 v118, v119, v118, s16
	v_perm_b32 v120, v121, v120, s17
	v_or_b32_e32 v115, v118, v120
	global_store_dwordx2 v136, v[114:115], s[10:11] offset:3072
	s_waitcnt vmcnt(34)
; __device__ __forceinline__ unsigned q8(float x) { return (unsigned)(int)__builtin_rintf(x) & 0xffu; }
; __device__ __forceinline__ void rows_bf16_to_i8(Frame& F, const bf16* XBp, const unsigned* rmax, unsigned* X8, float* sx, int pitch4 = D / 4) {
;     ...
;         const float mx = __builtin_bit_cast(float, rb), inv = mx > 0.f ? 127.0f / mx : 0.f;
;         v2u* dst = (v2u*)(X8 + (size_t)m * pitch4) + lane;
; #pragma unroll
;         for (int j = 0; j < 8; ++j) { v2u o;
;             o.x = q8(blo(w[j].x) * inv) | (q8(bhi(w[j].x) * inv) << 8) | (q8(blo(w[j].y) * inv) << 16) | (q8(bhi(w[j].y) * inv) << 24);
;             o.y = q8(blo(w[j].z) * inv) | (q8(bhi(w[j].z) * inv) << 8) | (q8(blo(w[j].w) * inv) << 16) | (q8(bhi(w[j].w) * inv) << 24);
;             dst[64 * j] = o; }
;         if (lane == 0) sx[m] = mx * (1.0f / 127.0f);
; #pragma unroll
;         for (int j = 0; j < 8; ++j) w[j] = wn[j];
;         rb = rbn;
	v_lshlrev_b32_e32 v118, 16, v62
	v_and_b32_e32 v119, 0xffff0000, v62
	v_lshlrev_b32_e32 v120, 16, v63
	v_and_b32_e32 v121, 0xffff0000, v63
	v_pk_mul_f32 v[118:119], v[126:127], v[118:119]
	v_pk_mul_f32 v[120:121], v[126:127], v[120:121]
	v_rndne_f32_e32 v118, v118
	v_rndne_f32_e32 v119, v119
	v_rndne_f32_e32 v120, v120
	v_rndne_f32_e32 v121, v121
	v_cvt_i32_f32_e32 v118, v118
	v_cvt_i32_f32_e32 v119, v119
	v_cvt_i32_f32_e32 v120, v120
	v_cvt_i32_f32_e32 v121, v121
	v_perm_b32 v118, v119, v118, s16
	v_perm_b32 v120, v121, v120, s17
	v_or_b32_e32 v116, v118, v120
	v_lshlrev_b32_e32 v118, 16, v64
	v_and_b32_e32 v119, 0xffff0000, v64
	v_lshlrev_b32_e32 v120, 16, v65
	v_and_b32_e32 v121, 0xffff0000, v65
	v_pk_mul_f32 v[118:119], v[126:127], v[118:119]
	v_pk_mul_f32 v[120:121], v[126:127], v[120:121]
	v_rndne_f32_e32 v118, v118
	v_rndne_f32_e32 v119, v119
	v_rndne_f32_e32 v120, v120
	v_rndne_f32_e32 v121, v121
	v_cvt_i32_f32_e32 v118, v118
	v_cvt_i32_f32_e32 v119, v119
	v_cvt_i32_f32_e32 v120, v120
	v_cvt_i32_f32_e32 v121, v121
	v_perm_b32 v118, v119, v118, s16
	v_perm_b32 v120, v121, v120, s17
	v_or_b32_e32 v117, v118, v120
	global_store_dwordx2 v136, v[116:117], s[10:11] offset:3584
	s_mov_b64 exec, s[12:13]
	global_store_dword v137, v138, s[8:9]
	s_mov_b64 exec, -1
	s_add_u32 s10, s10, 0x800000
	s_addc_u32 s11, s11, 0
	s_add_u32 s8, s8, 0x2000
	s_addc_u32 s9, s9, 0
	global_load_dword v99, v137, s[6:7]
	global_load_dwordx4 v[34:37], v134, s[4:5] offset:0
	global_load_dwordx4 v[38:41], v134, s[4:5] offset:1024
	global_load_dwordx4 v[42:45], v134, s[4:5] offset:2048
	global_load_dwordx4 v[46:49], v134, s[4:5] offset:3072
	global_load_dwordx4 v[50:53], v135, s[4:5] offset:0
	global_load_dwordx4 v[54:57], v135, s[4:5] offset:1024
	global_load_dwordx4 v[58:61], v135, s[4:5] offset:2048
	global_load_dwordx4 v[62:65], v135, s[4:5] offset:3072
	s_add_u32 s4, s4, 0x1000000
	s_addc_u32 s5, s5, 0
	s_add_u32 s6, s6, 0x2000
	s_addc_u32 s7, s7, 0
	s_waitcnt vmcnt(44)
	v_div_scale_f32 v128, s[14:15], v100, v100, s3
	v_rcp_f32_e32 v129, v128
	v_div_scale_f32 v130, vcc, s3, v100, s3
	v_fma_f32 v131, -v128, v129, 1.0
	v_fmac_f32_e32 v129, v131, v129
	v_mul_f32_e32 v131, v130, v129
	v_fma_f32 v132, -v128, v131, v130
	v_fmac_f32_e32 v131, v132, v129
	v_fma_f32 v128, -v128, v131, v130
	v_div_fmas_f32 v128, v128, v129, v131
	v_div_fixup_f32 v128, v128, v100, s3
	v_cmp_lt_f32_e32 vcc, 0, v100
	v_mul_f32_e32 v138, 0x3c010204, v100
	v_cndmask_b32_e32 v126, 0, v128, vcc
	v_mov_b32_e32 v127, v126
	s_waitcnt vmcnt(43)
	v_lshlrev_b32_e32 v118, 16, v66
	v_and_b32_e32 v119, 0xffff0000, v66
	v_lshlrev_b32_e32 v120, 16, v67
	v_and_b32_e32 v121, 0xffff0000, v67
	v_pk_mul_f32 v[118:119], v[126:127], v[118:119]
	v_pk_mul_f32 v[120:121], v[126:127], v[120:121]
	v_rndne_f32_e32 v118, v118
	v_rndne_f32_e32 v119, v119
	v_rndne_f32_e32 v120, v120
	v_rndne_f32_e32 v121, v121
	v_cvt_i32_f32_e32 v118, v118
	v_cvt_i32_f32_e32 v119, v119
	v_cvt_i32_f32_e32 v120, v120
	v_cvt_i32_f32_e32 v121, v121
	v_perm_b32 v118, v119, v118, s16
	v_perm_b32 v120, v121, v120, s17
	v_or_b32_e32 v102, v118, v120
	v_lshlrev_b32_e32 v118, 16, v68
	v_and_b32_e32 v119, 0xffff0000, v68
	v_lshlrev_b32_e32 v120, 16, v69
	v_and_b32_e32 v121, 0xffff0000, v69
	v_pk_mul_f32 v[118:119], v[126:127], v[118:119]
	v_pk_mul_f32 v[120:121], v[126:127], v[120:121]
	v_rndne_f32_e32 v118, v118
	v_rndne_f32_e32 v119, v119
	v_rndne_f32_e32 v120, v120
	v_rndne_f32_e32 v121, v121
	v_cvt_i32_f32_e32 v118, v118
	v_cvt_i32_f32_e32 v119, v119
	v_cvt_i32_f32_e32 v120, v120
	v_cvt_i32_f32_e32 v121, v121
	v_perm_b32 v118, v119, v118, s16
	v_perm_b32 v120, v121, v120, s17
	v_or_b32_e32 v103, v118, v120
	global_store_dwordx2 v136, v[102:103], s[10:11] offset:0
	s_waitcnt vmcnt(43)
	v_lshlrev_b32_e32 v118, 16, v70
	v_and_b32_e32 v119, 0xffff0000, v70
	v_lshlrev_b32_e32 v120, 16, v71
	v_and_b32_e32 v121, 0xffff0000, v71
	v_pk_mul_f32 v[118:119], v[126:127], v[118:119]
	v_pk_mul_f32 v[120:121], v[126:127], v[120:121]
	v_rndne_f32_e32 v118, v118
	v_rndne_f32_e32 v119, v119
	v_rndne_f32_e32 v120, v120
	v_rndne_f32_e32 v121, v121
	v_cvt_i32_f32_e32 v118, v118
	v_cvt_i32_f32_e32 v119, v119
	v_cvt_i32_f32_e32 v120, v120
	v_cvt_i32_f32_e32 v121, v121
	v_perm_b32 v118, v119, v118, s16
	v_perm_b32 v120, v121, v120, s17
	v_or_b32_e32 v104, v118, v120
	v_lshlrev_b32_e32 v118, 16, v72
	v_and_b32_e32 v119, 0xffff0000, v72
	v_lshlrev_b32_e32 v120, 16, v73
	v_and_b32_e32 v121, 0xffff0000, v73
	v_pk_mul_f32 v[118:119], v[126:127], v[118:119]
	v_pk_mul_f32 v[120:121], v[126:127], v[120:121]
	v_rndne_f32_e32 v118, v118
	v_rndne_f32_e32 v119, v119
	v_rndne_f32_e32 v120, v120
	v_rndne_f32_e32 v121, v121
	v_cvt_i32_f32_e32 v118, v118
	v_cvt_i32_f32_e32 v119, v119
	v_cvt_i32_f32_e32 v120, v120
	v_cvt_i32_f32_e32 v121, v121
	v_perm_b32 v118, v119, v118, s16
	v_perm_b32 v120, v121, v120, s17
	v_or_b32_e32 v105, v118, v120
	global_store_dwordx2 v136, v[104:105], s[10:11] offset:512
	s_waitcnt vmcnt(43)
	v_lshlrev_b32_e32 v118, 16, v74
	v_and_b32_e32 v119, 0xffff0000, v74
	v_lshlrev_b32_e32 v120, 16, v75
	v_and_b32_e32 v121, 0xffff0000, v75
	v_pk_mul_f32 v[118:119], v[126:127], v[118:119]
	v_pk_mul_f32 v[120:121], v[126:127], v[120:121]
	v_rndne_f32_e32 v118, v118
	v_rndne_f32_e32 v119, v119
	v_rndne_f32_e32 v120, v120
	v_rndne_f32_e32 v121, v121
	v_cvt_i32_f32_e32 v118, v118
	v_cvt_i32_f32_e32 v119, v119
	v_cvt_i32_f32_e32 v120, v120
	v_cvt_i32_f32_e32 v121, v121
	v_perm_b32 v118, v119, v118, s16
	v_perm_b32 v120, v121, v120, s17
	v_or_b32_e32 v106, v118, v120
	v_lshlrev_b32_e32 v118, 16, v76
	v_and_b32_e32 v119, 0xffff0000, v76
	v_lshlrev_b32_e32 v120, 16, v77
	v_and_b32_e32 v121, 0xffff0000, v77
	v_pk_mul_f32 v[118:119], v[126:127], v[118:119]
	v_pk_mul_f32 v[120:121], v[126:127], v[120:121]
	v_rndne_f32_e32 v118, v118
	v_rndne_f32_e32 v119, v119
	v_rndne_f32_e32 v120, v120
	v_rndne_f32_e32 v121, v121
	v_cvt_i32_f32_e32 v118, v118
	v_cvt_i32_f32_e32 v119, v119
	v_cvt_i32_f32_e32 v120, v120
	v_cvt_i32_f32_e32 v121, v121
	v_perm_b32 v118, v119, v118, s16
	v_perm_b32 v120, v121, v120, s17
	v_or_b32_e32 v107, v118, v120
	global_store_dwordx2 v136, v[106:107], s[10:11] offset:1024
	s_waitcnt vmcnt(43)
; __device__ __forceinline__ unsigned q8(float x) { return (unsigned)(int)__builtin_rintf(x) & 0xffu; }
; __device__ __forceinline__ void rows_bf16_to_i8(Frame& F, const bf16* XBp, const unsigned* rmax, unsigned* X8, float* sx, int pitch4 = D / 4) {
;     ...
; #pragma unroll
;         for (int j = 0; j < 8; ++j) { v2u o;
;             o.x = q8(blo(w[j].x) * inv) | (q8(bhi(w[j].x) * inv) << 8) | (q8(blo(w[j].y) * inv) << 16) | (q8(bhi(w[j].y) * inv) << 24);
;             o.y = q8(blo(w[j].z) * inv) | (q8(bhi(w[j].z) * inv) << 8) | (q8(blo(w[j].w) * inv) << 16) | (q8(bhi(w[j].w) * inv) << 24);
;             dst[64 * j] = o; }
	v_lshlrev_b32_e32 v118, 16, v78
	v_and_b32_e32 v119, 0xffff0000, v78
	v_lshlrev_b32_e32 v120, 16, v79
	v_and_b32_e32 v121, 0xffff0000, v79
	v_pk_mul_f32 v[118:119], v[126:127], v[118:119]
	v_pk_mul_f32 v[120:121], v[126:127], v[120:121]
	v_rndne_f32_e32 v118, v118
	v_rndne_f32_e32 v119, v119
	v_rndne_f32_e32 v120, v120
	v_rndne_f32_e32 v121, v121
	v_cvt_i32_f32_e32 v118, v118
	v_cvt_i32_f32_e32 v119, v119
	v_cvt_i32_f32_e32 v120, v120
	v_cvt_i32_f32_e32 v121, v121
	v_perm_b32 v118, v119, v118, s16
	v_perm_b32 v120, v121, v120, s17
	v_or_b32_e32 v108, v118, v120
	v_lshlrev_b32_e32 v118, 16, v80
	v_and_b32_e32 v119, 0xffff0000, v80
	v_lshlrev_b32_e32 v120, 16, v81
	v_and_b32_e32 v121, 0xffff0000, v81
	v_pk_mul_f32 v[118:119], v[126:127], v[118:119]
	v_pk_mul_f32 v[120:121], v[126:127], v[120:121]
	v_rndne_f32_e32 v118, v118
	v_rndne_f32_e32 v119, v119
	v_rndne_f32_e32 v120, v120
	v_rndne_f32_e32 v121, v121
	v_cvt_i32_f32_e32 v118, v118
	v_cvt_i32_f32_e32 v119, v119
	v_cvt_i32_f32_e32 v120, v120
	v_cvt_i32_f32_e32 v121, v121
	v_perm_b32 v118, v119, v118, s16
	v_perm_b32 v120, v121, v120, s17
	v_or_b32_e32 v109, v118, v120
	global_store_dwordx2 v136, v[108:109], s[10:11] offset:1536
	s_waitcnt vmcnt(43)
	v_lshlrev_b32_e32 v118, 16, v82
	v_and_b32_e32 v119, 0xffff0000, v82
	v_lshlrev_b32_e32 v120, 16, v83
	v_and_b32_e32 v121, 0xffff0000, v83
	v_pk_mul_f32 v[118:119], v[126:127], v[118:119]
	v_pk_mul_f32 v[120:121], v[126:127], v[120:121]
	v_rndne_f32_e32 v118, v118
	v_rndne_f32_e32 v119, v119
	v_rndne_f32_e32 v120, v120
	v_rndne_f32_e32 v121, v121
	v_cvt_i32_f32_e32 v118, v118
	v_cvt_i32_f32_e32 v119, v119
	v_cvt_i32_f32_e32 v120, v120
	v_cvt_i32_f32_e32 v121, v121
	v_perm_b32 v118, v119, v118, s16
	v_perm_b32 v120, v121, v120, s17
	v_or_b32_e32 v110, v118, v120
	v_lshlrev_b32_e32 v118, 16, v84
	v_and_b32_e32 v119, 0xffff0000, v84
	v_lshlrev_b32_e32 v120, 16, v85
	v_and_b32_e32 v121, 0xffff0000, v85
	v_pk_mul_f32 v[118:119], v[126:127], v[118:119]
	v_pk_mul_f32 v[120:121], v[126:127], v[120:121]
	v_rndne_f32_e32 v118, v118
	v_rndne_f32_e32 v119, v119
	v_rndne_f32_e32 v120, v120
	v_rndne_f32_e32 v121, v121
	v_cvt_i32_f32_e32 v118, v118
	v_cvt_i32_f32_e32 v119, v119
	v_cvt_i32_f32_e32 v120, v120
	v_cvt_i32_f32_e32 v121, v121
	v_perm_b32 v118, v119, v118, s16
	v_perm_b32 v120, v121, v120, s17
	v_or_b32_e32 v111, v118, v120
	global_store_dwordx2 v136, v[110:111], s[10:11] offset:2048
	s_waitcnt vmcnt(43)
	v_lshlrev_b32_e32 v118, 16, v86
	v_and_b32_e32 v119, 0xffff0000, v86
	v_lshlrev_b32_e32 v120, 16, v87
	v_and_b32_e32 v121, 0xffff0000, v87
	v_pk_mul_f32 v[118:119], v[126:127], v[118:119]
	v_pk_mul_f32 v[120:121], v[126:127], v[120:121]
	v_rndne_f32_e32 v118, v118
	v_rndne_f32_e32 v119, v119
	v_rndne_f32_e32 v120, v120
	v_rndne_f32_e32 v121, v121
	v_cvt_i32_f32_e32 v118, v118
	v_cvt_i32_f32_e32 v119, v119
	v_cvt_i32_f32_e32 v120, v120
	v_cvt_i32_f32_e32 v121, v121
	v_perm_b32 v118, v119, v118, s16
	v_perm_b32 v120, v121, v120, s17
	v_or_b32_e32 v112, v118, v120
	v_lshlrev_b32_e32 v118, 16, v88
	v_and_b32_e32 v119, 0xffff0000, v88
	v_lshlrev_b32_e32 v120, 16, v89
	v_and_b32_e32 v121, 0xffff0000, v89
	v_pk_mul_f32 v[118:119], v[126:127], v[118:119]
	v_pk_mul_f32 v[120:121], v[126:127], v[120:121]
	v_rndne_f32_e32 v118, v118
	v_rndne_f32_e32 v119, v119
	v_rndne_f32_e32 v120, v120
	v_rndne_f32_e32 v121, v121
	v_cvt_i32_f32_e32 v118, v118
	v_cvt_i32_f32_e32 v119, v119
	v_cvt_i32_f32_e32 v120, v120
	v_cvt_i32_f32_e32 v121, v121
	v_perm_b32 v118, v119, v118, s16
	v_perm_b32 v120, v121, v120, s17
	v_or_b32_e32 v113, v118, v120
	global_store_dwordx2 v136, v[112:113], s[10:11] offset:2560
	s_waitcnt vmcnt(43)
	v_lshlrev_b32_e32 v118, 16, v90
	v_and_b32_e32 v119, 0xffff0000, v90
	v_lshlrev_b32_e32 v120, 16, v91
	v_and_b32_e32 v121, 0xffff0000, v91
	v_pk_mul_f32 v[118:119], v[126:127], v[118:119]
	v_pk_mul_f32 v[120:121], v[126:127], v[120:121]
	v_rndne_f32_e32 v118, v118
	v_rndne_f32_e32 v119, v119
	v_rndne_f32_e32 v120, v120
	v_rndne_f32_e32 v121, v121
	v_cvt_i32_f32_e32 v118, v118
	v_cvt_i32_f32_e32 v119, v119
	v_cvt_i32_f32_e32 v120, v120
	v_cvt_i32_f32_e32 v121, v121
	v_perm_b32 v118, v119, v118, s16
	v_perm_b32 v120, v121, v120, s17
	v_or_b32_e32 v114, v118, v120
	v_lshlrev_b32_e32 v118, 16, v92
	v_and_b32_e32 v119, 0xffff0000, v92
	v_lshlrev_b32_e32 v120, 16, v93
	v_and_b32_e32 v121, 0xffff0000, v93
	v_pk_mul_f32 v[118:119], v[126:127], v[118:119]
	v_pk_mul_f32 v[120:121], v[126:127], v[120:121]
	v_rndne_f32_e32 v118, v118
	v_rndne_f32_e32 v119, v119
	v_rndne_f32_e32 v120, v120
	v_rndne_f32_e32 v121, v121
	v_cvt_i32_f32_e32 v118, v118
	v_cvt_i32_f32_e32 v119, v119
	v_cvt_i32_f32_e32 v120, v120
	v_cvt_i32_f32_e32 v121, v121
	v_perm_b32 v118, v119, v118, s16
	v_perm_b32 v120, v121, v120, s17
	v_or_b32_e32 v115, v118, v120
	global_store_dwordx2 v136, v[114:115], s[10:11] offset:3072
	s_waitcnt vmcnt(43)
; __device__ __forceinline__ unsigned q8(float x) { return (unsigned)(int)__builtin_rintf(x) & 0xffu; }
; __device__ __forceinline__ void rows_bf16_to_i8(Frame& F, const bf16* XBp, const unsigned* rmax, unsigned* X8, float* sx, int pitch4 = D / 4) {
;     ...
;         const float mx = __builtin_bit_cast(float, rb), inv = mx > 0.f ? 127.0f / mx : 0.f;
;         v2u* dst = (v2u*)(X8 + (size_t)m * pitch4) + lane;
; #pragma unroll
;         for (int j = 0; j < 8; ++j) { v2u o;
;             o.x = q8(blo(w[j].x) * inv) | (q8(bhi(w[j].x) * inv) << 8) | (q8(blo(w[j].y) * inv) << 16) | (q8(bhi(w[j].y) * inv) << 24);
;             o.y = q8(blo(w[j].z) * inv) | (q8(bhi(w[j].z) * inv) << 8) | (q8(blo(w[j].w) * inv) << 16) | (q8(bhi(w[j].w) * inv) << 24);
;             dst[64 * j] = o; }
;         if (lane == 0) sx[m] = mx * (1.0f / 127.0f);
; #pragma unroll
;         for (int j = 0; j < 8; ++j) w[j] = wn[j];
;         rb = rbn;
	v_lshlrev_b32_e32 v118, 16, v94
	v_and_b32_e32 v119, 0xffff0000, v94
	v_lshlrev_b32_e32 v120, 16, v95
	v_and_b32_e32 v121, 0xffff0000, v95
	v_pk_mul_f32 v[118:119], v[126:127], v[118:119]
	v_pk_mul_f32 v[120:121], v[126:127], v[120:121]
	v_rndne_f32_e32 v118, v118
	v_rndne_f32_e32 v119, v119
	v_rndne_f32_e32 v120, v120
	v_rndne_f32_e32 v121, v121
	v_cvt_i32_f32_e32 v118, v118
	v_cvt_i32_f32_e32 v119, v119
	v_cvt_i32_f32_e32 v120, v120
	v_cvt_i32_f32_e32 v121, v121
	v_perm_b32 v118, v119, v118, s16
	v_perm_b32 v120, v121, v120, s17
	v_or_b32_e32 v116, v118, v120
	v_lshlrev_b32_e32 v118, 16, v96
	v_and_b32_e32 v119, 0xffff0000, v96
	v_lshlrev_b32_e32 v120, 16, v97
	v_and_b32_e32 v121, 0xffff0000, v97
	v_pk_mul_f32 v[118:119], v[126:127], v[118:119]
	v_pk_mul_f32 v[120:121], v[126:127], v[120:121]
	v_rndne_f32_e32 v118, v118
	v_rndne_f32_e32 v119, v119
	v_rndne_f32_e32 v120, v120
	v_rndne_f32_e32 v121, v121
	v_cvt_i32_f32_e32 v118, v118
	v_cvt_i32_f32_e32 v119, v119
	v_cvt_i32_f32_e32 v120, v120
	v_cvt_i32_f32_e32 v121, v121
	v_perm_b32 v118, v119, v118, s16
	v_perm_b32 v120, v121, v120, s17
	v_or_b32_e32 v117, v118, v120
	global_store_dwordx2 v136, v[116:117], s[10:11] offset:3584
	s_mov_b64 exec, s[12:13]
	global_store_dword v137, v138, s[8:9]
	s_mov_b64 exec, -1
	s_add_u32 s10, s10, 0x800000
	s_addc_u32 s11, s11, 0
	s_add_u32 s8, s8, 0x2000
	s_addc_u32 s9, s9, 0
	global_load_dword v100, v137, s[6:7]
	global_load_dwordx4 v[66:69], v134, s[4:5] offset:0
	global_load_dwordx4 v[70:73], v134, s[4:5] offset:1024
	global_load_dwordx4 v[74:77], v134, s[4:5] offset:2048
	global_load_dwordx4 v[78:81], v134, s[4:5] offset:3072
	global_load_dwordx4 v[82:85], v135, s[4:5] offset:0
	global_load_dwordx4 v[86:89], v135, s[4:5] offset:1024
	global_load_dwordx4 v[90:93], v135, s[4:5] offset:2048
	global_load_dwordx4 v[94:97], v135, s[4:5] offset:3072
	s_add_u32 s4, s4, 0x1000000
	s_addc_u32 s5, s5, 0
	s_add_u32 s6, s6, 0x2000
	s_addc_u32 s7, s7, 0
	s_waitcnt vmcnt(44)
	v_div_scale_f32 v128, s[14:15], v98, v98, s3
	v_rcp_f32_e32 v129, v128
	v_div_scale_f32 v130, vcc, s3, v98, s3
	v_fma_f32 v131, -v128, v129, 1.0
	v_fmac_f32_e32 v129, v131, v129
	v_mul_f32_e32 v131, v130, v129
	v_fma_f32 v132, -v128, v131, v130
	v_fmac_f32_e32 v131, v132, v129
	v_fma_f32 v128, -v128, v131, v130
	v_div_fmas_f32 v128, v128, v129, v131
	v_div_fixup_f32 v128, v128, v98, s3
	v_cmp_lt_f32_e32 vcc, 0, v98
	v_mul_f32_e32 v138, 0x3c010204, v98
	v_cndmask_b32_e32 v126, 0, v128, vcc
	v_mov_b32_e32 v127, v126
	s_waitcnt vmcnt(43)
	v_lshlrev_b32_e32 v118, 16, v2
	v_and_b32_e32 v119, 0xffff0000, v2
	v_lshlrev_b32_e32 v120, 16, v3
	v_and_b32_e32 v121, 0xffff0000, v3
	v_pk_mul_f32 v[118:119], v[126:127], v[118:119]
	v_pk_mul_f32 v[120:121], v[126:127], v[120:121]
	v_rndne_f32_e32 v118, v118
	v_rndne_f32_e32 v119, v119
	v_rndne_f32_e32 v120, v120
	v_rndne_f32_e32 v121, v121
	v_cvt_i32_f32_e32 v118, v118
	v_cvt_i32_f32_e32 v119, v119
	v_cvt_i32_f32_e32 v120, v120
	v_cvt_i32_f32_e32 v121, v121
	v_perm_b32 v118, v119, v118, s16
	v_perm_b32 v120, v121, v120, s17
	v_or_b32_e32 v102, v118, v120
	v_lshlrev_b32_e32 v118, 16, v4
	v_and_b32_e32 v119, 0xffff0000, v4
	v_lshlrev_b32_e32 v120, 16, v5
	v_and_b32_e32 v121, 0xffff0000, v5
	v_pk_mul_f32 v[118:119], v[126:127], v[118:119]
	v_pk_mul_f32 v[120:121], v[126:127], v[120:121]
	v_rndne_f32_e32 v118, v118
	v_rndne_f32_e32 v119, v119
	v_rndne_f32_e32 v120, v120
	v_rndne_f32_e32 v121, v121
	v_cvt_i32_f32_e32 v118, v118
	v_cvt_i32_f32_e32 v119, v119
	v_cvt_i32_f32_e32 v120, v120
	v_cvt_i32_f32_e32 v121, v121
	v_perm_b32 v118, v119, v118, s16
	v_perm_b32 v120, v121, v120, s17
	v_or_b32_e32 v103, v118, v120
	global_store_dwordx2 v136, v[102:103], s[10:11] offset:0
	s_waitcnt vmcnt(43)
	v_lshlrev_b32_e32 v118, 16, v6
	v_and_b32_e32 v119, 0xffff0000, v6
	v_lshlrev_b32_e32 v120, 16, v7
	v_and_b32_e32 v121, 0xffff0000, v7
	v_pk_mul_f32 v[118:119], v[126:127], v[118:119]
	v_pk_mul_f32 v[120:121], v[126:127], v[120:121]
	v_rndne_f32_e32 v118, v118
	v_rndne_f32_e32 v119, v119
	v_rndne_f32_e32 v120, v120
	v_rndne_f32_e32 v121, v121
	v_cvt_i32_f32_e32 v118, v118
	v_cvt_i32_f32_e32 v119, v119
	v_cvt_i32_f32_e32 v120, v120
	v_cvt_i32_f32_e32 v121, v121
	v_perm_b32 v118, v119, v118, s16
	v_perm_b32 v120, v121, v120, s17
	v_or_b32_e32 v104, v118, v120
	v_lshlrev_b32_e32 v118, 16, v8
	v_and_b32_e32 v119, 0xffff0000, v8
	v_lshlrev_b32_e32 v120, 16, v9
	v_and_b32_e32 v121, 0xffff0000, v9
	v_pk_mul_f32 v[118:119], v[126:127], v[118:119]
	v_pk_mul_f32 v[120:121], v[126:127], v[120:121]
	v_rndne_f32_e32 v118, v118
	v_rndne_f32_e32 v119, v119
	v_rndne_f32_e32 v120, v120
	v_rndne_f32_e32 v121, v121
	v_cvt_i32_f32_e32 v118, v118
	v_cvt_i32_f32_e32 v119, v119
	v_cvt_i32_f32_e32 v120, v120
	v_cvt_i32_f32_e32 v121, v121
	v_perm_b32 v118, v119, v118, s16
	v_perm_b32 v120, v121, v120, s17
	v_or_b32_e32 v105, v118, v120
	global_store_dwordx2 v136, v[104:105], s[10:11] offset:512
	s_waitcnt vmcnt(43)
	v_lshlrev_b32_e32 v118, 16, v10
	v_and_b32_e32 v119, 0xffff0000, v10
	v_lshlrev_b32_e32 v120, 16, v11
	v_and_b32_e32 v121, 0xffff0000, v11
	v_pk_mul_f32 v[118:119], v[126:127], v[118:119]
	v_pk_mul_f32 v[120:121], v[126:127], v[120:121]
	v_rndne_f32_e32 v118, v118
	v_rndne_f32_e32 v119, v119
	v_rndne_f32_e32 v120, v120
	v_rndne_f32_e32 v121, v121
	v_cvt_i32_f32_e32 v118, v118
	v_cvt_i32_f32_e32 v119, v119
	v_cvt_i32_f32_e32 v120, v120
	v_cvt_i32_f32_e32 v121, v121
	v_perm_b32 v118, v119, v118, s16
	v_perm_b32 v120, v121, v120, s17
	v_or_b32_e32 v106, v118, v120
	v_lshlrev_b32_e32 v118, 16, v12
	v_and_b32_e32 v119, 0xffff0000, v12
	v_lshlrev_b32_e32 v120, 16, v13
	v_and_b32_e32 v121, 0xffff0000, v13
	v_pk_mul_f32 v[118:119], v[126:127], v[118:119]
	v_pk_mul_f32 v[120:121], v[126:127], v[120:121]
	v_rndne_f32_e32 v118, v118
	v_rndne_f32_e32 v119, v119
	v_rndne_f32_e32 v120, v120
	v_rndne_f32_e32 v121, v121
	v_cvt_i32_f32_e32 v118, v118
	v_cvt_i32_f32_e32 v119, v119
	v_cvt_i32_f32_e32 v120, v120
	v_cvt_i32_f32_e32 v121, v121
	v_perm_b32 v118, v119, v118, s16
	v_perm_b32 v120, v121, v120, s17
	v_or_b32_e32 v107, v118, v120
	global_store_dwordx2 v136, v[106:107], s[10:11] offset:1024
	s_waitcnt vmcnt(43)
; __device__ __forceinline__ unsigned q8(float x) { return (unsigned)(int)__builtin_rintf(x) & 0xffu; }
; __device__ __forceinline__ void rows_bf16_to_i8(Frame& F, const bf16* XBp, const unsigned* rmax, unsigned* X8, float* sx, int pitch4 = D / 4) {
;     ...
; #pragma unroll
;         for (int j = 0; j < 8; ++j) { v2u o;
;             o.x = q8(blo(w[j].x) * inv) | (q8(bhi(w[j].x) * inv) << 8) | (q8(blo(w[j].y) * inv) << 16) | (q8(bhi(w[j].y) * inv) << 24);
;             o.y = q8(blo(w[j].z) * inv) | (q8(bhi(w[j].z) * inv) << 8) | (q8(blo(w[j].w) * inv) << 16) | (q8(bhi(w[j].w) * inv) << 24);
;             dst[64 * j] = o; }
	v_lshlrev_b32_e32 v118, 16, v14
	v_and_b32_e32 v119, 0xffff0000, v14
	v_lshlrev_b32_e32 v120, 16, v15
	v_and_b32_e32 v121, 0xffff0000, v15
	v_pk_mul_f32 v[118:119], v[126:127], v[118:119]
	v_pk_mul_f32 v[120:121], v[126:127], v[120:121]
	v_rndne_f32_e32 v118, v118
	v_rndne_f32_e32 v119, v119
	v_rndne_f32_e32 v120, v120
	v_rndne_f32_e32 v121, v121
	v_cvt_i32_f32_e32 v118, v118
	v_cvt_i32_f32_e32 v119, v119
	v_cvt_i32_f32_e32 v120, v120
	v_cvt_i32_f32_e32 v121, v121
	v_perm_b32 v118, v119, v118, s16
	v_perm_b32 v120, v121, v120, s17
	v_or_b32_e32 v108, v118, v120
	v_lshlrev_b32_e32 v118, 16, v16
	v_and_b32_e32 v119, 0xffff0000, v16
	v_lshlrev_b32_e32 v120, 16, v17
	v_and_b32_e32 v121, 0xffff0000, v17
	v_pk_mul_f32 v[118:119], v[126:127], v[118:119]
	v_pk_mul_f32 v[120:121], v[126:127], v[120:121]
	v_rndne_f32_e32 v118, v118
	v_rndne_f32_e32 v119, v119
	v_rndne_f32_e32 v120, v120
	v_rndne_f32_e32 v121, v121
	v_cvt_i32_f32_e32 v118, v118
	v_cvt_i32_f32_e32 v119, v119
	v_cvt_i32_f32_e32 v120, v120
	v_cvt_i32_f32_e32 v121, v121
	v_perm_b32 v118, v119, v118, s16
	v_perm_b32 v120, v121, v120, s17
	v_or_b32_e32 v109, v118, v120
	global_store_dwordx2 v136, v[108:109], s[10:11] offset:1536
	s_waitcnt vmcnt(43)
	v_lshlrev_b32_e32 v118, 16, v18
	v_and_b32_e32 v119, 0xffff0000, v18
	v_lshlrev_b32_e32 v120, 16, v19
	v_and_b32_e32 v121, 0xffff0000, v19
	v_pk_mul_f32 v[118:119], v[126:127], v[118:119]
	v_pk_mul_f32 v[120:121], v[126:127], v[120:121]
	v_rndne_f32_e32 v118, v118
	v_rndne_f32_e32 v119, v119
	v_rndne_f32_e32 v120, v120
	v_rndne_f32_e32 v121, v121
	v_cvt_i32_f32_e32 v118, v118
	v_cvt_i32_f32_e32 v119, v119
	v_cvt_i32_f32_e32 v120, v120
	v_cvt_i32_f32_e32 v121, v121
	v_perm_b32 v118, v119, v118, s16
	v_perm_b32 v120, v121, v120, s17
	v_or_b32_e32 v110, v118, v120
	v_lshlrev_b32_e32 v118, 16, v20
	v_and_b32_e32 v119, 0xffff0000, v20
	v_lshlrev_b32_e32 v120, 16, v21
	v_and_b32_e32 v121, 0xffff0000, v21
	v_pk_mul_f32 v[118:119], v[126:127], v[118:119]
	v_pk_mul_f32 v[120:121], v[126:127], v[120:121]
	v_rndne_f32_e32 v118, v118
	v_rndne_f32_e32 v119, v119
	v_rndne_f32_e32 v120, v120
	v_rndne_f32_e32 v121, v121
	v_cvt_i32_f32_e32 v118, v118
	v_cvt_i32_f32_e32 v119, v119
	v_cvt_i32_f32_e32 v120, v120
	v_cvt_i32_f32_e32 v121, v121
	v_perm_b32 v118, v119, v118, s16
	v_perm_b32 v120, v121, v120, s17
	v_or_b32_e32 v111, v118, v120
	global_store_dwordx2 v136, v[110:111], s[10:11] offset:2048
	s_waitcnt vmcnt(43)
	v_lshlrev_b32_e32 v118, 16, v22
	v_and_b32_e32 v119, 0xffff0000, v22
	v_lshlrev_b32_e32 v120, 16, v23
	v_and_b32_e32 v121, 0xffff0000, v23
	v_pk_mul_f32 v[118:119], v[126:127], v[118:119]
	v_pk_mul_f32 v[120:121], v[126:127], v[120:121]
	v_rndne_f32_e32 v118, v118
	v_rndne_f32_e32 v119, v119
	v_rndne_f32_e32 v120, v120
	v_rndne_f32_e32 v121, v121
	v_cvt_i32_f32_e32 v118, v118
	v_cvt_i32_f32_e32 v119, v119
	v_cvt_i32_f32_e32 v120, v120
	v_cvt_i32_f32_e32 v121, v121
	v_perm_b32 v118, v119, v118, s16
	v_perm_b32 v120, v121, v120, s17
	v_or_b32_e32 v112, v118, v120
	v_lshlrev_b32_e32 v118, 16, v24
	v_and_b32_e32 v119, 0xffff0000, v24
	v_lshlrev_b32_e32 v120, 16, v25
	v_and_b32_e32 v121, 0xffff0000, v25
	v_pk_mul_f32 v[118:119], v[126:127], v[118:119]
	v_pk_mul_f32 v[120:121], v[126:127], v[120:121]
	v_rndne_f32_e32 v118, v118
	v_rndne_f32_e32 v119, v119
	v_rndne_f32_e32 v120, v120
	v_rndne_f32_e32 v121, v121
	v_cvt_i32_f32_e32 v118, v118
	v_cvt_i32_f32_e32 v119, v119
	v_cvt_i32_f32_e32 v120, v120
	v_cvt_i32_f32_e32 v121, v121
	v_perm_b32 v118, v119, v118, s16
	v_perm_b32 v120, v121, v120, s17
	v_or_b32_e32 v113, v118, v120
	global_store_dwordx2 v136, v[112:113], s[10:11] offset:2560
	s_waitcnt vmcnt(43)
	v_lshlrev_b32_e32 v118, 16, v26
	v_and_b32_e32 v119, 0xffff0000, v26
	v_lshlrev_b32_e32 v120, 16, v27
	v_and_b32_e32 v121, 0xffff0000, v27
	v_pk_mul_f32 v[118:119], v[126:127], v[118:119]
	v_pk_mul_f32 v[120:121], v[126:127], v[120:121]
	v_rndne_f32_e32 v118, v118
	v_rndne_f32_e32 v119, v119
	v_rndne_f32_e32 v120, v120
	v_rndne_f32_e32 v121, v121
	v_cvt_i32_f32_e32 v118, v118
	v_cvt_i32_f32_e32 v119, v119
	v_cvt_i32_f32_e32 v120, v120
	v_cvt_i32_f32_e32 v121, v121
	v_perm_b32 v118, v119, v118, s16
	v_perm_b32 v120, v121, v120, s17
	v_or_b32_e32 v114, v118, v120
	v_lshlrev_b32_e32 v118, 16, v28
	v_and_b32_e32 v119, 0xffff0000, v28
	v_lshlrev_b32_e32 v120, 16, v29
	v_and_b32_e32 v121, 0xffff0000, v29
	v_pk_mul_f32 v[118:119], v[126:127], v[118:119]
	v_pk_mul_f32 v[120:121], v[126:127], v[120:121]
	v_rndne_f32_e32 v118, v118
	v_rndne_f32_e32 v119, v119
	v_rndne_f32_e32 v120, v120
	v_rndne_f32_e32 v121, v121
	v_cvt_i32_f32_e32 v118, v118
	v_cvt_i32_f32_e32 v119, v119
	v_cvt_i32_f32_e32 v120, v120
	v_cvt_i32_f32_e32 v121, v121
	v_perm_b32 v118, v119, v118, s16
	v_perm_b32 v120, v121, v120, s17
	v_or_b32_e32 v115, v118, v120
	global_store_dwordx2 v136, v[114:115], s[10:11] offset:3072
	s_waitcnt vmcnt(43)
; __device__ __forceinline__ unsigned q8(float x) { return (unsigned)(int)__builtin_rintf(x) & 0xffu; }
; __device__ __forceinline__ void rows_bf16_to_i8(Frame& F, const bf16* XBp, const unsigned* rmax, unsigned* X8, float* sx, int pitch4 = D / 4) {
;     ...
;         const float mx = __builtin_bit_cast(float, rb), inv = mx > 0.f ? 127.0f / mx : 0.f;
;         v2u* dst = (v2u*)(X8 + (size_t)m * pitch4) + lane;
; #pragma unroll
;         for (int j = 0; j < 8; ++j) { v2u o;
;             o.x = q8(blo(w[j].x) * inv) | (q8(bhi(w[j].x) * inv) << 8) | (q8(blo(w[j].y) * inv) << 16) | (q8(bhi(w[j].y) * inv) << 24);
;             o.y = q8(blo(w[j].z) * inv) | (q8(bhi(w[j].z) * inv) << 8) | (q8(blo(w[j].w) * inv) << 16) | (q8(bhi(w[j].w) * inv) << 24);
;             dst[64 * j] = o; }
;         if (lane == 0) sx[m] = mx * (1.0f / 127.0f);
; #pragma unroll
;         for (int j = 0; j < 8; ++j) w[j] = wn[j];
;         rb = rbn;
	v_lshlrev_b32_e32 v118, 16, v30
	v_and_b32_e32 v119, 0xffff0000, v30
	v_lshlrev_b32_e32 v120, 16, v31
	v_and_b32_e32 v121, 0xffff0000, v31
	v_pk_mul_f32 v[118:119], v[126:127], v[118:119]
	v_pk_mul_f32 v[120:121], v[126:127], v[120:121]
	v_rndne_f32_e32 v118, v118
	v_rndne_f32_e32 v119, v119
	v_rndne_f32_e32 v120, v120
	v_rndne_f32_e32 v121, v121
	v_cvt_i32_f32_e32 v118, v118
	v_cvt_i32_f32_e32 v119, v119
	v_cvt_i32_f32_e32 v120, v120
	v_cvt_i32_f32_e32 v121, v121
	v_perm_b32 v118, v119, v118, s16
	v_perm_b32 v120, v121, v120, s17
	v_or_b32_e32 v116, v118, v120
	v_lshlrev_b32_e32 v118, 16, v32
	v_and_b32_e32 v119, 0xffff0000, v32
	v_lshlrev_b32_e32 v120, 16, v33
	v_and_b32_e32 v121, 0xffff0000, v33
	v_pk_mul_f32 v[118:119], v[126:127], v[118:119]
	v_pk_mul_f32 v[120:121], v[126:127], v[120:121]
	v_rndne_f32_e32 v118, v118
	v_rndne_f32_e32 v119, v119
	v_rndne_f32_e32 v120, v120
	v_rndne_f32_e32 v121, v121
	v_cvt_i32_f32_e32 v118, v118
	v_cvt_i32_f32_e32 v119, v119
	v_cvt_i32_f32_e32 v120, v120
	v_cvt_i32_f32_e32 v121, v121
	v_perm_b32 v118, v119, v118, s16
	v_perm_b32 v120, v121, v120, s17
	v_or_b32_e32 v117, v118, v120
	global_store_dwordx2 v136, v[116:117], s[10:11] offset:3584
	s_mov_b64 exec, s[12:13]
	global_store_dword v137, v138, s[8:9]
	s_mov_b64 exec, -1
	s_add_u32 s10, s10, 0x800000
	s_addc_u32 s11, s11, 0
	s_add_u32 s8, s8, 0x2000
	s_addc_u32 s9, s9, 0
	global_load_dword v98, v137, s[6:7]
	global_load_dwordx4 v[2:5], v134, s[4:5] offset:0
	global_load_dwordx4 v[6:9], v134, s[4:5] offset:1024
	global_load_dwordx4 v[10:13], v134, s[4:5] offset:2048
	global_load_dwordx4 v[14:17], v134, s[4:5] offset:3072
	global_load_dwordx4 v[18:21], v135, s[4:5] offset:0
	global_load_dwordx4 v[22:25], v135, s[4:5] offset:1024
	global_load_dwordx4 v[26:29], v135, s[4:5] offset:2048
	global_load_dwordx4 v[30:33], v135, s[4:5] offset:3072
	s_add_u32 s4, s4, 0x1000000
	s_addc_u32 s5, s5, 0
	s_add_u32 s6, s6, 0x2000
	s_addc_u32 s7, s7, 0
	s_waitcnt vmcnt(44)
	v_div_scale_f32 v128, s[14:15], v99, v99, s3
	v_rcp_f32_e32 v129, v128
	v_div_scale_f32 v130, vcc, s3, v99, s3
	v_fma_f32 v131, -v128, v129, 1.0
	v_fmac_f32_e32 v129, v131, v129
	v_mul_f32_e32 v131, v130, v129
	v_fma_f32 v132, -v128, v131, v130
	v_fmac_f32_e32 v131, v132, v129
	v_fma_f32 v128, -v128, v131, v130
	v_div_fmas_f32 v128, v128, v129, v131
	v_div_fixup_f32 v128, v128, v99, s3
	v_cmp_lt_f32_e32 vcc, 0, v99
	v_mul_f32_e32 v138, 0x3c010204, v99
	v_cndmask_b32_e32 v126, 0, v128, vcc
	v_mov_b32_e32 v127, v126
	s_waitcnt vmcnt(43)
	v_lshlrev_b32_e32 v118, 16, v34
	v_and_b32_e32 v119, 0xffff0000, v34
	v_lshlrev_b32_e32 v120, 16, v35
	v_and_b32_e32 v121, 0xffff0000, v35
	v_pk_mul_f32 v[118:119], v[126:127], v[118:119]
	v_pk_mul_f32 v[120:121], v[126:127], v[120:121]
	v_rndne_f32_e32 v118, v118
	v_rndne_f32_e32 v119, v119
	v_rndne_f32_e32 v120, v120
	v_rndne_f32_e32 v121, v121
	v_cvt_i32_f32_e32 v118, v118
	v_cvt_i32_f32_e32 v119, v119
	v_cvt_i32_f32_e32 v120, v120
	v_cvt_i32_f32_e32 v121, v121
	v_perm_b32 v118, v119, v118, s16
	v_perm_b32 v120, v121, v120, s17
	v_or_b32_e32 v102, v118, v120
	v_lshlrev_b32_e32 v118, 16, v36
	v_and_b32_e32 v119, 0xffff0000, v36
	v_lshlrev_b32_e32 v120, 16, v37
	v_and_b32_e32 v121, 0xffff0000, v37
	v_pk_mul_f32 v[118:119], v[126:127], v[118:119]
	v_pk_mul_f32 v[120:121], v[126:127], v[120:121]
	v_rndne_f32_e32 v118, v118
	v_rndne_f32_e32 v119, v119
	v_rndne_f32_e32 v120, v120
	v_rndne_f32_e32 v121, v121
	v_cvt_i32_f32_e32 v118, v118
	v_cvt_i32_f32_e32 v119, v119
	v_cvt_i32_f32_e32 v120, v120
	v_cvt_i32_f32_e32 v121, v121
	v_perm_b32 v118, v119, v118, s16
	v_perm_b32 v120, v121, v120, s17
	v_or_b32_e32 v103, v118, v120
	global_store_dwordx2 v136, v[102:103], s[10:11] offset:0
	s_waitcnt vmcnt(43)
	v_lshlrev_b32_e32 v118, 16, v38
	v_and_b32_e32 v119, 0xffff0000, v38
	v_lshlrev_b32_e32 v120, 16, v39
	v_and_b32_e32 v121, 0xffff0000, v39
	v_pk_mul_f32 v[118:119], v[126:127], v[118:119]
	v_pk_mul_f32 v[120:121], v[126:127], v[120:121]
	v_rndne_f32_e32 v118, v118
	v_rndne_f32_e32 v119, v119
	v_rndne_f32_e32 v120, v120
	v_rndne_f32_e32 v121, v121
	v_cvt_i32_f32_e32 v118, v118
	v_cvt_i32_f32_e32 v119, v119
	v_cvt_i32_f32_e32 v120, v120
	v_cvt_i32_f32_e32 v121, v121
	v_perm_b32 v118, v119, v118, s16
	v_perm_b32 v120, v121, v120, s17
	v_or_b32_e32 v104, v118, v120
	v_lshlrev_b32_e32 v118, 16, v40
	v_and_b32_e32 v119, 0xffff0000, v40
	v_lshlrev_b32_e32 v120, 16, v41
	v_and_b32_e32 v121, 0xffff0000, v41
	v_pk_mul_f32 v[118:119], v[126:127], v[118:119]
	v_pk_mul_f32 v[120:121], v[126:127], v[120:121]
	v_rndne_f32_e32 v118, v118
	v_rndne_f32_e32 v119, v119
	v_rndne_f32_e32 v120, v120
	v_rndne_f32_e32 v121, v121
	v_cvt_i32_f32_e32 v118, v118
	v_cvt_i32_f32_e32 v119, v119
	v_cvt_i32_f32_e32 v120, v120
	v_cvt_i32_f32_e32 v121, v121
	v_perm_b32 v118, v119, v118, s16
	v_perm_b32 v120, v121, v120, s17
	v_or_b32_e32 v105, v118, v120
	global_store_dwordx2 v136, v[104:105], s[10:11] offset:512
	s_waitcnt vmcnt(43)
	v_lshlrev_b32_e32 v118, 16, v42
	v_and_b32_e32 v119, 0xffff0000, v42
	v_lshlrev_b32_e32 v120, 16, v43
	v_and_b32_e32 v121, 0xffff0000, v43
	v_pk_mul_f32 v[118:119], v[126:127], v[118:119]
	v_pk_mul_f32 v[120:121], v[126:127], v[120:121]
	v_rndne_f32_e32 v118, v118
	v_rndne_f32_e32 v119, v119
	v_rndne_f32_e32 v120, v120
	v_rndne_f32_e32 v121, v121
	v_cvt_i32_f32_e32 v118, v118
	v_cvt_i32_f32_e32 v119, v119
	v_cvt_i32_f32_e32 v120, v120
	v_cvt_i32_f32_e32 v121, v121
	v_perm_b32 v118, v119, v118, s16
	v_perm_b32 v120, v121, v120, s17
	v_or_b32_e32 v106, v118, v120
	v_lshlrev_b32_e32 v118, 16, v44
	v_and_b32_e32 v119, 0xffff0000, v44
	v_lshlrev_b32_e32 v120, 16, v45
	v_and_b32_e32 v121, 0xffff0000, v45
	v_pk_mul_f32 v[118:119], v[126:127], v[118:119]
	v_pk_mul_f32 v[120:121], v[126:127], v[120:121]
	v_rndne_f32_e32 v118, v118
	v_rndne_f32_e32 v119, v119
	v_rndne_f32_e32 v120, v120
	v_rndne_f32_e32 v121, v121
	v_cvt_i32_f32_e32 v118, v118
	v_cvt_i32_f32_e32 v119, v119
	v_cvt_i32_f32_e32 v120, v120
	v_cvt_i32_f32_e32 v121, v121
	v_perm_b32 v118, v119, v118, s16
	v_perm_b32 v120, v121, v120, s17
	v_or_b32_e32 v107, v118, v120
	global_store_dwordx2 v136, v[106:107], s[10:11] offset:1024
	s_waitcnt vmcnt(43)
; __device__ __forceinline__ unsigned q8(float x) { return (unsigned)(int)__builtin_rintf(x) & 0xffu; }
; __device__ __forceinline__ void rows_bf16_to_i8(Frame& F, const bf16* XBp, const unsigned* rmax, unsigned* X8, float* sx, int pitch4 = D / 4) {
;     ...
; #pragma unroll
;         for (int j = 0; j < 8; ++j) { v2u o;
;             o.x = q8(blo(w[j].x) * inv) | (q8(bhi(w[j].x) * inv) << 8) | (q8(blo(w[j].y) * inv) << 16) | (q8(bhi(w[j].y) * inv) << 24);
;             o.y = q8(blo(w[j].z) * inv) | (q8(bhi(w[j].z) * inv) << 8) | (q8(blo(w[j].w) * inv) << 16) | (q8(bhi(w[j].w) * inv) << 24);
;             dst[64 * j] = o; }
	v_lshlrev_b32_e32 v118, 16, v46
	v_and_b32_e32 v119, 0xffff0000, v46
	v_lshlrev_b32_e32 v120, 16, v47
	v_and_b32_e32 v121, 0xffff0000, v47
	v_pk_mul_f32 v[118:119], v[126:127], v[118:119]
	v_pk_mul_f32 v[120:121], v[126:127], v[120:121]
	v_rndne_f32_e32 v118, v118
	v_rndne_f32_e32 v119, v119
	v_rndne_f32_e32 v120, v120
	v_rndne_f32_e32 v121, v121
	v_cvt_i32_f32_e32 v118, v118
	v_cvt_i32_f32_e32 v119, v119
	v_cvt_i32_f32_e32 v120, v120
	v_cvt_i32_f32_e32 v121, v121
	v_perm_b32 v118, v119, v118, s16
	v_perm_b32 v120, v121, v120, s17
	v_or_b32_e32 v108, v118, v120
	v_lshlrev_b32_e32 v118, 16, v48
	v_and_b32_e32 v119, 0xffff0000, v48
	v_lshlrev_b32_e32 v120, 16, v49
	v_and_b32_e32 v121, 0xffff0000, v49
	v_pk_mul_f32 v[118:119], v[126:127], v[118:119]
	v_pk_mul_f32 v[120:121], v[126:127], v[120:121]
	v_rndne_f32_e32 v118, v118
	v_rndne_f32_e32 v119, v119
	v_rndne_f32_e32 v120, v120
	v_rndne_f32_e32 v121, v121
	v_cvt_i32_f32_e32 v118, v118
	v_cvt_i32_f32_e32 v119, v119
	v_cvt_i32_f32_e32 v120, v120
	v_cvt_i32_f32_e32 v121, v121
	v_perm_b32 v118, v119, v118, s16
	v_perm_b32 v120, v121, v120, s17
	v_or_b32_e32 v109, v118, v120
	global_store_dwordx2 v136, v[108:109], s[10:11] offset:1536
	s_waitcnt vmcnt(43)
	v_lshlrev_b32_e32 v118, 16, v50
	v_and_b32_e32 v119, 0xffff0000, v50
	v_lshlrev_b32_e32 v120, 16, v51
	v_and_b32_e32 v121, 0xffff0000, v51
	v_pk_mul_f32 v[118:119], v[126:127], v[118:119]
	v_pk_mul_f32 v[120:121], v[126:127], v[120:121]
	v_rndne_f32_e32 v118, v118
	v_rndne_f32_e32 v119, v119
	v_rndne_f32_e32 v120, v120
	v_rndne_f32_e32 v121, v121
	v_cvt_i32_f32_e32 v118, v118
	v_cvt_i32_f32_e32 v119, v119
	v_cvt_i32_f32_e32 v120, v120
	v_cvt_i32_f32_e32 v121, v121
	v_perm_b32 v118, v119, v118, s16
	v_perm_b32 v120, v121, v120, s17
	v_or_b32_e32 v110, v118, v120
	v_lshlrev_b32_e32 v118, 16, v52
	v_and_b32_e32 v119, 0xffff0000, v52
	v_lshlrev_b32_e32 v120, 16, v53
	v_and_b32_e32 v121, 0xffff0000, v53
	v_pk_mul_f32 v[118:119], v[126:127], v[118:119]
	v_pk_mul_f32 v[120:121], v[126:127], v[120:121]
	v_rndne_f32_e32 v118, v118
	v_rndne_f32_e32 v119, v119
	v_rndne_f32_e32 v120, v120
	v_rndne_f32_e32 v121, v121
	v_cvt_i32_f32_e32 v118, v118
	v_cvt_i32_f32_e32 v119, v119
	v_cvt_i32_f32_e32 v120, v120
	v_cvt_i32_f32_e32 v121, v121
	v_perm_b32 v118, v119, v118, s16
	v_perm_b32 v120, v121, v120, s17
	v_or_b32_e32 v111, v118, v120
	global_store_dwordx2 v136, v[110:111], s[10:11] offset:2048
	s_waitcnt vmcnt(43)
	v_lshlrev_b32_e32 v118, 16, v54
	v_and_b32_e32 v119, 0xffff0000, v54
	v_lshlrev_b32_e32 v120, 16, v55
	v_and_b32_e32 v121, 0xffff0000, v55
	v_pk_mul_f32 v[118:119], v[126:127], v[118:119]
	v_pk_mul_f32 v[120:121], v[126:127], v[120:121]
	v_rndne_f32_e32 v118, v118
	v_rndne_f32_e32 v119, v119
	v_rndne_f32_e32 v120, v120
	v_rndne_f32_e32 v121, v121
	v_cvt_i32_f32_e32 v118, v118
	v_cvt_i32_f32_e32 v119, v119
	v_cvt_i32_f32_e32 v120, v120
	v_cvt_i32_f32_e32 v121, v121
	v_perm_b32 v118, v119, v118, s16
	v_perm_b32 v120, v121, v120, s17
	v_or_b32_e32 v112, v118, v120
	v_lshlrev_b32_e32 v118, 16, v56
	v_and_b32_e32 v119, 0xffff0000, v56
	v_lshlrev_b32_e32 v120, 16, v57
	v_and_b32_e32 v121, 0xffff0000, v57
	v_pk_mul_f32 v[118:119], v[126:127], v[118:119]
	v_pk_mul_f32 v[120:121], v[126:127], v[120:121]
	v_rndne_f32_e32 v118, v118
	v_rndne_f32_e32 v119, v119
	v_rndne_f32_e32 v120, v120
	v_rndne_f32_e32 v121, v121
	v_cvt_i32_f32_e32 v118, v118
	v_cvt_i32_f32_e32 v119, v119
	v_cvt_i32_f32_e32 v120, v120
	v_cvt_i32_f32_e32 v121, v121
	v_perm_b32 v118, v119, v118, s16
	v_perm_b32 v120, v121, v120, s17
	v_or_b32_e32 v113, v118, v120
	global_store_dwordx2 v136, v[112:113], s[10:11] offset:2560
	s_waitcnt vmcnt(43)
	v_lshlrev_b32_e32 v118, 16, v58
	v_and_b32_e32 v119, 0xffff0000, v58
	v_lshlrev_b32_e32 v120, 16, v59
	v_and_b32_e32 v121, 0xffff0000, v59
	v_pk_mul_f32 v[118:119], v[126:127], v[118:119]
	v_pk_mul_f32 v[120:121], v[126:127], v[120:121]
	v_rndne_f32_e32 v118, v118
	v_rndne_f32_e32 v119, v119
	v_rndne_f32_e32 v120, v120
	v_rndne_f32_e32 v121, v121
	v_cvt_i32_f32_e32 v118, v118
	v_cvt_i32_f32_e32 v119, v119
	v_cvt_i32_f32_e32 v120, v120
	v_cvt_i32_f32_e32 v121, v121
	v_perm_b32 v118, v119, v118, s16
	v_perm_b32 v120, v121, v120, s17
	v_or_b32_e32 v114, v118, v120
	v_lshlrev_b32_e32 v118, 16, v60
	v_and_b32_e32 v119, 0xffff0000, v60
	v_lshlrev_b32_e32 v120, 16, v61
	v_and_b32_e32 v121, 0xffff0000, v61
	v_pk_mul_f32 v[118:119], v[126:127], v[118:119]
	v_pk_mul_f32 v[120:121], v[126:127], v[120:121]
	v_rndne_f32_e32 v118, v118
	v_rndne_f32_e32 v119, v119
	v_rndne_f32_e32 v120, v120
	v_rndne_f32_e32 v121, v121
	v_cvt_i32_f32_e32 v118, v118
	v_cvt_i32_f32_e32 v119, v119
	v_cvt_i32_f32_e32 v120, v120
	v_cvt_i32_f32_e32 v121, v121
	v_perm_b32 v118, v119, v118, s16
	v_perm_b32 v120, v121, v120, s17
	v_or_b32_e32 v115, v118, v120
	global_store_dwordx2 v136, v[114:115], s[10:11] offset:3072
	s_waitcnt vmcnt(43)
; __device__ __forceinline__ unsigned q8(float x) { return (unsigned)(int)__builtin_rintf(x) & 0xffu; }
; __device__ __forceinline__ void rows_bf16_to_i8(Frame& F, const bf16* XBp, const unsigned* rmax, unsigned* X8, float* sx, int pitch4 = D / 4) {
;     ...
;         const float mx = __builtin_bit_cast(float, rb), inv = mx > 0.f ? 127.0f / mx : 0.f;
;         v2u* dst = (v2u*)(X8 + (size_t)m * pitch4) + lane;
; #pragma unroll
;         for (int j = 0; j < 8; ++j) { v2u o;
;             o.x = q8(blo(w[j].x) * inv) | (q8(bhi(w[j].x) * inv) << 8) | (q8(blo(w[j].y) * inv) << 16) | (q8(bhi(w[j].y) * inv) << 24);
;             o.y = q8(blo(w[j].z) * inv) | (q8(bhi(w[j].z) * inv) << 8) | (q8(blo(w[j].w) * inv) << 16) | (q8(bhi(w[j].w) * inv) << 24);
;             dst[64 * j] = o; }
;         if (lane == 0) sx[m] = mx * (1.0f / 127.0f);
; #pragma unroll
;         for (int j = 0; j < 8; ++j) w[j] = wn[j];
;         rb = rbn;
	v_lshlrev_b32_e32 v118, 16, v62
	v_and_b32_e32 v119, 0xffff0000, v62
	v_lshlrev_b32_e32 v120, 16, v63
	v_and_b32_e32 v121, 0xffff0000, v63
	v_pk_mul_f32 v[118:119], v[126:127], v[118:119]
	v_pk_mul_f32 v[120:121], v[126:127], v[120:121]
	v_rndne_f32_e32 v118, v118
	v_rndne_f32_e32 v119, v119
	v_rndne_f32_e32 v120, v120
	v_rndne_f32_e32 v121, v121
	v_cvt_i32_f32_e32 v118, v118
	v_cvt_i32_f32_e32 v119, v119
	v_cvt_i32_f32_e32 v120, v120
	v_cvt_i32_f32_e32 v121, v121
	v_perm_b32 v118, v119, v118, s16
	v_perm_b32 v120, v121, v120, s17
	v_or_b32_e32 v116, v118, v120
	v_lshlrev_b32_e32 v118, 16, v64
	v_and_b32_e32 v119, 0xffff0000, v64
	v_lshlrev_b32_e32 v120, 16, v65
	v_and_b32_e32 v121, 0xffff0000, v65
	v_pk_mul_f32 v[118:119], v[126:127], v[118:119]
	v_pk_mul_f32 v[120:121], v[126:127], v[120:121]
	v_rndne_f32_e32 v118, v118
	v_rndne_f32_e32 v119, v119
	v_rndne_f32_e32 v120, v120
	v_rndne_f32_e32 v121, v121
	v_cvt_i32_f32_e32 v118, v118
	v_cvt_i32_f32_e32 v119, v119
	v_cvt_i32_f32_e32 v120, v120
	v_cvt_i32_f32_e32 v121, v121
	v_perm_b32 v118, v119, v118, s16
	v_perm_b32 v120, v121, v120, s17
	v_or_b32_e32 v117, v118, v120
	global_store_dwordx2 v136, v[116:117], s[10:11] offset:3584
	s_mov_b64 exec, s[12:13]
	global_store_dword v137, v138, s[8:9]
	s_mov_b64 exec, -1
	s_add_u32 s10, s10, 0x800000
	s_addc_u32 s11, s11, 0
	s_add_u32 s8, s8, 0x2000
	s_addc_u32 s9, s9, 0
	global_load_dword v99, v137, s[6:7]
	global_load_dwordx4 v[34:37], v134, s[4:5] offset:0
	global_load_dwordx4 v[38:41], v134, s[4:5] offset:1024
	global_load_dwordx4 v[42:45], v134, s[4:5] offset:2048
	global_load_dwordx4 v[46:49], v134, s[4:5] offset:3072
	global_load_dwordx4 v[50:53], v135, s[4:5] offset:0
	global_load_dwordx4 v[54:57], v135, s[4:5] offset:1024
	global_load_dwordx4 v[58:61], v135, s[4:5] offset:2048
	global_load_dwordx4 v[62:65], v135, s[4:5] offset:3072
	s_add_u32 s4, s4, 0x1000000
	s_addc_u32 s5, s5, 0
	s_add_u32 s6, s6, 0x2000
	s_addc_u32 s7, s7, 0
	s_waitcnt vmcnt(44)
	v_div_scale_f32 v128, s[14:15], v100, v100, s3
	v_rcp_f32_e32 v129, v128
	v_div_scale_f32 v130, vcc, s3, v100, s3
	v_fma_f32 v131, -v128, v129, 1.0
	v_fmac_f32_e32 v129, v131, v129
	v_mul_f32_e32 v131, v130, v129
	v_fma_f32 v132, -v128, v131, v130
	v_fmac_f32_e32 v131, v132, v129
	v_fma_f32 v128, -v128, v131, v130
	v_div_fmas_f32 v128, v128, v129, v131
	v_div_fixup_f32 v128, v128, v100, s3
	v_cmp_lt_f32_e32 vcc, 0, v100
	v_mul_f32_e32 v138, 0x3c010204, v100
	v_cndmask_b32_e32 v126, 0, v128, vcc
	v_mov_b32_e32 v127, v126
	s_waitcnt vmcnt(43)
	v_lshlrev_b32_e32 v118, 16, v66
	v_and_b32_e32 v119, 0xffff0000, v66
	v_lshlrev_b32_e32 v120, 16, v67
	v_and_b32_e32 v121, 0xffff0000, v67
	v_pk_mul_f32 v[118:119], v[126:127], v[118:119]
	v_pk_mul_f32 v[120:121], v[126:127], v[120:121]
	v_rndne_f32_e32 v118, v118
	v_rndne_f32_e32 v119, v119
	v_rndne_f32_e32 v120, v120
	v_rndne_f32_e32 v121, v121
	v_cvt_i32_f32_e32 v118, v118
	v_cvt_i32_f32_e32 v119, v119
	v_cvt_i32_f32_e32 v120, v120
	v_cvt_i32_f32_e32 v121, v121
	v_perm_b32 v118, v119, v118, s16
	v_perm_b32 v120, v121, v120, s17
	v_or_b32_e32 v102, v118, v120
	v_lshlrev_b32_e32 v118, 16, v68
	v_and_b32_e32 v119, 0xffff0000, v68
	v_lshlrev_b32_e32 v120, 16, v69
	v_and_b32_e32 v121, 0xffff0000, v69
	v_pk_mul_f32 v[118:119], v[126:127], v[118:119]
	v_pk_mul_f32 v[120:121], v[126:127], v[120:121]
	v_rndne_f32_e32 v118, v118
	v_rndne_f32_e32 v119, v119
	v_rndne_f32_e32 v120, v120
	v_rndne_f32_e32 v121, v121
	v_cvt_i32_f32_e32 v118, v118
	v_cvt_i32_f32_e32 v119, v119
	v_cvt_i32_f32_e32 v120, v120
	v_cvt_i32_f32_e32 v121, v121
	v_perm_b32 v118, v119, v118, s16
	v_perm_b32 v120, v121, v120, s17
	v_or_b32_e32 v103, v118, v120
	global_store_dwordx2 v136, v[102:103], s[10:11] offset:0
	s_waitcnt vmcnt(43)
	v_lshlrev_b32_e32 v118, 16, v70
	v_and_b32_e32 v119, 0xffff0000, v70
	v_lshlrev_b32_e32 v120, 16, v71
	v_and_b32_e32 v121, 0xffff0000, v71
	v_pk_mul_f32 v[118:119], v[126:127], v[118:119]
	v_pk_mul_f32 v[120:121], v[126:127], v[120:121]
	v_rndne_f32_e32 v118, v118
	v_rndne_f32_e32 v119, v119
	v_rndne_f32_e32 v120, v120
	v_rndne_f32_e32 v121, v121
	v_cvt_i32_f32_e32 v118, v118
	v_cvt_i32_f32_e32 v119, v119
	v_cvt_i32_f32_e32 v120, v120
	v_cvt_i32_f32_e32 v121, v121
	v_perm_b32 v118, v119, v118, s16
	v_perm_b32 v120, v121, v120, s17
	v_or_b32_e32 v104, v118, v120
	v_lshlrev_b32_e32 v118, 16, v72
	v_and_b32_e32 v119, 0xffff0000, v72
	v_lshlrev_b32_e32 v120, 16, v73
	v_and_b32_e32 v121, 0xffff0000, v73
	v_pk_mul_f32 v[118:119], v[126:127], v[118:119]
	v_pk_mul_f32 v[120:121], v[126:127], v[120:121]
	v_rndne_f32_e32 v118, v118
	v_rndne_f32_e32 v119, v119
	v_rndne_f32_e32 v120, v120
	v_rndne_f32_e32 v121, v121
	v_cvt_i32_f32_e32 v118, v118
	v_cvt_i32_f32_e32 v119, v119
	v_cvt_i32_f32_e32 v120, v120
	v_cvt_i32_f32_e32 v121, v121
	v_perm_b32 v118, v119, v118, s16
	v_perm_b32 v120, v121, v120, s17
	v_or_b32_e32 v105, v118, v120
	global_store_dwordx2 v136, v[104:105], s[10:11] offset:512
	s_waitcnt vmcnt(43)
	v_lshlrev_b32_e32 v118, 16, v74
	v_and_b32_e32 v119, 0xffff0000, v74
	v_lshlrev_b32_e32 v120, 16, v75
	v_and_b32_e32 v121, 0xffff0000, v75
	v_pk_mul_f32 v[118:119], v[126:127], v[118:119]
	v_pk_mul_f32 v[120:121], v[126:127], v[120:121]
	v_rndne_f32_e32 v118, v118
	v_rndne_f32_e32 v119, v119
	v_rndne_f32_e32 v120, v120
	v_rndne_f32_e32 v121, v121
	v_cvt_i32_f32_e32 v118, v118
	v_cvt_i32_f32_e32 v119, v119
	v_cvt_i32_f32_e32 v120, v120
	v_cvt_i32_f32_e32 v121, v121
	v_perm_b32 v118, v119, v118, s16
	v_perm_b32 v120, v121, v120, s17
	v_or_b32_e32 v106, v118, v120
	v_lshlrev_b32_e32 v118, 16, v76
	v_and_b32_e32 v119, 0xffff0000, v76
	v_lshlrev_b32_e32 v120, 16, v77
	v_and_b32_e32 v121, 0xffff0000, v77
	v_pk_mul_f32 v[118:119], v[126:127], v[118:119]
	v_pk_mul_f32 v[120:121], v[126:127], v[120:121]
	v_rndne_f32_e32 v118, v118
	v_rndne_f32_e32 v119, v119
	v_rndne_f32_e32 v120, v120
	v_rndne_f32_e32 v121, v121
	v_cvt_i32_f32_e32 v118, v118
	v_cvt_i32_f32_e32 v119, v119
	v_cvt_i32_f32_e32 v120, v120
	v_cvt_i32_f32_e32 v121, v121
	v_perm_b32 v118, v119, v118, s16
	v_perm_b32 v120, v121, v120, s17
	v_or_b32_e32 v107, v118, v120
	global_store_dwordx2 v136, v[106:107], s[10:11] offset:1024
	s_waitcnt vmcnt(43)
; __device__ __forceinline__ unsigned q8(float x) { return (unsigned)(int)__builtin_rintf(x) & 0xffu; }
; __device__ __forceinline__ void rows_bf16_to_i8(Frame& F, const bf16* XBp, const unsigned* rmax, unsigned* X8, float* sx, int pitch4 = D / 4) {
;     ...
;         const float mx = __builtin_bit_cast(float, rb), inv = mx > 0.f ? 127.0f / mx : 0.f;
;         v2u* dst = (v2u*)(X8 + (size_t)m * pitch4) + lane;
; #pragma unroll
;         for (int j = 0; j < 8; ++j) { v2u o;
;             o.x = q8(blo(w[j].x) * inv) | (q8(bhi(w[j].x) * inv) << 8) | (q8(blo(w[j].y) * inv) << 16) | (q8(bhi(w[j].y) * inv) << 24);
;             o.y = q8(blo(w[j].z) * inv) | (q8(bhi(w[j].z) * inv) << 8) | (q8(blo(w[j].w) * inv) << 16) | (q8(bhi(w[j].w) * inv) << 24);
;             dst[64 * j] = o; }
;         if (lane == 0) sx[m] = mx * (1.0f / 127.0f);
; #pragma unroll
;         for (int j = 0; j < 8; ++j) w[j] = wn[j];
;         rb = rbn;
	v_lshlrev_b32_e32 v118, 16, v78
	v_and_b32_e32 v119, 0xffff0000, v78
	v_lshlrev_b32_e32 v120, 16, v79
	v_and_b32_e32 v121, 0xffff0000, v79
	v_pk_mul_f32 v[118:119], v[126:127], v[118:119]
	v_pk_mul_f32 v[120:121], v[126:127], v[120:121]
	v_rndne_f32_e32 v118, v118
	v_rndne_f32_e32 v119, v119
	v_rndne_f32_e32 v120, v120
	v_rndne_f32_e32 v121, v121
	v_cvt_i32_f32_e32 v118, v118
	v_cvt_i32_f32_e32 v119, v119
	v_cvt_i32_f32_e32 v120, v120
	v_cvt_i32_f32_e32 v121, v121
	v_perm_b32 v118, v119, v118, s16
	v_perm_b32 v120, v121, v120, s17
	v_or_b32_e32 v108, v118, v120
	v_lshlrev_b32_e32 v118, 16, v80
	v_and_b32_e32 v119, 0xffff0000, v80
	v_lshlrev_b32_e32 v120, 16, v81
	v_and_b32_e32 v121, 0xffff0000, v81
	v_pk_mul_f32 v[118:119], v[126:127], v[118:119]
	v_pk_mul_f32 v[120:121], v[126:127], v[120:121]
	v_rndne_f32_e32 v118, v118
	v_rndne_f32_e32 v119, v119
	v_rndne_f32_e32 v120, v120
	v_rndne_f32_e32 v121, v121
	v_cvt_i32_f32_e32 v118, v118
	v_cvt_i32_f32_e32 v119, v119
	v_cvt_i32_f32_e32 v120, v120
	v_cvt_i32_f32_e32 v121, v121
	v_perm_b32 v118, v119, v118, s16
	v_perm_b32 v120, v121, v120, s17
	v_or_b32_e32 v109, v118, v120
	global_store_dwordx2 v136, v[108:109], s[10:11] offset:1536
	s_waitcnt vmcnt(43)
	v_lshlrev_b32_e32 v118, 16, v82
	v_and_b32_e32 v119, 0xffff0000, v82
	v_lshlrev_b32_e32 v120, 16, v83
	v_and_b32_e32 v121, 0xffff0000, v83
	v_pk_mul_f32 v[118:119], v[126:127], v[118:119]
	v_pk_mul_f32 v[120:121], v[126:127], v[120:121]
	v_rndne_f32_e32 v118, v118
	v_rndne_f32_e32 v119, v119
	v_rndne_f32_e32 v120, v120
	v_rndne_f32_e32 v121, v121
	v_cvt_i32_f32_e32 v118, v118
	v_cvt_i32_f32_e32 v119, v119
	v_cvt_i32_f32_e32 v120, v120
	v_cvt_i32_f32_e32 v121, v121
	v_perm_b32 v118, v119, v118, s16
	v_perm_b32 v120, v121, v120, s17
	v_or_b32_e32 v110, v118, v120
	v_lshlrev_b32_e32 v118, 16, v84
	v_and_b32_e32 v119, 0xffff0000, v84
	v_lshlrev_b32_e32 v120, 16, v85
	v_and_b32_e32 v121, 0xffff0000, v85
	v_pk_mul_f32 v[118:119], v[126:127], v[118:119]
	v_pk_mul_f32 v[120:121], v[126:127], v[120:121]
	v_rndne_f32_e32 v118, v118
	v_rndne_f32_e32 v119, v119
	v_rndne_f32_e32 v120, v120
	v_rndne_f32_e32 v121, v121
	v_cvt_i32_f32_e32 v118, v118
	v_cvt_i32_f32_e32 v119, v119
	v_cvt_i32_f32_e32 v120, v120
	v_cvt_i32_f32_e32 v121, v121
	v_perm_b32 v118, v119, v118, s16
	v_perm_b32 v120, v121, v120, s17
	v_or_b32_e32 v111, v118, v120
	global_store_dwordx2 v136, v[110:111], s[10:11] offset:2048
	s_waitcnt vmcnt(43)
	v_lshlrev_b32_e32 v118, 16, v86
	v_and_b32_e32 v119, 0xffff0000, v86
	v_lshlrev_b32_e32 v120, 16, v87
	v_and_b32_e32 v121, 0xffff0000, v87
	v_pk_mul_f32 v[118:119], v[126:127], v[118:119]
	v_pk_mul_f32 v[120:121], v[126:127], v[120:121]
	v_rndne_f32_e32 v118, v118
	v_rndne_f32_e32 v119, v119
	v_rndne_f32_e32 v120, v120
	v_rndne_f32_e32 v121, v121
	v_cvt_i32_f32_e32 v118, v118
	v_cvt_i32_f32_e32 v119, v119
	v_cvt_i32_f32_e32 v120, v120
	v_cvt_i32_f32_e32 v121, v121
	v_perm_b32 v118, v119, v118, s16
	v_perm_b32 v120, v121, v120, s17
	v_or_b32_e32 v112, v118, v120
	v_lshlrev_b32_e32 v118, 16, v88
	v_and_b32_e32 v119, 0xffff0000, v88
	v_lshlrev_b32_e32 v120, 16, v89
	v_and_b32_e32 v121, 0xffff0000, v89
	v_pk_mul_f32 v[118:119], v[126:127], v[118:119]
	v_pk_mul_f32 v[120:121], v[126:127], v[120:121]
	v_rndne_f32_e32 v118, v118
	v_rndne_f32_e32 v119, v119
	v_rndne_f32_e32 v120, v120
	v_rndne_f32_e32 v121, v121
	v_cvt_i32_f32_e32 v118, v118
	v_cvt_i32_f32_e32 v119, v119
	v_cvt_i32_f32_e32 v120, v120
	v_cvt_i32_f32_e32 v121, v121
	v_perm_b32 v118, v119, v118, s16
	v_perm_b32 v120, v121, v120, s17
	v_or_b32_e32 v113, v118, v120
	global_store_dwordx2 v136, v[112:113], s[10:11] offset:2560
	s_waitcnt vmcnt(43)
	v_lshlrev_b32_e32 v118, 16, v90
	v_and_b32_e32 v119, 0xffff0000, v90
	v_lshlrev_b32_e32 v120, 16, v91
	v_and_b32_e32 v121, 0xffff0000, v91
	v_pk_mul_f32 v[118:119], v[126:127], v[118:119]
	v_pk_mul_f32 v[120:121], v[126:127], v[120:121]
	v_rndne_f32_e32 v118, v118
	v_rndne_f32_e32 v119, v119
	v_rndne_f32_e32 v120, v120
	v_rndne_f32_e32 v121, v121
	v_cvt_i32_f32_e32 v118, v118
	v_cvt_i32_f32_e32 v119, v119
	v_cvt_i32_f32_e32 v120, v120
	v_cvt_i32_f32_e32 v121, v121
	v_perm_b32 v118, v119, v118, s16
	v_perm_b32 v120, v121, v120, s17
	v_or_b32_e32 v114, v118, v120
	v_lshlrev_b32_e32 v118, 16, v92
	v_and_b32_e32 v119, 0xffff0000, v92
	v_lshlrev_b32_e32 v120, 16, v93
	v_and_b32_e32 v121, 0xffff0000, v93
	v_pk_mul_f32 v[118:119], v[126:127], v[118:119]
	v_pk_mul_f32 v[120:121], v[126:127], v[120:121]
	v_rndne_f32_e32 v118, v118
	v_rndne_f32_e32 v119, v119
	v_rndne_f32_e32 v120, v120
	v_rndne_f32_e32 v121, v121
	v_cvt_i32_f32_e32 v118, v118
	v_cvt_i32_f32_e32 v119, v119
	v_cvt_i32_f32_e32 v120, v120
	v_cvt_i32_f32_e32 v121, v121
	v_perm_b32 v118, v119, v118, s16
	v_perm_b32 v120, v121, v120, s17
	v_or_b32_e32 v115, v118, v120
	global_store_dwordx2 v136, v[114:115], s[10:11] offset:3072
	s_waitcnt vmcnt(43)
	v_lshlrev_b32_e32 v118, 16, v94
	v_and_b32_e32 v119, 0xffff0000, v94
	v_lshlrev_b32_e32 v120, 16, v95
	v_and_b32_e32 v121, 0xffff0000, v95
	v_pk_mul_f32 v[118:119], v[126:127], v[118:119]
	v_pk_mul_f32 v[120:121], v[126:127], v[120:121]
	v_rndne_f32_e32 v118, v118
	v_rndne_f32_e32 v119, v119
	v_rndne_f32_e32 v120, v120
	v_rndne_f32_e32 v121, v121
	v_cvt_i32_f32_e32 v118, v118
	v_cvt_i32_f32_e32 v119, v119
	v_cvt_i32_f32_e32 v120, v120
	v_cvt_i32_f32_e32 v121, v121
	v_perm_b32 v118, v119, v118, s16
	v_perm_b32 v120, v121, v120, s17
	v_or_b32_e32 v116, v118, v120
	v_lshlrev_b32_e32 v118, 16, v96
	v_and_b32_e32 v119, 0xffff0000, v96
	v_lshlrev_b32_e32 v120, 16, v97
	v_and_b32_e32 v121, 0xffff0000, v97
	v_pk_mul_f32 v[118:119], v[126:127], v[118:119]
	v_pk_mul_f32 v[120:121], v[126:127], v[120:121]
	v_rndne_f32_e32 v118, v118
	v_rndne_f32_e32 v119, v119
	v_rndne_f32_e32 v120, v120
	v_rndne_f32_e32 v121, v121
	v_cvt_i32_f32_e32 v118, v118
	v_cvt_i32_f32_e32 v119, v119
	v_cvt_i32_f32_e32 v120, v120
	v_cvt_i32_f32_e32 v121, v121
	v_perm_b32 v118, v119, v118, s16
	v_perm_b32 v120, v121, v120, s17
	v_or_b32_e32 v117, v118, v120
	global_store_dwordx2 v136, v[116:117], s[10:11] offset:3584
	s_mov_b64 exec, s[12:13]
	global_store_dword v137, v138, s[8:9]
	s_mov_b64 exec, -1
	s_add_u32 s10, s10, 0x800000
	s_addc_u32 s11, s11, 0
	s_add_u32 s8, s8, 0x2000
	s_addc_u32 s9, s9, 0
	s_waitcnt vmcnt(35)
; __device__ __forceinline__ unsigned q8(float x) { return (unsigned)(int)__builtin_rintf(x) & 0xffu; }
; __device__ __forceinline__ void rows_bf16_to_i8(Frame& F, const bf16* XBp, const unsigned* rmax, unsigned* X8, float* sx, int pitch4 = D / 4) {
;     ...
;         const float mx = __builtin_bit_cast(float, rb), inv = mx > 0.f ? 127.0f / mx : 0.f;
;         v2u* dst = (v2u*)(X8 + (size_t)m * pitch4) + lane;
; #pragma unroll
;         for (int j = 0; j < 8; ++j) { v2u o;
;             o.x = q8(blo(w[j].x) * inv) | (q8(bhi(w[j].x) * inv) << 8) | (q8(blo(w[j].y) * inv) << 16) | (q8(bhi(w[j].y) * inv) << 24);
;             o.y = q8(blo(w[j].z) * inv) | (q8(bhi(w[j].z) * inv) << 8) | (q8(blo(w[j].w) * inv) << 16) | (q8(bhi(w[j].w) * inv) << 24);
;             dst[64 * j] = o; }
	v_div_scale_f32 v128, s[14:15], v98, v98, s3
	v_rcp_f32_e32 v129, v128
	v_div_scale_f32 v130, vcc, s3, v98, s3
	v_fma_f32 v131, -v128, v129, 1.0
	v_fmac_f32_e32 v129, v131, v129
	v_mul_f32_e32 v131, v130, v129
	v_fma_f32 v132, -v128, v131, v130
	v_fmac_f32_e32 v131, v132, v129
	v_fma_f32 v128, -v128, v131, v130
	v_div_fmas_f32 v128, v128, v129, v131
	v_div_fixup_f32 v128, v128, v98, s3
	v_cmp_lt_f32_e32 vcc, 0, v98
	v_mul_f32_e32 v138, 0x3c010204, v98
	v_cndmask_b32_e32 v126, 0, v128, vcc
	v_mov_b32_e32 v127, v126
	s_waitcnt vmcnt(34)
	v_lshlrev_b32_e32 v118, 16, v2
	v_and_b32_e32 v119, 0xffff0000, v2
	v_lshlrev_b32_e32 v120, 16, v3
	v_and_b32_e32 v121, 0xffff0000, v3
	v_pk_mul_f32 v[118:119], v[126:127], v[118:119]
	v_pk_mul_f32 v[120:121], v[126:127], v[120:121]
	v_rndne_f32_e32 v118, v118
	v_rndne_f32_e32 v119, v119
	v_rndne_f32_e32 v120, v120
	v_rndne_f32_e32 v121, v121
	v_cvt_i32_f32_e32 v118, v118
	v_cvt_i32_f32_e32 v119, v119
	v_cvt_i32_f32_e32 v120, v120
	v_cvt_i32_f32_e32 v121, v121
	v_perm_b32 v118, v119, v118, s16
	v_perm_b32 v120, v121, v120, s17
	v_or_b32_e32 v102, v118, v120
	v_lshlrev_b32_e32 v118, 16, v4
	v_and_b32_e32 v119, 0xffff0000, v4
	v_lshlrev_b32_e32 v120, 16, v5
	v_and_b32_e32 v121, 0xffff0000, v5
	v_pk_mul_f32 v[118:119], v[126:127], v[118:119]
	v_pk_mul_f32 v[120:121], v[126:127], v[120:121]
	v_rndne_f32_e32 v118, v118
	v_rndne_f32_e32 v119, v119
	v_rndne_f32_e32 v120, v120
	v_rndne_f32_e32 v121, v121
	v_cvt_i32_f32_e32 v118, v118
	v_cvt_i32_f32_e32 v119, v119
	v_cvt_i32_f32_e32 v120, v120
	v_cvt_i32_f32_e32 v121, v121
	v_perm_b32 v118, v119, v118, s16
	v_perm_b32 v120, v121, v120, s17
	v_or_b32_e32 v103, v118, v120
	global_store_dwordx2 v136, v[102:103], s[10:11] offset:0
	s_waitcnt vmcnt(34)
	v_lshlrev_b32_e32 v118, 16, v6
	v_and_b32_e32 v119, 0xffff0000, v6
	v_lshlrev_b32_e32 v120, 16, v7
	v_and_b32_e32 v121, 0xffff0000, v7
	v_pk_mul_f32 v[118:119], v[126:127], v[118:119]
	v_pk_mul_f32 v[120:121], v[126:127], v[120:121]
	v_rndne_f32_e32 v118, v118
	v_rndne_f32_e32 v119, v119
	v_rndne_f32_e32 v120, v120
	v_rndne_f32_e32 v121, v121
	v_cvt_i32_f32_e32 v118, v118
	v_cvt_i32_f32_e32 v119, v119
	v_cvt_i32_f32_e32 v120, v120
	v_cvt_i32_f32_e32 v121, v121
	v_perm_b32 v118, v119, v118, s16
	v_perm_b32 v120, v121, v120, s17
	v_or_b32_e32 v104, v118, v120
	v_lshlrev_b32_e32 v118, 16, v8
	v_and_b32_e32 v119, 0xffff0000, v8
	v_lshlrev_b32_e32 v120, 16, v9
	v_and_b32_e32 v121, 0xffff0000, v9
	v_pk_mul_f32 v[118:119], v[126:127], v[118:119]
	v_pk_mul_f32 v[120:121], v[126:127], v[120:121]
	v_rndne_f32_e32 v118, v118
	v_rndne_f32_e32 v119, v119
	v_rndne_f32_e32 v120, v120
	v_rndne_f32_e32 v121, v121
	v_cvt_i32_f32_e32 v118, v118
	v_cvt_i32_f32_e32 v119, v119
	v_cvt_i32_f32_e32 v120, v120
	v_cvt_i32_f32_e32 v121, v121
	v_perm_b32 v118, v119, v118, s16
	v_perm_b32 v120, v121, v120, s17
	v_or_b32_e32 v105, v118, v120
	global_store_dwordx2 v136, v[104:105], s[10:11] offset:512
	s_waitcnt vmcnt(34)
	v_lshlrev_b32_e32 v118, 16, v10
	v_and_b32_e32 v119, 0xffff0000, v10
	v_lshlrev_b32_e32 v120, 16, v11
	v_and_b32_e32 v121, 0xffff0000, v11
	v_pk_mul_f32 v[118:119], v[126:127], v[118:119]
	v_pk_mul_f32 v[120:121], v[126:127], v[120:121]
	v_rndne_f32_e32 v118, v118
	v_rndne_f32_e32 v119, v119
	v_rndne_f32_e32 v120, v120
	v_rndne_f32_e32 v121, v121
	v_cvt_i32_f32_e32 v118, v118
	v_cvt_i32_f32_e32 v119, v119
	v_cvt_i32_f32_e32 v120, v120
	v_cvt_i32_f32_e32 v121, v121
	v_perm_b32 v118, v119, v118, s16
	v_perm_b32 v120, v121, v120, s17
	v_or_b32_e32 v106, v118, v120
	v_lshlrev_b32_e32 v118, 16, v12
	v_and_b32_e32 v119, 0xffff0000, v12
	v_lshlrev_b32_e32 v120, 16, v13
	v_and_b32_e32 v121, 0xffff0000, v13
	v_pk_mul_f32 v[118:119], v[126:127], v[118:119]
	v_pk_mul_f32 v[120:121], v[126:127], v[120:121]
	v_rndne_f32_e32 v118, v118
	v_rndne_f32_e32 v119, v119
	v_rndne_f32_e32 v120, v120
	v_rndne_f32_e32 v121, v121
	v_cvt_i32_f32_e32 v118, v118
	v_cvt_i32_f32_e32 v119, v119
	v_cvt_i32_f32_e32 v120, v120
	v_cvt_i32_f32_e32 v121, v121
	v_perm_b32 v118, v119, v118, s16
	v_perm_b32 v120, v121, v120, s17
	v_or_b32_e32 v107, v118, v120
	global_store_dwordx2 v136, v[106:107], s[10:11] offset:1024
	s_waitcnt vmcnt(34)
	v_lshlrev_b32_e32 v118, 16, v14
	v_and_b32_e32 v119, 0xffff0000, v14
	v_lshlrev_b32_e32 v120, 16, v15
	v_and_b32_e32 v121, 0xffff0000, v15
	v_pk_mul_f32 v[118:119], v[126:127], v[118:119]
	v_pk_mul_f32 v[120:121], v[126:127], v[120:121]
	v_rndne_f32_e32 v118, v118
	v_rndne_f32_e32 v119, v119
	v_rndne_f32_e32 v120, v120
	v_rndne_f32_e32 v121, v121
	v_cvt_i32_f32_e32 v118, v118
	v_cvt_i32_f32_e32 v119, v119
	v_cvt_i32_f32_e32 v120, v120
	v_cvt_i32_f32_e32 v121, v121
	v_perm_b32 v118, v119, v118, s16
	v_perm_b32 v120, v121, v120, s17
	v_or_b32_e32 v108, v118, v120
	v_lshlrev_b32_e32 v118, 16, v16
	v_and_b32_e32 v119, 0xffff0000, v16
	v_lshlrev_b32_e32 v120, 16, v17
	v_and_b32_e32 v121, 0xffff0000, v17
	v_pk_mul_f32 v[118:119], v[126:127], v[118:119]
	v_pk_mul_f32 v[120:121], v[126:127], v[120:121]
	v_rndne_f32_e32 v118, v118
	v_rndne_f32_e32 v119, v119
	v_rndne_f32_e32 v120, v120
	v_rndne_f32_e32 v121, v121
	v_cvt_i32_f32_e32 v118, v118
	v_cvt_i32_f32_e32 v119, v119
	v_cvt_i32_f32_e32 v120, v120
	v_cvt_i32_f32_e32 v121, v121
	v_perm_b32 v118, v119, v118, s16
	v_perm_b32 v120, v121, v120, s17
	v_or_b32_e32 v109, v118, v120
	global_store_dwordx2 v136, v[108:109], s[10:11] offset:1536
	s_waitcnt vmcnt(34)
; __device__ __forceinline__ unsigned q8(float x) { return (unsigned)(int)__builtin_rintf(x) & 0xffu; }
; __device__ __forceinline__ void rows_bf16_to_i8(Frame& F, const bf16* XBp, const unsigned* rmax, unsigned* X8, float* sx, int pitch4 = D / 4) {
;     ...
;         const float mx = __builtin_bit_cast(float, rb), inv = mx > 0.f ? 127.0f / mx : 0.f;
;         v2u* dst = (v2u*)(X8 + (size_t)m * pitch4) + lane;
; #pragma unroll
;         for (int j = 0; j < 8; ++j) { v2u o;
;             o.x = q8(blo(w[j].x) * inv) | (q8(bhi(w[j].x) * inv) << 8) | (q8(blo(w[j].y) * inv) << 16) | (q8(bhi(w[j].y) * inv) << 24);
;             o.y = q8(blo(w[j].z) * inv) | (q8(bhi(w[j].z) * inv) << 8) | (q8(blo(w[j].w) * inv) << 16) | (q8(bhi(w[j].w) * inv) << 24);
;             dst[64 * j] = o; }
;         if (lane == 0) sx[m] = mx * (1.0f / 127.0f);
	v_lshlrev_b32_e32 v118, 16, v18
	v_and_b32_e32 v119, 0xffff0000, v18
	v_lshlrev_b32_e32 v120, 16, v19
	v_and_b32_e32 v121, 0xffff0000, v19
	v_pk_mul_f32 v[118:119], v[126:127], v[118:119]
	v_pk_mul_f32 v[120:121], v[126:127], v[120:121]
	v_rndne_f32_e32 v118, v118
	v_rndne_f32_e32 v119, v119
	v_rndne_f32_e32 v120, v120
	v_rndne_f32_e32 v121, v121
	v_cvt_i32_f32_e32 v118, v118
	v_cvt_i32_f32_e32 v119, v119
	v_cvt_i32_f32_e32 v120, v120
	v_cvt_i32_f32_e32 v121, v121
	v_perm_b32 v118, v119, v118, s16
	v_perm_b32 v120, v121, v120, s17
	v_or_b32_e32 v110, v118, v120
	v_lshlrev_b32_e32 v118, 16, v20
	v_and_b32_e32 v119, 0xffff0000, v20
	v_lshlrev_b32_e32 v120, 16, v21
	v_and_b32_e32 v121, 0xffff0000, v21
	v_pk_mul_f32 v[118:119], v[126:127], v[118:119]
	v_pk_mul_f32 v[120:121], v[126:127], v[120:121]
	v_rndne_f32_e32 v118, v118
	v_rndne_f32_e32 v119, v119
	v_rndne_f32_e32 v120, v120
	v_rndne_f32_e32 v121, v121
	v_cvt_i32_f32_e32 v118, v118
	v_cvt_i32_f32_e32 v119, v119
	v_cvt_i32_f32_e32 v120, v120
	v_cvt_i32_f32_e32 v121, v121
	v_perm_b32 v118, v119, v118, s16
	v_perm_b32 v120, v121, v120, s17
	v_or_b32_e32 v111, v118, v120
	global_store_dwordx2 v136, v[110:111], s[10:11] offset:2048
	s_waitcnt vmcnt(34)
	v_lshlrev_b32_e32 v118, 16, v22
	v_and_b32_e32 v119, 0xffff0000, v22
	v_lshlrev_b32_e32 v120, 16, v23
	v_and_b32_e32 v121, 0xffff0000, v23
	v_pk_mul_f32 v[118:119], v[126:127], v[118:119]
	v_pk_mul_f32 v[120:121], v[126:127], v[120:121]
	v_rndne_f32_e32 v118, v118
	v_rndne_f32_e32 v119, v119
	v_rndne_f32_e32 v120, v120
	v_rndne_f32_e32 v121, v121
	v_cvt_i32_f32_e32 v118, v118
	v_cvt_i32_f32_e32 v119, v119
	v_cvt_i32_f32_e32 v120, v120
	v_cvt_i32_f32_e32 v121, v121
	v_perm_b32 v118, v119, v118, s16
	v_perm_b32 v120, v121, v120, s17
	v_or_b32_e32 v112, v118, v120
	v_lshlrev_b32_e32 v118, 16, v24
	v_and_b32_e32 v119, 0xffff0000, v24
	v_lshlrev_b32_e32 v120, 16, v25
	v_and_b32_e32 v121, 0xffff0000, v25
	v_pk_mul_f32 v[118:119], v[126:127], v[118:119]
	v_pk_mul_f32 v[120:121], v[126:127], v[120:121]
	v_rndne_f32_e32 v118, v118
	v_rndne_f32_e32 v119, v119
	v_rndne_f32_e32 v120, v120
	v_rndne_f32_e32 v121, v121
	v_cvt_i32_f32_e32 v118, v118
	v_cvt_i32_f32_e32 v119, v119
	v_cvt_i32_f32_e32 v120, v120
	v_cvt_i32_f32_e32 v121, v121
	v_perm_b32 v118, v119, v118, s16
	v_perm_b32 v120, v121, v120, s17
	v_or_b32_e32 v113, v118, v120
	global_store_dwordx2 v136, v[112:113], s[10:11] offset:2560
	s_waitcnt vmcnt(34)
	v_lshlrev_b32_e32 v118, 16, v26
	v_and_b32_e32 v119, 0xffff0000, v26
	v_lshlrev_b32_e32 v120, 16, v27
	v_and_b32_e32 v121, 0xffff0000, v27
	v_pk_mul_f32 v[118:119], v[126:127], v[118:119]
	v_pk_mul_f32 v[120:121], v[126:127], v[120:121]
	v_rndne_f32_e32 v118, v118
	v_rndne_f32_e32 v119, v119
	v_rndne_f32_e32 v120, v120
	v_rndne_f32_e32 v121, v121
	v_cvt_i32_f32_e32 v118, v118
	v_cvt_i32_f32_e32 v119, v119
	v_cvt_i32_f32_e32 v120, v120
	v_cvt_i32_f32_e32 v121, v121
	v_perm_b32 v118, v119, v118, s16
	v_perm_b32 v120, v121, v120, s17
	v_or_b32_e32 v114, v118, v120
	v_lshlrev_b32_e32 v118, 16, v28
	v_and_b32_e32 v119, 0xffff0000, v28
	v_lshlrev_b32_e32 v120, 16, v29
	v_and_b32_e32 v121, 0xffff0000, v29
	v_pk_mul_f32 v[118:119], v[126:127], v[118:119]
	v_pk_mul_f32 v[120:121], v[126:127], v[120:121]
	v_rndne_f32_e32 v118, v118
	v_rndne_f32_e32 v119, v119
	v_rndne_f32_e32 v120, v120
	v_rndne_f32_e32 v121, v121
	v_cvt_i32_f32_e32 v118, v118
	v_cvt_i32_f32_e32 v119, v119
	v_cvt_i32_f32_e32 v120, v120
	v_cvt_i32_f32_e32 v121, v121
	v_perm_b32 v118, v119, v118, s16
	v_perm_b32 v120, v121, v120, s17
	v_or_b32_e32 v115, v118, v120
	global_store_dwordx2 v136, v[114:115], s[10:11] offset:3072
	s_waitcnt vmcnt(34)
	v_lshlrev_b32_e32 v118, 16, v30
	v_and_b32_e32 v119, 0xffff0000, v30
	v_lshlrev_b32_e32 v120, 16, v31
	v_and_b32_e32 v121, 0xffff0000, v31
	v_pk_mul_f32 v[118:119], v[126:127], v[118:119]
	v_pk_mul_f32 v[120:121], v[126:127], v[120:121]
	v_rndne_f32_e32 v118, v118
	v_rndne_f32_e32 v119, v119
	v_rndne_f32_e32 v120, v120
	v_rndne_f32_e32 v121, v121
	v_cvt_i32_f32_e32 v118, v118
	v_cvt_i32_f32_e32 v119, v119
	v_cvt_i32_f32_e32 v120, v120
	v_cvt_i32_f32_e32 v121, v121
	v_perm_b32 v118, v119, v118, s16
	v_perm_b32 v120, v121, v120, s17
	v_or_b32_e32 v116, v118, v120
	v_lshlrev_b32_e32 v118, 16, v32
	v_and_b32_e32 v119, 0xffff0000, v32
	v_lshlrev_b32_e32 v120, 16, v33
	v_and_b32_e32 v121, 0xffff0000, v33
	v_pk_mul_f32 v[118:119], v[126:127], v[118:119]
	v_pk_mul_f32 v[120:121], v[126:127], v[120:121]
	v_rndne_f32_e32 v118, v118
	v_rndne_f32_e32 v119, v119
	v_rndne_f32_e32 v120, v120
	v_rndne_f32_e32 v121, v121
	v_cvt_i32_f32_e32 v118, v118
	v_cvt_i32_f32_e32 v119, v119
	v_cvt_i32_f32_e32 v120, v120
	v_cvt_i32_f32_e32 v121, v121
	v_perm_b32 v118, v119, v118, s16
	v_perm_b32 v120, v121, v120, s17
	v_or_b32_e32 v117, v118, v120
	global_store_dwordx2 v136, v[116:117], s[10:11] offset:3584
	s_mov_b64 exec, s[12:13]
	global_store_dword v137, v138, s[8:9]
	s_mov_b64 exec, -1
	s_add_u32 s10, s10, 0x800000
	s_addc_u32 s11, s11, 0
	s_add_u32 s8, s8, 0x2000
	s_addc_u32 s9, s9, 0
	s_waitcnt vmcnt(26)
	v_div_scale_f32 v128, s[14:15], v99, v99, s3
	v_rcp_f32_e32 v129, v128
	v_div_scale_f32 v130, vcc, s3, v99, s3
	v_fma_f32 v131, -v128, v129, 1.0
	v_fmac_f32_e32 v129, v131, v129
	v_mul_f32_e32 v131, v130, v129
	v_fma_f32 v132, -v128, v131, v130
	v_fmac_f32_e32 v131, v132, v129
	v_fma_f32 v128, -v128, v131, v130
	v_div_fmas_f32 v128, v128, v129, v131
	v_div_fixup_f32 v128, v128, v99, s3
	v_cmp_lt_f32_e32 vcc, 0, v99
	v_mul_f32_e32 v138, 0x3c010204, v99
	v_cndmask_b32_e32 v126, 0, v128, vcc
	v_mov_b32_e32 v127, v126
	s_waitcnt vmcnt(25)
; __device__ __forceinline__ unsigned q8(float x) { return (unsigned)(int)__builtin_rintf(x) & 0xffu; }
; __device__ __forceinline__ void rows_bf16_to_i8(Frame& F, const bf16* XBp, const unsigned* rmax, unsigned* X8, float* sx, int pitch4 = D / 4) {
;     ...
; #pragma unroll
;         for (int j = 0; j < 8; ++j) { v2u o;
;             o.x = q8(blo(w[j].x) * inv) | (q8(bhi(w[j].x) * inv) << 8) | (q8(blo(w[j].y) * inv) << 16) | (q8(bhi(w[j].y) * inv) << 24);
;             o.y = q8(blo(w[j].z) * inv) | (q8(bhi(w[j].z) * inv) << 8) | (q8(blo(w[j].w) * inv) << 16) | (q8(bhi(w[j].w) * inv) << 24);
;             dst[64 * j] = o; }
	v_lshlrev_b32_e32 v118, 16, v34
	v_and_b32_e32 v119, 0xffff0000, v34
	v_lshlrev_b32_e32 v120, 16, v35
	v_and_b32_e32 v121, 0xffff0000, v35
	v_pk_mul_f32 v[118:119], v[126:127], v[118:119]
	v_pk_mul_f32 v[120:121], v[126:127], v[120:121]
	v_rndne_f32_e32 v118, v118
	v_rndne_f32_e32 v119, v119
	v_rndne_f32_e32 v120, v120
	v_rndne_f32_e32 v121, v121
	v_cvt_i32_f32_e32 v118, v118
	v_cvt_i32_f32_e32 v119, v119
	v_cvt_i32_f32_e32 v120, v120
	v_cvt_i32_f32_e32 v121, v121
	v_perm_b32 v118, v119, v118, s16
	v_perm_b32 v120, v121, v120, s17
	v_or_b32_e32 v102, v118, v120
	v_lshlrev_b32_e32 v118, 16, v36
	v_and_b32_e32 v119, 0xffff0000, v36
	v_lshlrev_b32_e32 v120, 16, v37
	v_and_b32_e32 v121, 0xffff0000, v37
	v_pk_mul_f32 v[118:119], v[126:127], v[118:119]
	v_pk_mul_f32 v[120:121], v[126:127], v[120:121]
	v_rndne_f32_e32 v118, v118
	v_rndne_f32_e32 v119, v119
	v_rndne_f32_e32 v120, v120
	v_rndne_f32_e32 v121, v121
	v_cvt_i32_f32_e32 v118, v118
	v_cvt_i32_f32_e32 v119, v119
	v_cvt_i32_f32_e32 v120, v120
	v_cvt_i32_f32_e32 v121, v121
	v_perm_b32 v118, v119, v118, s16
	v_perm_b32 v120, v121, v120, s17
	v_or_b32_e32 v103, v118, v120
	global_store_dwordx2 v136, v[102:103], s[10:11] offset:0
	s_waitcnt vmcnt(25)
	v_lshlrev_b32_e32 v118, 16, v38
	v_and_b32_e32 v119, 0xffff0000, v38
	v_lshlrev_b32_e32 v120, 16, v39
	v_and_b32_e32 v121, 0xffff0000, v39
	v_pk_mul_f32 v[118:119], v[126:127], v[118:119]
	v_pk_mul_f32 v[120:121], v[126:127], v[120:121]
	v_rndne_f32_e32 v118, v118
	v_rndne_f32_e32 v119, v119
	v_rndne_f32_e32 v120, v120
	v_rndne_f32_e32 v121, v121
	v_cvt_i32_f32_e32 v118, v118
	v_cvt_i32_f32_e32 v119, v119
	v_cvt_i32_f32_e32 v120, v120
	v_cvt_i32_f32_e32 v121, v121
	v_perm_b32 v118, v119, v118, s16
	v_perm_b32 v120, v121, v120, s17
	v_or_b32_e32 v104, v118, v120
	v_lshlrev_b32_e32 v118, 16, v40
	v_and_b32_e32 v119, 0xffff0000, v40
	v_lshlrev_b32_e32 v120, 16, v41
	v_and_b32_e32 v121, 0xffff0000, v41
	v_pk_mul_f32 v[118:119], v[126:127], v[118:119]
	v_pk_mul_f32 v[120:121], v[126:127], v[120:121]
	v_rndne_f32_e32 v118, v118
	v_rndne_f32_e32 v119, v119
	v_rndne_f32_e32 v120, v120
	v_rndne_f32_e32 v121, v121
	v_cvt_i32_f32_e32 v118, v118
	v_cvt_i32_f32_e32 v119, v119
	v_cvt_i32_f32_e32 v120, v120
	v_cvt_i32_f32_e32 v121, v121
	v_perm_b32 v118, v119, v118, s16
	v_perm_b32 v120, v121, v120, s17
	v_or_b32_e32 v105, v118, v120
	global_store_dwordx2 v136, v[104:105], s[10:11] offset:512
	s_waitcnt vmcnt(25)
	v_lshlrev_b32_e32 v118, 16, v42
	v_and_b32_e32 v119, 0xffff0000, v42
	v_lshlrev_b32_e32 v120, 16, v43
	v_and_b32_e32 v121, 0xffff0000, v43
	v_pk_mul_f32 v[118:119], v[126:127], v[118:119]
	v_pk_mul_f32 v[120:121], v[126:127], v[120:121]
	v_rndne_f32_e32 v118, v118
	v_rndne_f32_e32 v119, v119
	v_rndne_f32_e32 v120, v120
	v_rndne_f32_e32 v121, v121
	v_cvt_i32_f32_e32 v118, v118
	v_cvt_i32_f32_e32 v119, v119
	v_cvt_i32_f32_e32 v120, v120
	v_cvt_i32_f32_e32 v121, v121
	v_perm_b32 v118, v119, v118, s16
	v_perm_b32 v120, v121, v120, s17
	v_or_b32_e32 v106, v118, v120
	v_lshlrev_b32_e32 v118, 16, v44
	v_and_b32_e32 v119, 0xffff0000, v44
	v_lshlrev_b32_e32 v120, 16, v45
	v_and_b32_e32 v121, 0xffff0000, v45
	v_pk_mul_f32 v[118:119], v[126:127], v[118:119]
	v_pk_mul_f32 v[120:121], v[126:127], v[120:121]
	v_rndne_f32_e32 v118, v118
	v_rndne_f32_e32 v119, v119
	v_rndne_f32_e32 v120, v120
	v_rndne_f32_e32 v121, v121
	v_cvt_i32_f32_e32 v118, v118
	v_cvt_i32_f32_e32 v119, v119
	v_cvt_i32_f32_e32 v120, v120
	v_cvt_i32_f32_e32 v121, v121
	v_perm_b32 v118, v119, v118, s16
	v_perm_b32 v120, v121, v120, s17
	v_or_b32_e32 v107, v118, v120
	global_store_dwordx2 v136, v[106:107], s[10:11] offset:1024
	s_waitcnt vmcnt(25)
	v_lshlrev_b32_e32 v118, 16, v46
	v_and_b32_e32 v119, 0xffff0000, v46
	v_lshlrev_b32_e32 v120, 16, v47
	v_and_b32_e32 v121, 0xffff0000, v47
	v_pk_mul_f32 v[118:119], v[126:127], v[118:119]
	v_pk_mul_f32 v[120:121], v[126:127], v[120:121]
	v_rndne_f32_e32 v118, v118
	v_rndne_f32_e32 v119, v119
	v_rndne_f32_e32 v120, v120
	v_rndne_f32_e32 v121, v121
	v_cvt_i32_f32_e32 v118, v118
	v_cvt_i32_f32_e32 v119, v119
	v_cvt_i32_f32_e32 v120, v120
	v_cvt_i32_f32_e32 v121, v121
	v_perm_b32 v118, v119, v118, s16
	v_perm_b32 v120, v121, v120, s17
	v_or_b32_e32 v108, v118, v120
	v_lshlrev_b32_e32 v118, 16, v48
	v_and_b32_e32 v119, 0xffff0000, v48
	v_lshlrev_b32_e32 v120, 16, v49
	v_and_b32_e32 v121, 0xffff0000, v49
	v_pk_mul_f32 v[118:119], v[126:127], v[118:119]
	v_pk_mul_f32 v[120:121], v[126:127], v[120:121]
	v_rndne_f32_e32 v118, v118
	v_rndne_f32_e32 v119, v119
	v_rndne_f32_e32 v120, v120
	v_rndne_f32_e32 v121, v121
	v_cvt_i32_f32_e32 v118, v118
	v_cvt_i32_f32_e32 v119, v119
	v_cvt_i32_f32_e32 v120, v120
	v_cvt_i32_f32_e32 v121, v121
	v_perm_b32 v118, v119, v118, s16
	v_perm_b32 v120, v121, v120, s17
	v_or_b32_e32 v109, v118, v120
	global_store_dwordx2 v136, v[108:109], s[10:11] offset:1536
	s_waitcnt vmcnt(25)
	v_lshlrev_b32_e32 v118, 16, v50
	v_and_b32_e32 v119, 0xffff0000, v50
	v_lshlrev_b32_e32 v120, 16, v51
	v_and_b32_e32 v121, 0xffff0000, v51
	v_pk_mul_f32 v[118:119], v[126:127], v[118:119]
	v_pk_mul_f32 v[120:121], v[126:127], v[120:121]
	v_rndne_f32_e32 v118, v118
	v_rndne_f32_e32 v119, v119
	v_rndne_f32_e32 v120, v120
	v_rndne_f32_e32 v121, v121
	v_cvt_i32_f32_e32 v118, v118
	v_cvt_i32_f32_e32 v119, v119
	v_cvt_i32_f32_e32 v120, v120
	v_cvt_i32_f32_e32 v121, v121
	v_perm_b32 v118, v119, v118, s16
	v_perm_b32 v120, v121, v120, s17
	v_or_b32_e32 v110, v118, v120
	v_lshlrev_b32_e32 v118, 16, v52
	v_and_b32_e32 v119, 0xffff0000, v52
	v_lshlrev_b32_e32 v120, 16, v53
	v_and_b32_e32 v121, 0xffff0000, v53
	v_pk_mul_f32 v[118:119], v[126:127], v[118:119]
	v_pk_mul_f32 v[120:121], v[126:127], v[120:121]
	v_rndne_f32_e32 v118, v118
	v_rndne_f32_e32 v119, v119
	v_rndne_f32_e32 v120, v120
	v_rndne_f32_e32 v121, v121
	v_cvt_i32_f32_e32 v118, v118
	v_cvt_i32_f32_e32 v119, v119
	v_cvt_i32_f32_e32 v120, v120
	v_cvt_i32_f32_e32 v121, v121
	v_perm_b32 v118, v119, v118, s16
	v_perm_b32 v120, v121, v120, s17
	v_or_b32_e32 v111, v118, v120
	global_store_dwordx2 v136, v[110:111], s[10:11] offset:2048
	s_waitcnt vmcnt(25)
; __device__ __forceinline__ unsigned q8(float x) { return (unsigned)(int)__builtin_rintf(x) & 0xffu; }
; __device__ __forceinline__ void rows_bf16_to_i8(Frame& F, const bf16* XBp, const unsigned* rmax, unsigned* X8, float* sx, int pitch4 = D / 4) {
;     ...
;         const float mx = __builtin_bit_cast(float, rb), inv = mx > 0.f ? 127.0f / mx : 0.f;
;         v2u* dst = (v2u*)(X8 + (size_t)m * pitch4) + lane;
; #pragma unroll
;         for (int j = 0; j < 8; ++j) { v2u o;
;             o.x = q8(blo(w[j].x) * inv) | (q8(bhi(w[j].x) * inv) << 8) | (q8(blo(w[j].y) * inv) << 16) | (q8(bhi(w[j].y) * inv) << 24);
;             o.y = q8(blo(w[j].z) * inv) | (q8(bhi(w[j].z) * inv) << 8) | (q8(blo(w[j].w) * inv) << 16) | (q8(bhi(w[j].w) * inv) << 24);
;             dst[64 * j] = o; }
;         if (lane == 0) sx[m] = mx * (1.0f / 127.0f);
; #pragma unroll
;         for (int j = 0; j < 8; ++j) w[j] = wn[j];
;         rb = rbn;
;     }
; }
	v_lshlrev_b32_e32 v118, 16, v54
	v_and_b32_e32 v119, 0xffff0000, v54
	v_lshlrev_b32_e32 v120, 16, v55
	v_and_b32_e32 v121, 0xffff0000, v55
	v_pk_mul_f32 v[118:119], v[126:127], v[118:119]
	v_pk_mul_f32 v[120:121], v[126:127], v[120:121]
	v_rndne_f32_e32 v118, v118
	v_rndne_f32_e32 v119, v119
	v_rndne_f32_e32 v120, v120
	v_rndne_f32_e32 v121, v121
	v_cvt_i32_f32_e32 v118, v118
	v_cvt_i32_f32_e32 v119, v119
	v_cvt_i32_f32_e32 v120, v120
	v_cvt_i32_f32_e32 v121, v121
	v_perm_b32 v118, v119, v118, s16
	v_perm_b32 v120, v121, v120, s17
	v_or_b32_e32 v112, v118, v120
	v_lshlrev_b32_e32 v118, 16, v56
	v_and_b32_e32 v119, 0xffff0000, v56
	v_lshlrev_b32_e32 v120, 16, v57
	v_and_b32_e32 v121, 0xffff0000, v57
	v_pk_mul_f32 v[118:119], v[126:127], v[118:119]
	v_pk_mul_f32 v[120:121], v[126:127], v[120:121]
	v_rndne_f32_e32 v118, v118
	v_rndne_f32_e32 v119, v119
	v_rndne_f32_e32 v120, v120
	v_rndne_f32_e32 v121, v121
	v_cvt_i32_f32_e32 v118, v118
	v_cvt_i32_f32_e32 v119, v119
	v_cvt_i32_f32_e32 v120, v120
	v_cvt_i32_f32_e32 v121, v121
	v_perm_b32 v118, v119, v118, s16
	v_perm_b32 v120, v121, v120, s17
	v_or_b32_e32 v113, v118, v120
	global_store_dwordx2 v136, v[112:113], s[10:11] offset:2560
	s_waitcnt vmcnt(25)
	v_lshlrev_b32_e32 v118, 16, v58
	v_and_b32_e32 v119, 0xffff0000, v58
	v_lshlrev_b32_e32 v120, 16, v59
	v_and_b32_e32 v121, 0xffff0000, v59
	v_pk_mul_f32 v[118:119], v[126:127], v[118:119]
	v_pk_mul_f32 v[120:121], v[126:127], v[120:121]
	v_rndne_f32_e32 v118, v118
	v_rndne_f32_e32 v119, v119
	v_rndne_f32_e32 v120, v120
	v_rndne_f32_e32 v121, v121
	v_cvt_i32_f32_e32 v118, v118
	v_cvt_i32_f32_e32 v119, v119
	v_cvt_i32_f32_e32 v120, v120
	v_cvt_i32_f32_e32 v121, v121
	v_perm_b32 v118, v119, v118, s16
	v_perm_b32 v120, v121, v120, s17
	v_or_b32_e32 v114, v118, v120
	v_lshlrev_b32_e32 v118, 16, v60
	v_and_b32_e32 v119, 0xffff0000, v60
	v_lshlrev_b32_e32 v120, 16, v61
	v_and_b32_e32 v121, 0xffff0000, v61
	v_pk_mul_f32 v[118:119], v[126:127], v[118:119]
	v_pk_mul_f32 v[120:121], v[126:127], v[120:121]
	v_rndne_f32_e32 v118, v118
	v_rndne_f32_e32 v119, v119
	v_rndne_f32_e32 v120, v120
	v_rndne_f32_e32 v121, v121
	v_cvt_i32_f32_e32 v118, v118
	v_cvt_i32_f32_e32 v119, v119
	v_cvt_i32_f32_e32 v120, v120
	v_cvt_i32_f32_e32 v121, v121
	v_perm_b32 v118, v119, v118, s16
	v_perm_b32 v120, v121, v120, s17
	v_or_b32_e32 v115, v118, v120
	global_store_dwordx2 v136, v[114:115], s[10:11] offset:3072
	s_waitcnt vmcnt(25)
	v_lshlrev_b32_e32 v118, 16, v62
	v_and_b32_e32 v119, 0xffff0000, v62
	v_lshlrev_b32_e32 v120, 16, v63
	v_and_b32_e32 v121, 0xffff0000, v63
	v_pk_mul_f32 v[118:119], v[126:127], v[118:119]
	v_pk_mul_f32 v[120:121], v[126:127], v[120:121]
	v_rndne_f32_e32 v118, v118
	v_rndne_f32_e32 v119, v119
	v_rndne_f32_e32 v120, v120
	v_rndne_f32_e32 v121, v121
	v_cvt_i32_f32_e32 v118, v118
	v_cvt_i32_f32_e32 v119, v119
	v_cvt_i32_f32_e32 v120, v120
	v_cvt_i32_f32_e32 v121, v121
	v_perm_b32 v118, v119, v118, s16
	v_perm_b32 v120, v121, v120, s17
	v_or_b32_e32 v116, v118, v120
	v_lshlrev_b32_e32 v118, 16, v64
	v_and_b32_e32 v119, 0xffff0000, v64
	v_lshlrev_b32_e32 v120, 16, v65
	v_and_b32_e32 v121, 0xffff0000, v65
	v_pk_mul_f32 v[118:119], v[126:127], v[118:119]
	v_pk_mul_f32 v[120:121], v[126:127], v[120:121]
	v_rndne_f32_e32 v118, v118
	v_rndne_f32_e32 v119, v119
	v_rndne_f32_e32 v120, v120
	v_rndne_f32_e32 v121, v121
	v_cvt_i32_f32_e32 v118, v118
	v_cvt_i32_f32_e32 v119, v119
	v_cvt_i32_f32_e32 v120, v120
	v_cvt_i32_f32_e32 v121, v121
	v_perm_b32 v118, v119, v118, s16
	v_perm_b32 v120, v121, v120, s17
	v_or_b32_e32 v117, v118, v120
	global_store_dwordx2 v136, v[116:117], s[10:11] offset:3584
	s_mov_b64 exec, s[12:13]
	global_store_dword v137, v138, s[8:9]
	s_mov_b64 exec, -1
	s_add_u32 s10, s10, 0x800000
	s_addc_u32 s11, s11, 0
	s_add_u32 s8, s8, 0x2000
	s_addc_u32 s9, s9, 0
	s_branch .LBB0_1650
.Lrows3_fb_gout:
	v_readlane_b32 s0, v254, 5
	s_lshl_b32 s0, s0, 3
	v_readlane_b32 s1, v254, 39
	s_add_i32 s0, s0, s1
	s_cmpk_gt_i32 s0, 0x3fff
	s_cbranch_scc1 .LBB0_1650
	v_readlane_b32 s2, v254, 6
	s_ashr_i32 s1, s0, 31
	s_lshl_b32 s2, s2, 3
	s_lshl_b64 s[4:5], s[0:1], 13
	s_add_u32 s4, s96, s4
	v_readlane_b32 s3, v254, 7
	s_addc_u32 s5, s97, s5
	v_lshlrev_b32_e32 v66, 4, v232
	v_mov_b32_e32 v67, 0
	s_waitcnt vmcnt(0) lgkmcnt(0)
	v_lshl_add_u64 v[2:3], s[4:5], 0, v[66:67]
	s_mov_b64 s[4:5], 0x1e400000
	s_lshl_b64 s[6:7], s[0:1], 2
	s_mov_b32 s3, 0x1e401000
	v_lshl_add_u64 v[4:5], v[2:3], 0, s[4:5]
	s_add_u32 s4, s96, s6
	v_add_co_u32_e32 v2, vcc, s3, v2
	s_addc_u32 s5, s97, s7
	v_mov_b32_e32 v6, 0xc0000
	v_addc_co_u32_e32 v3, vcc, 0, v3, vcc
	global_load_dwordx4 v[58:61], v[4:5], off offset:1024
	global_load_dwordx4 v[54:57], v[4:5], off offset:2048
	global_load_dword v1, v6, s[4:5]
	global_load_dwordx4 v[50:53], v[4:5], off offset:3072
	global_load_dwordx4 v[62:65], v[2:3], off offset:-4096
	global_load_dwordx4 v[46:49], v[2:3], off
	global_load_dwordx4 v[42:45], v[2:3], off offset:1024
	global_load_dwordx4 v[38:41], v[2:3], off offset:2048
	global_load_dwordx4 v[34:37], v[2:3], off offset:3072
	s_add_u32 s16, s6, 0x4d4b0000
	s_addc_u32 s17, s7, 0
	s_add_i32 s10, s0, s2
	s_ashr_i32 s3, s2, 31
	s_lshl_b64 s[8:9], s[0:1], 12
	s_ashr_i32 s11, s10, 31
	s_lshl_b64 s[6:7], s[2:3], 2
	v_lshl_or_b32 v68, v232, 3, s8
	v_mov_b32_e32 v69, s9
	s_lshl_b64 s[8:9], s[2:3], 12
	s_lshl_b64 s[12:13], s[10:11], 2
	s_add_u32 s1, s12, 0xc0000
	s_addc_u32 s18, s13, 0
	s_lshl_b64 s[10:11], s[10:11], 13
	v_cmp_eq_u32_e64 s[4:5], 0, v232
	v_or_b32_e32 v70, s10, v66
	v_mov_b32_e32 v71, s11
	s_lshl_b64 s[10:11], s[2:3], 13
	s_mov_b32 s3, 0x42fe0000
	s_mov_b32 s19, 0xc0c0500
	s_mov_b32 s20, 0x40c0c00
	s_mov_b32 s21, 0x15400000
	v_mov_b32_e32 v66, 0
	s_branch .LBB0_1646

; __device__ __forceinline__ unsigned q8(float x) { return (unsigned)(int)__builtin_rintf(x) & 0xffu; }
; __device__ __forceinline__ void rows_bf16_to_i8(Frame& F, const bf16* XBp, const unsigned* rmax, unsigned* X8, float* sx, int pitch4 = D / 4) {
;     const int gw = F.vcu * NWAVES + F.wave, NGW = F.G * NWAVES, lane = F.lane;
;     v4u w[8], wn[8]; unsigned rb = 0, rbn = 0;
;     int m = gw;
;     if (m < M) { const v4u* src = (const v4u*)(XBp + (size_t)m * D) + lane; rb = rmax[m];
; #pragma unroll
;         for (int j = 0; j < 8; ++j) w[j] = src[64 * j]; }
;     for (; m < M; m += NGW) {
;         const int mn = m + NGW;
;         if (mn < M) { const v4u* src = (const v4u*)(XBp + (size_t)mn * D) + lane; rbn = rmax[mn];
; #pragma unroll
;             for (int j = 0; j < 8; ++j) wn[j] = src[64 * j]; }
;         const float mx = __builtin_bit_cast(float, rb), inv = mx > 0.f ? 127.0f / mx : 0.f;
;         v2u* dst = (v2u*)(X8 + (size_t)m * pitch4) + lane;
; #pragma unroll
;         for (int j = 0; j < 8; ++j) { v2u o;
;             o.x = q8(blo(w[j].x) * inv) | (q8(bhi(w[j].x) * inv) << 8) | (q8(blo(w[j].y) * inv) << 16) | (q8(bhi(w[j].y) * inv) << 24);
;             o.y = q8(blo(w[j].z) * inv) | (q8(bhi(w[j].z) * inv) << 8) | (q8(blo(w[j].w) * inv) << 16) | (q8(bhi(w[j].w) * inv) << 24);
;             dst[64 * j] = o; }
; __global__ void __launch_bounds__(NWAVES * 64, 2) mk_fwd(Args args) {
;     ...
;     if (IN(G_PP)) {
;         rows_bf16_to_i8(F, XB, (const unsigned*)(ws + CTL_RMAX4), (unsigned*)(ws + WS_X8D), (float*)(ws + WS_SX4));
.LBB0_2220:
	s_cmp_lt_i32 s72, 14
	s_cselect_b64 s[0:1], -1, 0
	s_cmp_gt_i32 s73, 13
	s_cselect_b64 s[2:3], -1, 0
	s_and_b64 s[0:1], s[0:1], s[2:3]
	s_andn2_b64 vcc, exec, s[0:1]
	s_cbranch_vccnz .LBB0_2304
	v_readlane_b32 s0, v254, 6
	s_cmp_lg_u32 s0, 0x100
	s_cbranch_scc1 .Lrows3_fb_gpp
	v_readlane_b32 s0, v254, 5
	v_readlane_b32 s1, v254, 39
	s_lshl_b32 s0, s0, 3
	s_add_i32 s0, s0, s1
	s_waitcnt vmcnt(0) lgkmcnt(0)
	v_readlane_b32 s4, v254, 40
	v_readlane_b32 s5, v254, 41
	s_lshl_b32 s2, s0, 13
	s_add_u32 s4, s4, s2
	s_addc_u32 s5, s5, 0
	s_lshl_b32 s2, s0, 2
	s_add_u32 s6, s96, s2
	s_addc_u32 s7, s97, 0
	s_add_u32 s8, s6, 0x4d4c0000
	s_addc_u32 s9, s7, 0
	s_add_u32 s6, s6, 0xd0000
	s_addc_u32 s7, s7, 0
	s_lshl_b32 s2, s0, 12
	s_add_u32 s10, s96, s2
	s_addc_u32 s11, s97, 0
	s_add_u32 s10, s10, 0x8200000
	s_addc_u32 s11, s11, 0
	v_and_b32_e32 v133, 63, v0
	v_lshlrev_b32_e32 v134, 4, v133
	v_add_u32_e32 v135, 0x1000, v134
	v_lshlrev_b32_e32 v136, 3, v133
	v_mov_b32_e32 v137, 0
	v_cmp_eq_u32_e64 s[12:13], 0, v133
	s_mov_b32 s3, 0x42fe0000
	s_mov_b32 s16, 0xc0c0400
	s_mov_b32 s17, 0x4000c0c
	global_load_dword v98, v137, s[6:7]
	global_load_dwordx4 v[2:5], v134, s[4:5] offset:0
	global_load_dwordx4 v[6:9], v134, s[4:5] offset:1024
	global_load_dwordx4 v[10:13], v134, s[4:5] offset:2048
	global_load_dwordx4 v[14:17], v134, s[4:5] offset:3072
	global_load_dwordx4 v[18:21], v135, s[4:5] offset:0
	global_load_dwordx4 v[22:25], v135, s[4:5] offset:1024
	global_load_dwordx4 v[26:29], v135, s[4:5] offset:2048
	global_load_dwordx4 v[30:33], v135, s[4:5] offset:3072
	s_add_u32 s4, s4, 0x1000000
	s_addc_u32 s5, s5, 0
	s_add_u32 s6, s6, 0x2000
	s_addc_u32 s7, s7, 0
	global_load_dword v99, v137, s[6:7]
	global_load_dwordx4 v[34:37], v134, s[4:5] offset:0
	global_load_dwordx4 v[38:41], v134, s[4:5] offset:1024
	global_load_dwordx4 v[42:45], v134, s[4:5] offset:2048
	global_load_dwordx4 v[46:49], v134, s[4:5] offset:3072
	global_load_dwordx4 v[50:53], v135, s[4:5] offset:0
	global_load_dwordx4 v[54:57], v135, s[4:5] offset:1024
	global_load_dwordx4 v[58:61], v135, s[4:5] offset:2048
	global_load_dwordx4 v[62:65], v135, s[4:5] offset:3072
	s_add_u32 s4, s4, 0x1000000
	s_addc_u32 s5, s5, 0
	s_add_u32 s6, s6, 0x2000
	s_addc_u32 s7, s7, 0
	global_load_dword v100, v137, s[6:7]
	global_load_dwordx4 v[66:69], v134, s[4:5] offset:0
	global_load_dwordx4 v[70:73], v134, s[4:5] offset:1024
	global_load_dwordx4 v[74:77], v134, s[4:5] offset:2048
	global_load_dwordx4 v[78:81], v134, s[4:5] offset:3072
	global_load_dwordx4 v[82:85], v135, s[4:5] offset:0
	global_load_dwordx4 v[86:89], v135, s[4:5] offset:1024
	global_load_dwordx4 v[90:93], v135, s[4:5] offset:2048
	global_load_dwordx4 v[94:97], v135, s[4:5] offset:3072
	s_add_u32 s4, s4, 0x1000000
	s_addc_u32 s5, s5, 0
	s_add_u32 s6, s6, 0x2000
	s_addc_u32 s7, s7, 0
	s_waitcnt vmcnt(26)
	v_div_scale_f32 v128, s[14:15], v98, v98, s3
	v_rcp_f32_e32 v129, v128
	v_div_scale_f32 v130, vcc, s3, v98, s3
	v_fma_f32 v131, -v128, v129, 1.0
	v_fmac_f32_e32 v129, v131, v129
	v_mul_f32_e32 v131, v130, v129
	v_fma_f32 v132, -v128, v131, v130
	v_fmac_f32_e32 v131, v132, v129
	v_fma_f32 v128, -v128, v131, v130
	v_div_fmas_f32 v128, v128, v129, v131
	v_div_fixup_f32 v128, v128, v98, s3
	v_cmp_lt_f32_e32 vcc, 0, v98
	v_mul_f32_e32 v138, 0x3c010204, v98
	v_cndmask_b32_e32 v126, 0, v128, vcc
	v_mov_b32_e32 v127, v126
	s_waitcnt vmcnt(25)
	v_lshlrev_b32_e32 v118, 16, v2
	v_and_b32_e32 v119, 0xffff0000, v2
	v_lshlrev_b32_e32 v120, 16, v3
	v_and_b32_e32 v121, 0xffff0000, v3
	v_pk_mul_f32 v[118:119], v[126:127], v[118:119]
	v_pk_mul_f32 v[120:121], v[126:127], v[120:121]
	v_rndne_f32_e32 v118, v118
	v_rndne_f32_e32 v119, v119
	v_rndne_f32_e32 v120, v120
	v_rndne_f32_e32 v121, v121
	v_cvt_i32_f32_e32 v118, v118
	v_cvt_i32_f32_e32 v119, v119
	v_cvt_i32_f32_e32 v120, v120
	v_cvt_i32_f32_e32 v121, v121
	v_perm_b32 v118, v119, v118, s16
	v_perm_b32 v120, v121, v120, s17
	v_or_b32_e32 v102, v118, v120
	v_lshlrev_b32_e32 v118, 16, v4
	v_and_b32_e32 v119, 0xffff0000, v4
	v_lshlrev_b32_e32 v120, 16, v5
	v_and_b32_e32 v121, 0xffff0000, v5
	v_pk_mul_f32 v[118:119], v[126:127], v[118:119]
	v_pk_mul_f32 v[120:121], v[126:127], v[120:121]
	v_rndne_f32_e32 v118, v118
	v_rndne_f32_e32 v119, v119
	v_rndne_f32_e32 v120, v120
	v_rndne_f32_e32 v121, v121
	v_cvt_i32_f32_e32 v118, v118
	v_cvt_i32_f32_e32 v119, v119
	v_cvt_i32_f32_e32 v120, v120
	v_cvt_i32_f32_e32 v121, v121
	v_perm_b32 v118, v119, v118, s16
	v_perm_b32 v120, v121, v120, s17
	v_or_b32_e32 v103, v118, v120
	global_store_dwordx2 v136, v[102:103], s[10:11] offset:0
	s_waitcnt vmcnt(25)
	v_lshlrev_b32_e32 v118, 16, v6
	v_and_b32_e32 v119, 0xffff0000, v6
	v_lshlrev_b32_e32 v120, 16, v7
	v_and_b32_e32 v121, 0xffff0000, v7
	v_pk_mul_f32 v[118:119], v[126:127], v[118:119]
	v_pk_mul_f32 v[120:121], v[126:127], v[120:121]
	v_rndne_f32_e32 v118, v118
	v_rndne_f32_e32 v119, v119
	v_rndne_f32_e32 v120, v120
	v_rndne_f32_e32 v121, v121
	v_cvt_i32_f32_e32 v118, v118
	v_cvt_i32_f32_e32 v119, v119
	v_cvt_i32_f32_e32 v120, v120
	v_cvt_i32_f32_e32 v121, v121
	v_perm_b32 v118, v119, v118, s16
	v_perm_b32 v120, v121, v120, s17
	v_or_b32_e32 v104, v118, v120
	v_lshlrev_b32_e32 v118, 16, v8
	v_and_b32_e32 v119, 0xffff0000, v8
	v_lshlrev_b32_e32 v120, 16, v9
	v_and_b32_e32 v121, 0xffff0000, v9
	v_pk_mul_f32 v[118:119], v[126:127], v[118:119]
	v_pk_mul_f32 v[120:121], v[126:127], v[120:121]
	v_rndne_f32_e32 v118, v118
	v_rndne_f32_e32 v119, v119
	v_rndne_f32_e32 v120, v120
	v_rndne_f32_e32 v121, v121
	v_cvt_i32_f32_e32 v118, v118
	v_cvt_i32_f32_e32 v119, v119
	v_cvt_i32_f32_e32 v120, v120
	v_cvt_i32_f32_e32 v121, v121
	v_perm_b32 v118, v119, v118, s16
	v_perm_b32 v120, v121, v120, s17
	v_or_b32_e32 v105, v118, v120
	global_store_dwordx2 v136, v[104:105], s[10:11] offset:512
	s_waitcnt vmcnt(25)
; __device__ __forceinline__ unsigned q8(float x) { return (unsigned)(int)__builtin_rintf(x) & 0xffu; }
; __device__ __forceinline__ void rows_bf16_to_i8(Frame& F, const bf16* XBp, const unsigned* rmax, unsigned* X8, float* sx, int pitch4 = D / 4) {
;     ...
; #pragma unroll
;         for (int j = 0; j < 8; ++j) { v2u o;
;             o.x = q8(blo(w[j].x) * inv) | (q8(bhi(w[j].x) * inv) << 8) | (q8(blo(w[j].y) * inv) << 16) | (q8(bhi(w[j].y) * inv) << 24);
;             o.y = q8(blo(w[j].z) * inv) | (q8(bhi(w[j].z) * inv) << 8) | (q8(blo(w[j].w) * inv) << 16) | (q8(bhi(w[j].w) * inv) << 24);
;             dst[64 * j] = o; }
	v_lshlrev_b32_e32 v118, 16, v10
	v_and_b32_e32 v119, 0xffff0000, v10
	v_lshlrev_b32_e32 v120, 16, v11
	v_and_b32_e32 v121, 0xffff0000, v11
	v_pk_mul_f32 v[118:119], v[126:127], v[118:119]
	v_pk_mul_f32 v[120:121], v[126:127], v[120:121]
	v_rndne_f32_e32 v118, v118
	v_rndne_f32_e32 v119, v119
	v_rndne_f32_e32 v120, v120
	v_rndne_f32_e32 v121, v121
	v_cvt_i32_f32_e32 v118, v118
	v_cvt_i32_f32_e32 v119, v119
	v_cvt_i32_f32_e32 v120, v120
	v_cvt_i32_f32_e32 v121, v121
	v_perm_b32 v118, v119, v118, s16
	v_perm_b32 v120, v121, v120, s17
	v_or_b32_e32 v106, v118, v120
	v_lshlrev_b32_e32 v118, 16, v12
	v_and_b32_e32 v119, 0xffff0000, v12
	v_lshlrev_b32_e32 v120, 16, v13
	v_and_b32_e32 v121, 0xffff0000, v13
	v_pk_mul_f32 v[118:119], v[126:127], v[118:119]
	v_pk_mul_f32 v[120:121], v[126:127], v[120:121]
	v_rndne_f32_e32 v118, v118
	v_rndne_f32_e32 v119, v119
	v_rndne_f32_e32 v120, v120
	v_rndne_f32_e32 v121, v121
	v_cvt_i32_f32_e32 v118, v118
	v_cvt_i32_f32_e32 v119, v119
	v_cvt_i32_f32_e32 v120, v120
	v_cvt_i32_f32_e32 v121, v121
	v_perm_b32 v118, v119, v118, s16
	v_perm_b32 v120, v121, v120, s17
	v_or_b32_e32 v107, v118, v120
	global_store_dwordx2 v136, v[106:107], s[10:11] offset:1024
	s_waitcnt vmcnt(25)
	v_lshlrev_b32_e32 v118, 16, v14
	v_and_b32_e32 v119, 0xffff0000, v14
	v_lshlrev_b32_e32 v120, 16, v15
	v_and_b32_e32 v121, 0xffff0000, v15
	v_pk_mul_f32 v[118:119], v[126:127], v[118:119]
	v_pk_mul_f32 v[120:121], v[126:127], v[120:121]
	v_rndne_f32_e32 v118, v118
	v_rndne_f32_e32 v119, v119
	v_rndne_f32_e32 v120, v120
	v_rndne_f32_e32 v121, v121
	v_cvt_i32_f32_e32 v118, v118
	v_cvt_i32_f32_e32 v119, v119
	v_cvt_i32_f32_e32 v120, v120
	v_cvt_i32_f32_e32 v121, v121
	v_perm_b32 v118, v119, v118, s16
	v_perm_b32 v120, v121, v120, s17
	v_or_b32_e32 v108, v118, v120
	v_lshlrev_b32_e32 v118, 16, v16
	v_and_b32_e32 v119, 0xffff0000, v16
	v_lshlrev_b32_e32 v120, 16, v17
	v_and_b32_e32 v121, 0xffff0000, v17
	v_pk_mul_f32 v[118:119], v[126:127], v[118:119]
	v_pk_mul_f32 v[120:121], v[126:127], v[120:121]
	v_rndne_f32_e32 v118, v118
	v_rndne_f32_e32 v119, v119
	v_rndne_f32_e32 v120, v120
	v_rndne_f32_e32 v121, v121
	v_cvt_i32_f32_e32 v118, v118
	v_cvt_i32_f32_e32 v119, v119
	v_cvt_i32_f32_e32 v120, v120
	v_cvt_i32_f32_e32 v121, v121
	v_perm_b32 v118, v119, v118, s16
	v_perm_b32 v120, v121, v120, s17
	v_or_b32_e32 v109, v118, v120
	global_store_dwordx2 v136, v[108:109], s[10:11] offset:1536
	s_waitcnt vmcnt(25)
	v_lshlrev_b32_e32 v118, 16, v18
	v_and_b32_e32 v119, 0xffff0000, v18
	v_lshlrev_b32_e32 v120, 16, v19
	v_and_b32_e32 v121, 0xffff0000, v19
	v_pk_mul_f32 v[118:119], v[126:127], v[118:119]
	v_pk_mul_f32 v[120:121], v[126:127], v[120:121]
	v_rndne_f32_e32 v118, v118
	v_rndne_f32_e32 v119, v119
	v_rndne_f32_e32 v120, v120
	v_rndne_f32_e32 v121, v121
	v_cvt_i32_f32_e32 v118, v118
	v_cvt_i32_f32_e32 v119, v119
	v_cvt_i32_f32_e32 v120, v120
	v_cvt_i32_f32_e32 v121, v121
	v_perm_b32 v118, v119, v118, s16
	v_perm_b32 v120, v121, v120, s17
	v_or_b32_e32 v110, v118, v120
	v_lshlrev_b32_e32 v118, 16, v20
	v_and_b32_e32 v119, 0xffff0000, v20
	v_lshlrev_b32_e32 v120, 16, v21
	v_and_b32_e32 v121, 0xffff0000, v21
	v_pk_mul_f32 v[118:119], v[126:127], v[118:119]
	v_pk_mul_f32 v[120:121], v[126:127], v[120:121]
	v_rndne_f32_e32 v118, v118
	v_rndne_f32_e32 v119, v119
	v_rndne_f32_e32 v120, v120
	v_rndne_f32_e32 v121, v121
	v_cvt_i32_f32_e32 v118, v118
	v_cvt_i32_f32_e32 v119, v119
	v_cvt_i32_f32_e32 v120, v120
	v_cvt_i32_f32_e32 v121, v121
	v_perm_b32 v118, v119, v118, s16
	v_perm_b32 v120, v121, v120, s17
	v_or_b32_e32 v111, v118, v120
	global_store_dwordx2 v136, v[110:111], s[10:11] offset:2048
	s_waitcnt vmcnt(25)
	v_lshlrev_b32_e32 v118, 16, v22
	v_and_b32_e32 v119, 0xffff0000, v22
	v_lshlrev_b32_e32 v120, 16, v23
	v_and_b32_e32 v121, 0xffff0000, v23
	v_pk_mul_f32 v[118:119], v[126:127], v[118:119]
	v_pk_mul_f32 v[120:121], v[126:127], v[120:121]
	v_rndne_f32_e32 v118, v118
	v_rndne_f32_e32 v119, v119
	v_rndne_f32_e32 v120, v120
	v_rndne_f32_e32 v121, v121
	v_cvt_i32_f32_e32 v118, v118
	v_cvt_i32_f32_e32 v119, v119
	v_cvt_i32_f32_e32 v120, v120
	v_cvt_i32_f32_e32 v121, v121
	v_perm_b32 v118, v119, v118, s16
	v_perm_b32 v120, v121, v120, s17
	v_or_b32_e32 v112, v118, v120
	v_lshlrev_b32_e32 v118, 16, v24
	v_and_b32_e32 v119, 0xffff0000, v24
	v_lshlrev_b32_e32 v120, 16, v25
	v_and_b32_e32 v121, 0xffff0000, v25
	v_pk_mul_f32 v[118:119], v[126:127], v[118:119]
	v_pk_mul_f32 v[120:121], v[126:127], v[120:121]
	v_rndne_f32_e32 v118, v118
	v_rndne_f32_e32 v119, v119
	v_rndne_f32_e32 v120, v120
	v_rndne_f32_e32 v121, v121
	v_cvt_i32_f32_e32 v118, v118
	v_cvt_i32_f32_e32 v119, v119
	v_cvt_i32_f32_e32 v120, v120
	v_cvt_i32_f32_e32 v121, v121
	v_perm_b32 v118, v119, v118, s16
	v_perm_b32 v120, v121, v120, s17
	v_or_b32_e32 v113, v118, v120
	global_store_dwordx2 v136, v[112:113], s[10:11] offset:2560
	s_waitcnt vmcnt(25)
	v_lshlrev_b32_e32 v118, 16, v26
	v_and_b32_e32 v119, 0xffff0000, v26
	v_lshlrev_b32_e32 v120, 16, v27
	v_and_b32_e32 v121, 0xffff0000, v27
	v_pk_mul_f32 v[118:119], v[126:127], v[118:119]
	v_pk_mul_f32 v[120:121], v[126:127], v[120:121]
	v_rndne_f32_e32 v118, v118
	v_rndne_f32_e32 v119, v119
	v_rndne_f32_e32 v120, v120
	v_rndne_f32_e32 v121, v121
	v_cvt_i32_f32_e32 v118, v118
	v_cvt_i32_f32_e32 v119, v119
	v_cvt_i32_f32_e32 v120, v120
	v_cvt_i32_f32_e32 v121, v121
	v_perm_b32 v118, v119, v118, s16
	v_perm_b32 v120, v121, v120, s17
	v_or_b32_e32 v114, v118, v120
	v_lshlrev_b32_e32 v118, 16, v28
	v_and_b32_e32 v119, 0xffff0000, v28
	v_lshlrev_b32_e32 v120, 16, v29
	v_and_b32_e32 v121, 0xffff0000, v29
	v_pk_mul_f32 v[118:119], v[126:127], v[118:119]
	v_pk_mul_f32 v[120:121], v[126:127], v[120:121]
	v_rndne_f32_e32 v118, v118
	v_rndne_f32_e32 v119, v119
	v_rndne_f32_e32 v120, v120
	v_rndne_f32_e32 v121, v121
	v_cvt_i32_f32_e32 v118, v118
	v_cvt_i32_f32_e32 v119, v119
	v_cvt_i32_f32_e32 v120, v120
	v_cvt_i32_f32_e32 v121, v121
	v_perm_b32 v118, v119, v118, s16
	v_perm_b32 v120, v121, v120, s17
	v_or_b32_e32 v115, v118, v120
	global_store_dwordx2 v136, v[114:115], s[10:11] offset:3072
	s_waitcnt vmcnt(25)
; __device__ __forceinline__ unsigned q8(float x) { return (unsigned)(int)__builtin_rintf(x) & 0xffu; }
; __device__ __forceinline__ void rows_bf16_to_i8(Frame& F, const bf16* XBp, const unsigned* rmax, unsigned* X8, float* sx, int pitch4 = D / 4) {
;     ...
;         const float mx = __builtin_bit_cast(float, rb), inv = mx > 0.f ? 127.0f / mx : 0.f;
;         v2u* dst = (v2u*)(X8 + (size_t)m * pitch4) + lane;
; #pragma unroll
;         for (int j = 0; j < 8; ++j) { v2u o;
;             o.x = q8(blo(w[j].x) * inv) | (q8(bhi(w[j].x) * inv) << 8) | (q8(blo(w[j].y) * inv) << 16) | (q8(bhi(w[j].y) * inv) << 24);
;             o.y = q8(blo(w[j].z) * inv) | (q8(bhi(w[j].z) * inv) << 8) | (q8(blo(w[j].w) * inv) << 16) | (q8(bhi(w[j].w) * inv) << 24);
;             dst[64 * j] = o; }
;         if (lane == 0) sx[m] = mx * (1.0f / 127.0f);
; #pragma unroll
;         for (int j = 0; j < 8; ++j) w[j] = wn[j];
;         rb = rbn;
	v_lshlrev_b32_e32 v118, 16, v30
	v_and_b32_e32 v119, 0xffff0000, v30
	v_lshlrev_b32_e32 v120, 16, v31
	v_and_b32_e32 v121, 0xffff0000, v31
	v_pk_mul_f32 v[118:119], v[126:127], v[118:119]
	v_pk_mul_f32 v[120:121], v[126:127], v[120:121]
	v_rndne_f32_e32 v118, v118
	v_rndne_f32_e32 v119, v119
	v_rndne_f32_e32 v120, v120
	v_rndne_f32_e32 v121, v121
	v_cvt_i32_f32_e32 v118, v118
	v_cvt_i32_f32_e32 v119, v119
	v_cvt_i32_f32_e32 v120, v120
	v_cvt_i32_f32_e32 v121, v121
	v_perm_b32 v118, v119, v118, s16
	v_perm_b32 v120, v121, v120, s17
	v_or_b32_e32 v116, v118, v120
	v_lshlrev_b32_e32 v118, 16, v32
	v_and_b32_e32 v119, 0xffff0000, v32
	v_lshlrev_b32_e32 v120, 16, v33
	v_and_b32_e32 v121, 0xffff0000, v33
	v_pk_mul_f32 v[118:119], v[126:127], v[118:119]
	v_pk_mul_f32 v[120:121], v[126:127], v[120:121]
	v_rndne_f32_e32 v118, v118
	v_rndne_f32_e32 v119, v119
	v_rndne_f32_e32 v120, v120
	v_rndne_f32_e32 v121, v121
	v_cvt_i32_f32_e32 v118, v118
	v_cvt_i32_f32_e32 v119, v119
	v_cvt_i32_f32_e32 v120, v120
	v_cvt_i32_f32_e32 v121, v121
	v_perm_b32 v118, v119, v118, s16
	v_perm_b32 v120, v121, v120, s17
	v_or_b32_e32 v117, v118, v120
	global_store_dwordx2 v136, v[116:117], s[10:11] offset:3584
	s_mov_b64 exec, s[12:13]
	global_store_dword v137, v138, s[8:9]
	s_mov_b64 exec, -1
	s_add_u32 s10, s10, 0x800000
	s_addc_u32 s11, s11, 0
	s_add_u32 s8, s8, 0x2000
	s_addc_u32 s9, s9, 0
	global_load_dword v98, v137, s[6:7]
	global_load_dwordx4 v[2:5], v134, s[4:5] offset:0
	global_load_dwordx4 v[6:9], v134, s[4:5] offset:1024
	global_load_dwordx4 v[10:13], v134, s[4:5] offset:2048
	global_load_dwordx4 v[14:17], v134, s[4:5] offset:3072
	global_load_dwordx4 v[18:21], v135, s[4:5] offset:0
	global_load_dwordx4 v[22:25], v135, s[4:5] offset:1024
	global_load_dwordx4 v[26:29], v135, s[4:5] offset:2048
	global_load_dwordx4 v[30:33], v135, s[4:5] offset:3072
	s_add_u32 s4, s4, 0x1000000
	s_addc_u32 s5, s5, 0
	s_add_u32 s6, s6, 0x2000
	s_addc_u32 s7, s7, 0
	s_waitcnt vmcnt(35)
	v_div_scale_f32 v128, s[14:15], v99, v99, s3
	v_rcp_f32_e32 v129, v128
	v_div_scale_f32 v130, vcc, s3, v99, s3
	v_fma_f32 v131, -v128, v129, 1.0
	v_fmac_f32_e32 v129, v131, v129
	v_mul_f32_e32 v131, v130, v129
	v_fma_f32 v132, -v128, v131, v130
	v_fmac_f32_e32 v131, v132, v129
	v_fma_f32 v128, -v128, v131, v130
	v_div_fmas_f32 v128, v128, v129, v131
	v_div_fixup_f32 v128, v128, v99, s3
	v_cmp_lt_f32_e32 vcc, 0, v99
	v_mul_f32_e32 v138, 0x3c010204, v99
	v_cndmask_b32_e32 v126, 0, v128, vcc
	v_mov_b32_e32 v127, v126
	s_waitcnt vmcnt(34)
	v_lshlrev_b32_e32 v118, 16, v34
	v_and_b32_e32 v119, 0xffff0000, v34
	v_lshlrev_b32_e32 v120, 16, v35
	v_and_b32_e32 v121, 0xffff0000, v35
	v_pk_mul_f32 v[118:119], v[126:127], v[118:119]
	v_pk_mul_f32 v[120:121], v[126:127], v[120:121]
	v_rndne_f32_e32 v118, v118
	v_rndne_f32_e32 v119, v119
	v_rndne_f32_e32 v120, v120
	v_rndne_f32_e32 v121, v121
	v_cvt_i32_f32_e32 v118, v118
	v_cvt_i32_f32_e32 v119, v119
	v_cvt_i32_f32_e32 v120, v120
	v_cvt_i32_f32_e32 v121, v121
	v_perm_b32 v118, v119, v118, s16
	v_perm_b32 v120, v121, v120, s17
	v_or_b32_e32 v102, v118, v120
	v_lshlrev_b32_e32 v118, 16, v36
	v_and_b32_e32 v119, 0xffff0000, v36
	v_lshlrev_b32_e32 v120, 16, v37
	v_and_b32_e32 v121, 0xffff0000, v37
	v_pk_mul_f32 v[118:119], v[126:127], v[118:119]
	v_pk_mul_f32 v[120:121], v[126:127], v[120:121]
	v_rndne_f32_e32 v118, v118
	v_rndne_f32_e32 v119, v119
	v_rndne_f32_e32 v120, v120
	v_rndne_f32_e32 v121, v121
	v_cvt_i32_f32_e32 v118, v118
	v_cvt_i32_f32_e32 v119, v119
	v_cvt_i32_f32_e32 v120, v120
	v_cvt_i32_f32_e32 v121, v121
	v_perm_b32 v118, v119, v118, s16
	v_perm_b32 v120, v121, v120, s17
	v_or_b32_e32 v103, v118, v120
	global_store_dwordx2 v136, v[102:103], s[10:11] offset:0
	s_waitcnt vmcnt(34)
	v_lshlrev_b32_e32 v118, 16, v38
	v_and_b32_e32 v119, 0xffff0000, v38
	v_lshlrev_b32_e32 v120, 16, v39
	v_and_b32_e32 v121, 0xffff0000, v39
	v_pk_mul_f32 v[118:119], v[126:127], v[118:119]
	v_pk_mul_f32 v[120:121], v[126:127], v[120:121]
	v_rndne_f32_e32 v118, v118
	v_rndne_f32_e32 v119, v119
	v_rndne_f32_e32 v120, v120
	v_rndne_f32_e32 v121, v121
	v_cvt_i32_f32_e32 v118, v118
	v_cvt_i32_f32_e32 v119, v119
	v_cvt_i32_f32_e32 v120, v120
	v_cvt_i32_f32_e32 v121, v121
	v_perm_b32 v118, v119, v118, s16
	v_perm_b32 v120, v121, v120, s17
	v_or_b32_e32 v104, v118, v120
	v_lshlrev_b32_e32 v118, 16, v40
	v_and_b32_e32 v119, 0xffff0000, v40
	v_lshlrev_b32_e32 v120, 16, v41
	v_and_b32_e32 v121, 0xffff0000, v41
	v_pk_mul_f32 v[118:119], v[126:127], v[118:119]
	v_pk_mul_f32 v[120:121], v[126:127], v[120:121]
	v_rndne_f32_e32 v118, v118
	v_rndne_f32_e32 v119, v119
	v_rndne_f32_e32 v120, v120
	v_rndne_f32_e32 v121, v121
	v_cvt_i32_f32_e32 v118, v118
	v_cvt_i32_f32_e32 v119, v119
	v_cvt_i32_f32_e32 v120, v120
	v_cvt_i32_f32_e32 v121, v121
	v_perm_b32 v118, v119, v118, s16
	v_perm_b32 v120, v121, v120, s17
	v_or_b32_e32 v105, v118, v120
	global_store_dwordx2 v136, v[104:105], s[10:11] offset:512
	s_waitcnt vmcnt(34)
	v_lshlrev_b32_e32 v118, 16, v42
	v_and_b32_e32 v119, 0xffff0000, v42
	v_lshlrev_b32_e32 v120, 16, v43
	v_and_b32_e32 v121, 0xffff0000, v43
	v_pk_mul_f32 v[118:119], v[126:127], v[118:119]
	v_pk_mul_f32 v[120:121], v[126:127], v[120:121]
	v_rndne_f32_e32 v118, v118
	v_rndne_f32_e32 v119, v119
	v_rndne_f32_e32 v120, v120
	v_rndne_f32_e32 v121, v121
	v_cvt_i32_f32_e32 v118, v118
	v_cvt_i32_f32_e32 v119, v119
	v_cvt_i32_f32_e32 v120, v120
	v_cvt_i32_f32_e32 v121, v121
	v_perm_b32 v118, v119, v118, s16
	v_perm_b32 v120, v121, v120, s17
	v_or_b32_e32 v106, v118, v120
	v_lshlrev_b32_e32 v118, 16, v44
	v_and_b32_e32 v119, 0xffff0000, v44
	v_lshlrev_b32_e32 v120, 16, v45
	v_and_b32_e32 v121, 0xffff0000, v45
	v_pk_mul_f32 v[118:119], v[126:127], v[118:119]
	v_pk_mul_f32 v[120:121], v[126:127], v[120:121]
	v_rndne_f32_e32 v118, v118
	v_rndne_f32_e32 v119, v119
	v_rndne_f32_e32 v120, v120
	v_rndne_f32_e32 v121, v121
	v_cvt_i32_f32_e32 v118, v118
	v_cvt_i32_f32_e32 v119, v119
	v_cvt_i32_f32_e32 v120, v120
	v_cvt_i32_f32_e32 v121, v121
	v_perm_b32 v118, v119, v118, s16
	v_perm_b32 v120, v121, v120, s17
	v_or_b32_e32 v107, v118, v120
	global_store_dwordx2 v136, v[106:107], s[10:11] offset:1024
	s_waitcnt vmcnt(34)
; __device__ __forceinline__ unsigned q8(float x) { return (unsigned)(int)__builtin_rintf(x) & 0xffu; }
; __device__ __forceinline__ void rows_bf16_to_i8(Frame& F, const bf16* XBp, const unsigned* rmax, unsigned* X8, float* sx, int pitch4 = D / 4) {
;     ...
; #pragma unroll
;         for (int j = 0; j < 8; ++j) { v2u o;
;             o.x = q8(blo(w[j].x) * inv) | (q8(bhi(w[j].x) * inv) << 8) | (q8(blo(w[j].y) * inv) << 16) | (q8(bhi(w[j].y) * inv) << 24);
;             o.y = q8(blo(w[j].z) * inv) | (q8(bhi(w[j].z) * inv) << 8) | (q8(blo(w[j].w) * inv) << 16) | (q8(bhi(w[j].w) * inv) << 24);
;             dst[64 * j] = o; }
	v_lshlrev_b32_e32 v118, 16, v46
	v_and_b32_e32 v119, 0xffff0000, v46
	v_lshlrev_b32_e32 v120, 16, v47
	v_and_b32_e32 v121, 0xffff0000, v47
	v_pk_mul_f32 v[118:119], v[126:127], v[118:119]
	v_pk_mul_f32 v[120:121], v[126:127], v[120:121]
	v_rndne_f32_e32 v118, v118
	v_rndne_f32_e32 v119, v119
	v_rndne_f32_e32 v120, v120
	v_rndne_f32_e32 v121, v121
	v_cvt_i32_f32_e32 v118, v118
	v_cvt_i32_f32_e32 v119, v119
	v_cvt_i32_f32_e32 v120, v120
	v_cvt_i32_f32_e32 v121, v121
	v_perm_b32 v118, v119, v118, s16
	v_perm_b32 v120, v121, v120, s17
	v_or_b32_e32 v108, v118, v120
	v_lshlrev_b32_e32 v118, 16, v48
	v_and_b32_e32 v119, 0xffff0000, v48
	v_lshlrev_b32_e32 v120, 16, v49
	v_and_b32_e32 v121, 0xffff0000, v49
	v_pk_mul_f32 v[118:119], v[126:127], v[118:119]
	v_pk_mul_f32 v[120:121], v[126:127], v[120:121]
	v_rndne_f32_e32 v118, v118
	v_rndne_f32_e32 v119, v119
	v_rndne_f32_e32 v120, v120
	v_rndne_f32_e32 v121, v121
	v_cvt_i32_f32_e32 v118, v118
	v_cvt_i32_f32_e32 v119, v119
	v_cvt_i32_f32_e32 v120, v120
	v_cvt_i32_f32_e32 v121, v121
	v_perm_b32 v118, v119, v118, s16
	v_perm_b32 v120, v121, v120, s17
	v_or_b32_e32 v109, v118, v120
	global_store_dwordx2 v136, v[108:109], s[10:11] offset:1536
	s_waitcnt vmcnt(34)
	v_lshlrev_b32_e32 v118, 16, v50
	v_and_b32_e32 v119, 0xffff0000, v50
	v_lshlrev_b32_e32 v120, 16, v51
	v_and_b32_e32 v121, 0xffff0000, v51
	v_pk_mul_f32 v[118:119], v[126:127], v[118:119]
	v_pk_mul_f32 v[120:121], v[126:127], v[120:121]
	v_rndne_f32_e32 v118, v118
	v_rndne_f32_e32 v119, v119
	v_rndne_f32_e32 v120, v120
	v_rndne_f32_e32 v121, v121
	v_cvt_i32_f32_e32 v118, v118
	v_cvt_i32_f32_e32 v119, v119
	v_cvt_i32_f32_e32 v120, v120
	v_cvt_i32_f32_e32 v121, v121
	v_perm_b32 v118, v119, v118, s16
	v_perm_b32 v120, v121, v120, s17
	v_or_b32_e32 v110, v118, v120
	v_lshlrev_b32_e32 v118, 16, v52
	v_and_b32_e32 v119, 0xffff0000, v52
	v_lshlrev_b32_e32 v120, 16, v53
	v_and_b32_e32 v121, 0xffff0000, v53
	v_pk_mul_f32 v[118:119], v[126:127], v[118:119]
	v_pk_mul_f32 v[120:121], v[126:127], v[120:121]
	v_rndne_f32_e32 v118, v118
	v_rndne_f32_e32 v119, v119
	v_rndne_f32_e32 v120, v120
	v_rndne_f32_e32 v121, v121
	v_cvt_i32_f32_e32 v118, v118
	v_cvt_i32_f32_e32 v119, v119
	v_cvt_i32_f32_e32 v120, v120
	v_cvt_i32_f32_e32 v121, v121
	v_perm_b32 v118, v119, v118, s16
	v_perm_b32 v120, v121, v120, s17
	v_or_b32_e32 v111, v118, v120
	global_store_dwordx2 v136, v[110:111], s[10:11] offset:2048
	s_waitcnt vmcnt(34)
	v_lshlrev_b32_e32 v118, 16, v54
	v_and_b32_e32 v119, 0xffff0000, v54
	v_lshlrev_b32_e32 v120, 16, v55
	v_and_b32_e32 v121, 0xffff0000, v55
	v_pk_mul_f32 v[118:119], v[126:127], v[118:119]
	v_pk_mul_f32 v[120:121], v[126:127], v[120:121]
	v_rndne_f32_e32 v118, v118
	v_rndne_f32_e32 v119, v119
	v_rndne_f32_e32 v120, v120
	v_rndne_f32_e32 v121, v121
	v_cvt_i32_f32_e32 v118, v118
	v_cvt_i32_f32_e32 v119, v119
	v_cvt_i32_f32_e32 v120, v120
	v_cvt_i32_f32_e32 v121, v121
	v_perm_b32 v118, v119, v118, s16
	v_perm_b32 v120, v121, v120, s17
	v_or_b32_e32 v112, v118, v120
	v_lshlrev_b32_e32 v118, 16, v56
	v_and_b32_e32 v119, 0xffff0000, v56
	v_lshlrev_b32_e32 v120, 16, v57
	v_and_b32_e32 v121, 0xffff0000, v57
	v_pk_mul_f32 v[118:119], v[126:127], v[118:119]
	v_pk_mul_f32 v[120:121], v[126:127], v[120:121]
	v_rndne_f32_e32 v118, v118
	v_rndne_f32_e32 v119, v119
	v_rndne_f32_e32 v120, v120
	v_rndne_f32_e32 v121, v121
	v_cvt_i32_f32_e32 v118, v118
	v_cvt_i32_f32_e32 v119, v119
	v_cvt_i32_f32_e32 v120, v120
	v_cvt_i32_f32_e32 v121, v121
	v_perm_b32 v118, v119, v118, s16
	v_perm_b32 v120, v121, v120, s17
	v_or_b32_e32 v113, v118, v120
	global_store_dwordx2 v136, v[112:113], s[10:11] offset:2560
	s_waitcnt vmcnt(34)
	v_lshlrev_b32_e32 v118, 16, v58
	v_and_b32_e32 v119, 0xffff0000, v58
	v_lshlrev_b32_e32 v120, 16, v59
	v_and_b32_e32 v121, 0xffff0000, v59
	v_pk_mul_f32 v[118:119], v[126:127], v[118:119]
	v_pk_mul_f32 v[120:121], v[126:127], v[120:121]
	v_rndne_f32_e32 v118, v118
	v_rndne_f32_e32 v119, v119
	v_rndne_f32_e32 v120, v120
	v_rndne_f32_e32 v121, v121
	v_cvt_i32_f32_e32 v118, v118
	v_cvt_i32_f32_e32 v119, v119
	v_cvt_i32_f32_e32 v120, v120
	v_cvt_i32_f32_e32 v121, v121
	v_perm_b32 v118, v119, v118, s16
	v_perm_b32 v120, v121, v120, s17
	v_or_b32_e32 v114, v118, v120
	v_lshlrev_b32_e32 v118, 16, v60
	v_and_b32_e32 v119, 0xffff0000, v60
	v_lshlrev_b32_e32 v120, 16, v61
	v_and_b32_e32 v121, 0xffff0000, v61
	v_pk_mul_f32 v[118:119], v[126:127], v[118:119]
	v_pk_mul_f32 v[120:121], v[126:127], v[120:121]
	v_rndne_f32_e32 v118, v118
	v_rndne_f32_e32 v119, v119
	v_rndne_f32_e32 v120, v120
	v_rndne_f32_e32 v121, v121
	v_cvt_i32_f32_e32 v118, v118
	v_cvt_i32_f32_e32 v119, v119
	v_cvt_i32_f32_e32 v120, v120
	v_cvt_i32_f32_e32 v121, v121
	v_perm_b32 v118, v119, v118, s16
	v_perm_b32 v120, v121, v120, s17
	v_or_b32_e32 v115, v118, v120
	global_store_dwordx2 v136, v[114:115], s[10:11] offset:3072
	s_waitcnt vmcnt(34)
; __device__ __forceinline__ unsigned q8(float x) { return (unsigned)(int)__builtin_rintf(x) & 0xffu; }
; __device__ __forceinline__ void rows_bf16_to_i8(Frame& F, const bf16* XBp, const unsigned* rmax, unsigned* X8, float* sx, int pitch4 = D / 4) {
;     const int gw = F.vcu * NWAVES + F.wave, NGW = F.G * NWAVES, lane = F.lane;
;     v4u w[8], wn[8]; unsigned rb = 0, rbn = 0;
;     int m = gw;
;     if (m < M) { const v4u* src = (const v4u*)(XBp + (size_t)m * D) + lane; rb = rmax[m];
; #pragma unroll
;         for (int j = 0; j < 8; ++j) w[j] = src[64 * j]; }
;     for (; m < M; m += NGW) {
;         const int mn = m + NGW;
;         if (mn < M) { const v4u* src = (const v4u*)(XBp + (size_t)mn * D) + lane; rbn = rmax[mn];
; #pragma unroll
;             for (int j = 0; j < 8; ++j) wn[j] = src[64 * j]; }
;         const float mx = __builtin_bit_cast(float, rb), inv = mx > 0.f ? 127.0f / mx : 0.f;
;         v2u* dst = (v2u*)(X8 + (size_t)m * pitch4) + lane;
; #pragma unroll
;         for (int j = 0; j < 8; ++j) { v2u o;
;             o.x = q8(blo(w[j].x) * inv) | (q8(bhi(w[j].x) * inv) << 8) | (q8(blo(w[j].y) * inv) << 16) | (q8(bhi(w[j].y) * inv) << 24);
;             o.y = q8(blo(w[j].z) * inv) | (q8(bhi(w[j].z) * inv) << 8) | (q8(blo(w[j].w) * inv) << 16) | (q8(bhi(w[j].w) * inv) << 24);
;             dst[64 * j] = o; }
;         if (lane == 0) sx[m] = mx * (1.0f / 127.0f);
; #pragma unroll
;         for (int j = 0; j < 8; ++j) w[j] = wn[j];
;         rb = rbn;
;     }
; }
	v_lshlrev_b32_e32 v118, 16, v62
	v_and_b32_e32 v119, 0xffff0000, v62
	v_lshlrev_b32_e32 v120, 16, v63
	v_and_b32_e32 v121, 0xffff0000, v63
	v_pk_mul_f32 v[118:119], v[126:127], v[118:119]
	v_pk_mul_f32 v[120:121], v[126:127], v[120:121]
	v_rndne_f32_e32 v118, v118
	v_rndne_f32_e32 v119, v119
	v_rndne_f32_e32 v120, v120
	v_rndne_f32_e32 v121, v121
	v_cvt_i32_f32_e32 v118, v118
	v_cvt_i32_f32_e32 v119, v119
	v_cvt_i32_f32_e32 v120, v120
	v_cvt_i32_f32_e32 v121, v121
	v_perm_b32 v118, v119, v118, s16
	v_perm_b32 v120, v121, v120, s17
	v_or_b32_e32 v116, v118, v120
	v_lshlrev_b32_e32 v118, 16, v64
	v_and_b32_e32 v119, 0xffff0000, v64
	v_lshlrev_b32_e32 v120, 16, v65
	v_and_b32_e32 v121, 0xffff0000, v65
	v_pk_mul_f32 v[118:119], v[126:127], v[118:119]
	v_pk_mul_f32 v[120:121], v[126:127], v[120:121]
	v_rndne_f32_e32 v118, v118
	v_rndne_f32_e32 v119, v119
	v_rndne_f32_e32 v120, v120
	v_rndne_f32_e32 v121, v121
	v_cvt_i32_f32_e32 v118, v118
	v_cvt_i32_f32_e32 v119, v119
	v_cvt_i32_f32_e32 v120, v120
	v_cvt_i32_f32_e32 v121, v121
	v_perm_b32 v118, v119, v118, s16
	v_perm_b32 v120, v121, v120, s17
	v_or_b32_e32 v117, v118, v120
	global_store_dwordx2 v136, v[116:117], s[10:11] offset:3584
	s_mov_b64 exec, s[12:13]
	global_store_dword v137, v138, s[8:9]
	s_mov_b64 exec, -1
	s_add_u32 s10, s10, 0x800000
	s_addc_u32 s11, s11, 0
	s_add_u32 s8, s8, 0x2000
	s_addc_u32 s9, s9, 0
	global_load_dword v99, v137, s[6:7]
	global_load_dwordx4 v[34:37], v134, s[4:5] offset:0
	global_load_dwordx4 v[38:41], v134, s[4:5] offset:1024
	global_load_dwordx4 v[42:45], v134, s[4:5] offset:2048
	global_load_dwordx4 v[46:49], v134, s[4:5] offset:3072
	global_load_dwordx4 v[50:53], v135, s[4:5] offset:0
	global_load_dwordx4 v[54:57], v135, s[4:5] offset:1024
	global_load_dwordx4 v[58:61], v135, s[4:5] offset:2048
	global_load_dwordx4 v[62:65], v135, s[4:5] offset:3072
	s_add_u32 s4, s4, 0x1000000
	s_addc_u32 s5, s5, 0
	s_add_u32 s6, s6, 0x2000
	s_addc_u32 s7, s7, 0
	s_waitcnt vmcnt(44)
	v_div_scale_f32 v128, s[14:15], v100, v100, s3
	v_rcp_f32_e32 v129, v128
	v_div_scale_f32 v130, vcc, s3, v100, s3
	v_fma_f32 v131, -v128, v129, 1.0
	v_fmac_f32_e32 v129, v131, v129
	v_mul_f32_e32 v131, v130, v129
	v_fma_f32 v132, -v128, v131, v130
	v_fmac_f32_e32 v131, v132, v129
	v_fma_f32 v128, -v128, v131, v130
	v_div_fmas_f32 v128, v128, v129, v131
	v_div_fixup_f32 v128, v128, v100, s3
	v_cmp_lt_f32_e32 vcc, 0, v100
	v_mul_f32_e32 v138, 0x3c010204, v100
	v_cndmask_b32_e32 v126, 0, v128, vcc
	v_mov_b32_e32 v127, v126
	s_waitcnt vmcnt(43)
	v_lshlrev_b32_e32 v118, 16, v66
	v_and_b32_e32 v119, 0xffff0000, v66
	v_lshlrev_b32_e32 v120, 16, v67
	v_and_b32_e32 v121, 0xffff0000, v67
	v_pk_mul_f32 v[118:119], v[126:127], v[118:119]
	v_pk_mul_f32 v[120:121], v[126:127], v[120:121]
	v_rndne_f32_e32 v118, v118
	v_rndne_f32_e32 v119, v119
	v_rndne_f32_e32 v120, v120
	v_rndne_f32_e32 v121, v121
	v_cvt_i32_f32_e32 v118, v118
	v_cvt_i32_f32_e32 v119, v119
	v_cvt_i32_f32_e32 v120, v120
	v_cvt_i32_f32_e32 v121, v121
	v_perm_b32 v118, v119, v118, s16
	v_perm_b32 v120, v121, v120, s17
	v_or_b32_e32 v102, v118, v120
	v_lshlrev_b32_e32 v118, 16, v68
	v_and_b32_e32 v119, 0xffff0000, v68
	v_lshlrev_b32_e32 v120, 16, v69
	v_and_b32_e32 v121, 0xffff0000, v69
	v_pk_mul_f32 v[118:119], v[126:127], v[118:119]
	v_pk_mul_f32 v[120:121], v[126:127], v[120:121]
	v_rndne_f32_e32 v118, v118
	v_rndne_f32_e32 v119, v119
	v_rndne_f32_e32 v120, v120
	v_rndne_f32_e32 v121, v121
	v_cvt_i32_f32_e32 v118, v118
	v_cvt_i32_f32_e32 v119, v119
	v_cvt_i32_f32_e32 v120, v120
	v_cvt_i32_f32_e32 v121, v121
	v_perm_b32 v118, v119, v118, s16
	v_perm_b32 v120, v121, v120, s17
	v_or_b32_e32 v103, v118, v120
	global_store_dwordx2 v136, v[102:103], s[10:11] offset:0
	s_waitcnt vmcnt(43)
	v_lshlrev_b32_e32 v118, 16, v70
	v_and_b32_e32 v119, 0xffff0000, v70
	v_lshlrev_b32_e32 v120, 16, v71
	v_and_b32_e32 v121, 0xffff0000, v71
	v_pk_mul_f32 v[118:119], v[126:127], v[118:119]
	v_pk_mul_f32 v[120:121], v[126:127], v[120:121]
	v_rndne_f32_e32 v118, v118
	v_rndne_f32_e32 v119, v119
	v_rndne_f32_e32 v120, v120
	v_rndne_f32_e32 v121, v121
	v_cvt_i32_f32_e32 v118, v118
	v_cvt_i32_f32_e32 v119, v119
	v_cvt_i32_f32_e32 v120, v120
	v_cvt_i32_f32_e32 v121, v121
	v_perm_b32 v118, v119, v118, s16
	v_perm_b32 v120, v121, v120, s17
	v_or_b32_e32 v104, v118, v120
	v_lshlrev_b32_e32 v118, 16, v72
	v_and_b32_e32 v119, 0xffff0000, v72
	v_lshlrev_b32_e32 v120, 16, v73
	v_and_b32_e32 v121, 0xffff0000, v73
	v_pk_mul_f32 v[118:119], v[126:127], v[118:119]
	v_pk_mul_f32 v[120:121], v[126:127], v[120:121]
	v_rndne_f32_e32 v118, v118
	v_rndne_f32_e32 v119, v119
	v_rndne_f32_e32 v120, v120
	v_rndne_f32_e32 v121, v121
	v_cvt_i32_f32_e32 v118, v118
	v_cvt_i32_f32_e32 v119, v119
	v_cvt_i32_f32_e32 v120, v120
	v_cvt_i32_f32_e32 v121, v121
	v_perm_b32 v118, v119, v118, s16
	v_perm_b32 v120, v121, v120, s17
	v_or_b32_e32 v105, v118, v120
	global_store_dwordx2 v136, v[104:105], s[10:11] offset:512
	s_waitcnt vmcnt(43)
	v_lshlrev_b32_e32 v118, 16, v74
	v_and_b32_e32 v119, 0xffff0000, v74
	v_lshlrev_b32_e32 v120, 16, v75
	v_and_b32_e32 v121, 0xffff0000, v75
	v_pk_mul_f32 v[118:119], v[126:127], v[118:119]
	v_pk_mul_f32 v[120:121], v[126:127], v[120:121]
	v_rndne_f32_e32 v118, v118
	v_rndne_f32_e32 v119, v119
	v_rndne_f32_e32 v120, v120
	v_rndne_f32_e32 v121, v121
	v_cvt_i32_f32_e32 v118, v118
	v_cvt_i32_f32_e32 v119, v119
	v_cvt_i32_f32_e32 v120, v120
	v_cvt_i32_f32_e32 v121, v121
	v_perm_b32 v118, v119, v118, s16
	v_perm_b32 v120, v121, v120, s17
	v_or_b32_e32 v106, v118, v120
	v_lshlrev_b32_e32 v118, 16, v76
	v_and_b32_e32 v119, 0xffff0000, v76
	v_lshlrev_b32_e32 v120, 16, v77
	v_and_b32_e32 v121, 0xffff0000, v77
	v_pk_mul_f32 v[118:119], v[126:127], v[118:119]
	v_pk_mul_f32 v[120:121], v[126:127], v[120:121]
	v_rndne_f32_e32 v118, v118
	v_rndne_f32_e32 v119, v119
	v_rndne_f32_e32 v120, v120
	v_rndne_f32_e32 v121, v121
	v_cvt_i32_f32_e32 v118, v118
	v_cvt_i32_f32_e32 v119, v119
	v_cvt_i32_f32_e32 v120, v120
	v_cvt_i32_f32_e32 v121, v121
	v_perm_b32 v118, v119, v118, s16
	v_perm_b32 v120, v121, v120, s17
	v_or_b32_e32 v107, v118, v120
	global_store_dwordx2 v136, v[106:107], s[10:11] offset:1024
	s_waitcnt vmcnt(43)
; __device__ __forceinline__ unsigned q8(float x) { return (unsigned)(int)__builtin_rintf(x) & 0xffu; }
; __device__ __forceinline__ void rows_bf16_to_i8(Frame& F, const bf16* XBp, const unsigned* rmax, unsigned* X8, float* sx, int pitch4 = D / 4) {
;     ...
;         const float mx = __builtin_bit_cast(float, rb), inv = mx > 0.f ? 127.0f / mx : 0.f;
;         v2u* dst = (v2u*)(X8 + (size_t)m * pitch4) + lane;
; #pragma unroll
;         for (int j = 0; j < 8; ++j) { v2u o;
;             o.x = q8(blo(w[j].x) * inv) | (q8(bhi(w[j].x) * inv) << 8) | (q8(blo(w[j].y) * inv) << 16) | (q8(bhi(w[j].y) * inv) << 24);
;             o.y = q8(blo(w[j].z) * inv) | (q8(bhi(w[j].z) * inv) << 8) | (q8(blo(w[j].w) * inv) << 16) | (q8(bhi(w[j].w) * inv) << 24);
;             dst[64 * j] = o; }
	v_lshlrev_b32_e32 v118, 16, v78
	v_and_b32_e32 v119, 0xffff0000, v78
	v_lshlrev_b32_e32 v120, 16, v79
	v_and_b32_e32 v121, 0xffff0000, v79
	v_pk_mul_f32 v[118:119], v[126:127], v[118:119]
	v_pk_mul_f32 v[120:121], v[126:127], v[120:121]
	v_rndne_f32_e32 v118, v118
	v_rndne_f32_e32 v119, v119
	v_rndne_f32_e32 v120, v120
	v_rndne_f32_e32 v121, v121
	v_cvt_i32_f32_e32 v118, v118
	v_cvt_i32_f32_e32 v119, v119
	v_cvt_i32_f32_e32 v120, v120
	v_cvt_i32_f32_e32 v121, v121
	v_perm_b32 v118, v119, v118, s16
	v_perm_b32 v120, v121, v120, s17
	v_or_b32_e32 v108, v118, v120
	v_lshlrev_b32_e32 v118, 16, v80
	v_and_b32_e32 v119, 0xffff0000, v80
	v_lshlrev_b32_e32 v120, 16, v81
	v_and_b32_e32 v121, 0xffff0000, v81
	v_pk_mul_f32 v[118:119], v[126:127], v[118:119]
	v_pk_mul_f32 v[120:121], v[126:127], v[120:121]
	v_rndne_f32_e32 v118, v118
	v_rndne_f32_e32 v119, v119
	v_rndne_f32_e32 v120, v120
	v_rndne_f32_e32 v121, v121
	v_cvt_i32_f32_e32 v118, v118
	v_cvt_i32_f32_e32 v119, v119
	v_cvt_i32_f32_e32 v120, v120
	v_cvt_i32_f32_e32 v121, v121
	v_perm_b32 v118, v119, v118, s16
	v_perm_b32 v120, v121, v120, s17
	v_or_b32_e32 v109, v118, v120
	global_store_dwordx2 v136, v[108:109], s[10:11] offset:1536
	s_waitcnt vmcnt(43)
	v_lshlrev_b32_e32 v118, 16, v82
	v_and_b32_e32 v119, 0xffff0000, v82
	v_lshlrev_b32_e32 v120, 16, v83
	v_and_b32_e32 v121, 0xffff0000, v83
	v_pk_mul_f32 v[118:119], v[126:127], v[118:119]
	v_pk_mul_f32 v[120:121], v[126:127], v[120:121]
	v_rndne_f32_e32 v118, v118
	v_rndne_f32_e32 v119, v119
	v_rndne_f32_e32 v120, v120
	v_rndne_f32_e32 v121, v121
	v_cvt_i32_f32_e32 v118, v118
	v_cvt_i32_f32_e32 v119, v119
	v_cvt_i32_f32_e32 v120, v120
	v_cvt_i32_f32_e32 v121, v121
	v_perm_b32 v118, v119, v118, s16
	v_perm_b32 v120, v121, v120, s17
	v_or_b32_e32 v110, v118, v120
	v_lshlrev_b32_e32 v118, 16, v84
	v_and_b32_e32 v119, 0xffff0000, v84
	v_lshlrev_b32_e32 v120, 16, v85
	v_and_b32_e32 v121, 0xffff0000, v85
	v_pk_mul_f32 v[118:119], v[126:127], v[118:119]
	v_pk_mul_f32 v[120:121], v[126:127], v[120:121]
	v_rndne_f32_e32 v118, v118
	v_rndne_f32_e32 v119, v119
	v_rndne_f32_e32 v120, v120
	v_rndne_f32_e32 v121, v121
	v_cvt_i32_f32_e32 v118, v118
	v_cvt_i32_f32_e32 v119, v119
	v_cvt_i32_f32_e32 v120, v120
	v_cvt_i32_f32_e32 v121, v121
	v_perm_b32 v118, v119, v118, s16
	v_perm_b32 v120, v121, v120, s17
	v_or_b32_e32 v111, v118, v120
	global_store_dwordx2 v136, v[110:111], s[10:11] offset:2048
	s_waitcnt vmcnt(43)
	v_lshlrev_b32_e32 v118, 16, v86
	v_and_b32_e32 v119, 0xffff0000, v86
	v_lshlrev_b32_e32 v120, 16, v87
	v_and_b32_e32 v121, 0xffff0000, v87
	v_pk_mul_f32 v[118:119], v[126:127], v[118:119]
	v_pk_mul_f32 v[120:121], v[126:127], v[120:121]
	v_rndne_f32_e32 v118, v118
	v_rndne_f32_e32 v119, v119
	v_rndne_f32_e32 v120, v120
	v_rndne_f32_e32 v121, v121
	v_cvt_i32_f32_e32 v118, v118
	v_cvt_i32_f32_e32 v119, v119
	v_cvt_i32_f32_e32 v120, v120
	v_cvt_i32_f32_e32 v121, v121
	v_perm_b32 v118, v119, v118, s16
	v_perm_b32 v120, v121, v120, s17
	v_or_b32_e32 v112, v118, v120
	v_lshlrev_b32_e32 v118, 16, v88
	v_and_b32_e32 v119, 0xffff0000, v88
	v_lshlrev_b32_e32 v120, 16, v89
	v_and_b32_e32 v121, 0xffff0000, v89
	v_pk_mul_f32 v[118:119], v[126:127], v[118:119]
	v_pk_mul_f32 v[120:121], v[126:127], v[120:121]
	v_rndne_f32_e32 v118, v118
	v_rndne_f32_e32 v119, v119
	v_rndne_f32_e32 v120, v120
	v_rndne_f32_e32 v121, v121
	v_cvt_i32_f32_e32 v118, v118
	v_cvt_i32_f32_e32 v119, v119
	v_cvt_i32_f32_e32 v120, v120
	v_cvt_i32_f32_e32 v121, v121
	v_perm_b32 v118, v119, v118, s16
	v_perm_b32 v120, v121, v120, s17
	v_or_b32_e32 v113, v118, v120
	global_store_dwordx2 v136, v[112:113], s[10:11] offset:2560
	s_waitcnt vmcnt(43)
	v_lshlrev_b32_e32 v118, 16, v90
	v_and_b32_e32 v119, 0xffff0000, v90
	v_lshlrev_b32_e32 v120, 16, v91
	v_and_b32_e32 v121, 0xffff0000, v91
	v_pk_mul_f32 v[118:119], v[126:127], v[118:119]
	v_pk_mul_f32 v[120:121], v[126:127], v[120:121]
	v_rndne_f32_e32 v118, v118
	v_rndne_f32_e32 v119, v119
	v_rndne_f32_e32 v120, v120
	v_rndne_f32_e32 v121, v121
	v_cvt_i32_f32_e32 v118, v118
	v_cvt_i32_f32_e32 v119, v119
	v_cvt_i32_f32_e32 v120, v120
	v_cvt_i32_f32_e32 v121, v121
	v_perm_b32 v118, v119, v118, s16
	v_perm_b32 v120, v121, v120, s17
	v_or_b32_e32 v114, v118, v120
	v_lshlrev_b32_e32 v118, 16, v92
	v_and_b32_e32 v119, 0xffff0000, v92
	v_lshlrev_b32_e32 v120, 16, v93
	v_and_b32_e32 v121, 0xffff0000, v93
	v_pk_mul_f32 v[118:119], v[126:127], v[118:119]
	v_pk_mul_f32 v[120:121], v[126:127], v[120:121]
	v_rndne_f32_e32 v118, v118
	v_rndne_f32_e32 v119, v119
	v_rndne_f32_e32 v120, v120
	v_rndne_f32_e32 v121, v121
	v_cvt_i32_f32_e32 v118, v118
	v_cvt_i32_f32_e32 v119, v119
	v_cvt_i32_f32_e32 v120, v120
	v_cvt_i32_f32_e32 v121, v121
	v_perm_b32 v118, v119, v118, s16
	v_perm_b32 v120, v121, v120, s17
	v_or_b32_e32 v115, v118, v120
	global_store_dwordx2 v136, v[114:115], s[10:11] offset:3072
	s_waitcnt vmcnt(43)
; __device__ __forceinline__ unsigned q8(float x) { return (unsigned)(int)__builtin_rintf(x) & 0xffu; }
; __device__ __forceinline__ void rows_bf16_to_i8(Frame& F, const bf16* XBp, const unsigned* rmax, unsigned* X8, float* sx, int pitch4 = D / 4) {
;     ...
;     if (m < M) { const v4u* src = (const v4u*)(XBp + (size_t)m * D) + lane; rb = rmax[m];
; #pragma unroll
;         for (int j = 0; j < 8; ++j) w[j] = src[64 * j]; }
;     for (; m < M; m += NGW) {
;         const int mn = m + NGW;
;         if (mn < M) { const v4u* src = (const v4u*)(XBp + (size_t)mn * D) + lane; rbn = rmax[mn];
; #pragma unroll
;             for (int j = 0; j < 8; ++j) wn[j] = src[64 * j]; }
;         const float mx = __builtin_bit_cast(float, rb), inv = mx > 0.f ? 127.0f / mx : 0.f;
;         v2u* dst = (v2u*)(X8 + (size_t)m * pitch4) + lane;
; #pragma unroll
;         for (int j = 0; j < 8; ++j) { v2u o;
;             o.x = q8(blo(w[j].x) * inv) | (q8(bhi(w[j].x) * inv) << 8) | (q8(blo(w[j].y) * inv) << 16) | (q8(bhi(w[j].y) * inv) << 24);
;             o.y = q8(blo(w[j].z) * inv) | (q8(bhi(w[j].z) * inv) << 8) | (q8(blo(w[j].w) * inv) << 16) | (q8(bhi(w[j].w) * inv) << 24);
;             dst[64 * j] = o; }
;         if (lane == 0) sx[m] = mx * (1.0f / 127.0f);
; #pragma unroll
;         for (int j = 0; j < 8; ++j) w[j] = wn[j];
;         rb = rbn;
;     }
; }
	v_lshlrev_b32_e32 v118, 16, v94
	v_and_b32_e32 v119, 0xffff0000, v94
	v_lshlrev_b32_e32 v120, 16, v95
	v_and_b32_e32 v121, 0xffff0000, v95
	v_pk_mul_f32 v[118:119], v[126:127], v[118:119]
	v_pk_mul_f32 v[120:121], v[126:127], v[120:121]
	v_rndne_f32_e32 v118, v118
	v_rndne_f32_e32 v119, v119
	v_rndne_f32_e32 v120, v120
	v_rndne_f32_e32 v121, v121
	v_cvt_i32_f32_e32 v118, v118
	v_cvt_i32_f32_e32 v119, v119
	v_cvt_i32_f32_e32 v120, v120
	v_cvt_i32_f32_e32 v121, v121
	v_perm_b32 v118, v119, v118, s16
	v_perm_b32 v120, v121, v120, s17
	v_or_b32_e32 v116, v118, v120
	v_lshlrev_b32_e32 v118, 16, v96
	v_and_b32_e32 v119, 0xffff0000, v96
	v_lshlrev_b32_e32 v120, 16, v97
	v_and_b32_e32 v121, 0xffff0000, v97
	v_pk_mul_f32 v[118:119], v[126:127], v[118:119]
	v_pk_mul_f32 v[120:121], v[126:127], v[120:121]
	v_rndne_f32_e32 v118, v118
	v_rndne_f32_e32 v119, v119
	v_rndne_f32_e32 v120, v120
	v_rndne_f32_e32 v121, v121
	v_cvt_i32_f32_e32 v118, v118
	v_cvt_i32_f32_e32 v119, v119
	v_cvt_i32_f32_e32 v120, v120
	v_cvt_i32_f32_e32 v121, v121
	v_perm_b32 v118, v119, v118, s16
	v_perm_b32 v120, v121, v120, s17
	v_or_b32_e32 v117, v118, v120
	global_store_dwordx2 v136, v[116:117], s[10:11] offset:3584
	s_mov_b64 exec, s[12:13]
	global_store_dword v137, v138, s[8:9]
	s_mov_b64 exec, -1
	s_add_u32 s10, s10, 0x800000
	s_addc_u32 s11, s11, 0
	s_add_u32 s8, s8, 0x2000
	s_addc_u32 s9, s9, 0
	global_load_dword v100, v137, s[6:7]
	global_load_dwordx4 v[66:69], v134, s[4:5] offset:0
	global_load_dwordx4 v[70:73], v134, s[4:5] offset:1024
	global_load_dwordx4 v[74:77], v134, s[4:5] offset:2048
	global_load_dwordx4 v[78:81], v134, s[4:5] offset:3072
	global_load_dwordx4 v[82:85], v135, s[4:5] offset:0
	global_load_dwordx4 v[86:89], v135, s[4:5] offset:1024
	global_load_dwordx4 v[90:93], v135, s[4:5] offset:2048
	global_load_dwordx4 v[94:97], v135, s[4:5] offset:3072
	s_add_u32 s4, s4, 0x1000000
	s_addc_u32 s5, s5, 0
	s_add_u32 s6, s6, 0x2000
	s_addc_u32 s7, s7, 0
	s_waitcnt vmcnt(44)
	v_div_scale_f32 v128, s[14:15], v98, v98, s3
	v_rcp_f32_e32 v129, v128
	v_div_scale_f32 v130, vcc, s3, v98, s3
	v_fma_f32 v131, -v128, v129, 1.0
	v_fmac_f32_e32 v129, v131, v129
	v_mul_f32_e32 v131, v130, v129
	v_fma_f32 v132, -v128, v131, v130
	v_fmac_f32_e32 v131, v132, v129
	v_fma_f32 v128, -v128, v131, v130
	v_div_fmas_f32 v128, v128, v129, v131
	v_div_fixup_f32 v128, v128, v98, s3
	v_cmp_lt_f32_e32 vcc, 0, v98
	v_mul_f32_e32 v138, 0x3c010204, v98
	v_cndmask_b32_e32 v126, 0, v128, vcc
	v_mov_b32_e32 v127, v126
	s_waitcnt vmcnt(43)
	v_lshlrev_b32_e32 v118, 16, v2
	v_and_b32_e32 v119, 0xffff0000, v2
	v_lshlrev_b32_e32 v120, 16, v3
	v_and_b32_e32 v121, 0xffff0000, v3
	v_pk_mul_f32 v[118:119], v[126:127], v[118:119]
	v_pk_mul_f32 v[120:121], v[126:127], v[120:121]
	v_rndne_f32_e32 v118, v118
	v_rndne_f32_e32 v119, v119
	v_rndne_f32_e32 v120, v120
	v_rndne_f32_e32 v121, v121
	v_cvt_i32_f32_e32 v118, v118
	v_cvt_i32_f32_e32 v119, v119
	v_cvt_i32_f32_e32 v120, v120
	v_cvt_i32_f32_e32 v121, v121
	v_perm_b32 v118, v119, v118, s16
	v_perm_b32 v120, v121, v120, s17
	v_or_b32_e32 v102, v118, v120
	v_lshlrev_b32_e32 v118, 16, v4
	v_and_b32_e32 v119, 0xffff0000, v4
	v_lshlrev_b32_e32 v120, 16, v5
	v_and_b32_e32 v121, 0xffff0000, v5
	v_pk_mul_f32 v[118:119], v[126:127], v[118:119]
	v_pk_mul_f32 v[120:121], v[126:127], v[120:121]
	v_rndne_f32_e32 v118, v118
	v_rndne_f32_e32 v119, v119
	v_rndne_f32_e32 v120, v120
	v_rndne_f32_e32 v121, v121
	v_cvt_i32_f32_e32 v118, v118
	v_cvt_i32_f32_e32 v119, v119
	v_cvt_i32_f32_e32 v120, v120
	v_cvt_i32_f32_e32 v121, v121
	v_perm_b32 v118, v119, v118, s16
	v_perm_b32 v120, v121, v120, s17
	v_or_b32_e32 v103, v118, v120
	global_store_dwordx2 v136, v[102:103], s[10:11] offset:0
	s_waitcnt vmcnt(43)
	v_lshlrev_b32_e32 v118, 16, v6
	v_and_b32_e32 v119, 0xffff0000, v6
	v_lshlrev_b32_e32 v120, 16, v7
	v_and_b32_e32 v121, 0xffff0000, v7
	v_pk_mul_f32 v[118:119], v[126:127], v[118:119]
	v_pk_mul_f32 v[120:121], v[126:127], v[120:121]
	v_rndne_f32_e32 v118, v118
	v_rndne_f32_e32 v119, v119
	v_rndne_f32_e32 v120, v120
	v_rndne_f32_e32 v121, v121
	v_cvt_i32_f32_e32 v118, v118
	v_cvt_i32_f32_e32 v119, v119
	v_cvt_i32_f32_e32 v120, v120
	v_cvt_i32_f32_e32 v121, v121
	v_perm_b32 v118, v119, v118, s16
	v_perm_b32 v120, v121, v120, s17
	v_or_b32_e32 v104, v118, v120
	v_lshlrev_b32_e32 v118, 16, v8
	v_and_b32_e32 v119, 0xffff0000, v8
	v_lshlrev_b32_e32 v120, 16, v9
	v_and_b32_e32 v121, 0xffff0000, v9
	v_pk_mul_f32 v[118:119], v[126:127], v[118:119]
	v_pk_mul_f32 v[120:121], v[126:127], v[120:121]
	v_rndne_f32_e32 v118, v118
	v_rndne_f32_e32 v119, v119
	v_rndne_f32_e32 v120, v120
	v_rndne_f32_e32 v121, v121
	v_cvt_i32_f32_e32 v118, v118
	v_cvt_i32_f32_e32 v119, v119
	v_cvt_i32_f32_e32 v120, v120
	v_cvt_i32_f32_e32 v121, v121
	v_perm_b32 v118, v119, v118, s16
	v_perm_b32 v120, v121, v120, s17
	v_or_b32_e32 v105, v118, v120
	global_store_dwordx2 v136, v[104:105], s[10:11] offset:512
	s_waitcnt vmcnt(43)
	v_lshlrev_b32_e32 v118, 16, v10
	v_and_b32_e32 v119, 0xffff0000, v10
	v_lshlrev_b32_e32 v120, 16, v11
	v_and_b32_e32 v121, 0xffff0000, v11
	v_pk_mul_f32 v[118:119], v[126:127], v[118:119]
	v_pk_mul_f32 v[120:121], v[126:127], v[120:121]
	v_rndne_f32_e32 v118, v118
	v_rndne_f32_e32 v119, v119
	v_rndne_f32_e32 v120, v120
	v_rndne_f32_e32 v121, v121
	v_cvt_i32_f32_e32 v118, v118
	v_cvt_i32_f32_e32 v119, v119
	v_cvt_i32_f32_e32 v120, v120
	v_cvt_i32_f32_e32 v121, v121
	v_perm_b32 v118, v119, v118, s16
	v_perm_b32 v120, v121, v120, s17
	v_or_b32_e32 v106, v118, v120
	v_lshlrev_b32_e32 v118, 16, v12
	v_and_b32_e32 v119, 0xffff0000, v12
	v_lshlrev_b32_e32 v120, 16, v13
	v_and_b32_e32 v121, 0xffff0000, v13
	v_pk_mul_f32 v[118:119], v[126:127], v[118:119]
	v_pk_mul_f32 v[120:121], v[126:127], v[120:121]
	v_rndne_f32_e32 v118, v118
	v_rndne_f32_e32 v119, v119
	v_rndne_f32_e32 v120, v120
	v_rndne_f32_e32 v121, v121
	v_cvt_i32_f32_e32 v118, v118
	v_cvt_i32_f32_e32 v119, v119
	v_cvt_i32_f32_e32 v120, v120
	v_cvt_i32_f32_e32 v121, v121
	v_perm_b32 v118, v119, v118, s16
	v_perm_b32 v120, v121, v120, s17
	v_or_b32_e32 v107, v118, v120
	global_store_dwordx2 v136, v[106:107], s[10:11] offset:1024
	s_waitcnt vmcnt(43)
; __device__ __forceinline__ unsigned q8(float x) { return (unsigned)(int)__builtin_rintf(x) & 0xffu; }
; __device__ __forceinline__ void rows_bf16_to_i8(Frame& F, const bf16* XBp, const unsigned* rmax, unsigned* X8, float* sx, int pitch4 = D / 4) {
;     ...
;         const float mx = __builtin_bit_cast(float, rb), inv = mx > 0.f ? 127.0f / mx : 0.f;
;         v2u* dst = (v2u*)(X8 + (size_t)m * pitch4) + lane;
; #pragma unroll
;         for (int j = 0; j < 8; ++j) { v2u o;
;             o.x = q8(blo(w[j].x) * inv) | (q8(bhi(w[j].x) * inv) << 8) | (q8(blo(w[j].y) * inv) << 16) | (q8(bhi(w[j].y) * inv) << 24);
;             o.y = q8(blo(w[j].z) * inv) | (q8(bhi(w[j].z) * inv) << 8) | (q8(blo(w[j].w) * inv) << 16) | (q8(bhi(w[j].w) * inv) << 24);
;             dst[64 * j] = o; }
	v_lshlrev_b32_e32 v118, 16, v14
	v_and_b32_e32 v119, 0xffff0000, v14
	v_lshlrev_b32_e32 v120, 16, v15
	v_and_b32_e32 v121, 0xffff0000, v15
	v_pk_mul_f32 v[118:119], v[126:127], v[118:119]
	v_pk_mul_f32 v[120:121], v[126:127], v[120:121]
	v_rndne_f32_e32 v118, v118
	v_rndne_f32_e32 v119, v119
	v_rndne_f32_e32 v120, v120
	v_rndne_f32_e32 v121, v121
	v_cvt_i32_f32_e32 v118, v118
	v_cvt_i32_f32_e32 v119, v119
	v_cvt_i32_f32_e32 v120, v120
	v_cvt_i32_f32_e32 v121, v121
	v_perm_b32 v118, v119, v118, s16
	v_perm_b32 v120, v121, v120, s17
	v_or_b32_e32 v108, v118, v120
	v_lshlrev_b32_e32 v118, 16, v16
	v_and_b32_e32 v119, 0xffff0000, v16
	v_lshlrev_b32_e32 v120, 16, v17
	v_and_b32_e32 v121, 0xffff0000, v17
	v_pk_mul_f32 v[118:119], v[126:127], v[118:119]
	v_pk_mul_f32 v[120:121], v[126:127], v[120:121]
	v_rndne_f32_e32 v118, v118
	v_rndne_f32_e32 v119, v119
	v_rndne_f32_e32 v120, v120
	v_rndne_f32_e32 v121, v121
	v_cvt_i32_f32_e32 v118, v118
	v_cvt_i32_f32_e32 v119, v119
	v_cvt_i32_f32_e32 v120, v120
	v_cvt_i32_f32_e32 v121, v121
	v_perm_b32 v118, v119, v118, s16
	v_perm_b32 v120, v121, v120, s17
	v_or_b32_e32 v109, v118, v120
	global_store_dwordx2 v136, v[108:109], s[10:11] offset:1536
	s_waitcnt vmcnt(43)
	v_lshlrev_b32_e32 v118, 16, v18
	v_and_b32_e32 v119, 0xffff0000, v18
	v_lshlrev_b32_e32 v120, 16, v19
	v_and_b32_e32 v121, 0xffff0000, v19
	v_pk_mul_f32 v[118:119], v[126:127], v[118:119]
	v_pk_mul_f32 v[120:121], v[126:127], v[120:121]
	v_rndne_f32_e32 v118, v118
	v_rndne_f32_e32 v119, v119
	v_rndne_f32_e32 v120, v120
	v_rndne_f32_e32 v121, v121
	v_cvt_i32_f32_e32 v118, v118
	v_cvt_i32_f32_e32 v119, v119
	v_cvt_i32_f32_e32 v120, v120
	v_cvt_i32_f32_e32 v121, v121
	v_perm_b32 v118, v119, v118, s16
	v_perm_b32 v120, v121, v120, s17
	v_or_b32_e32 v110, v118, v120
	v_lshlrev_b32_e32 v118, 16, v20
	v_and_b32_e32 v119, 0xffff0000, v20
	v_lshlrev_b32_e32 v120, 16, v21
	v_and_b32_e32 v121, 0xffff0000, v21
	v_pk_mul_f32 v[118:119], v[126:127], v[118:119]
	v_pk_mul_f32 v[120:121], v[126:127], v[120:121]
	v_rndne_f32_e32 v118, v118
	v_rndne_f32_e32 v119, v119
	v_rndne_f32_e32 v120, v120
	v_rndne_f32_e32 v121, v121
	v_cvt_i32_f32_e32 v118, v118
	v_cvt_i32_f32_e32 v119, v119
	v_cvt_i32_f32_e32 v120, v120
	v_cvt_i32_f32_e32 v121, v121
	v_perm_b32 v118, v119, v118, s16
	v_perm_b32 v120, v121, v120, s17
	v_or_b32_e32 v111, v118, v120
	global_store_dwordx2 v136, v[110:111], s[10:11] offset:2048
	s_waitcnt vmcnt(43)
	v_lshlrev_b32_e32 v118, 16, v22
	v_and_b32_e32 v119, 0xffff0000, v22
	v_lshlrev_b32_e32 v120, 16, v23
	v_and_b32_e32 v121, 0xffff0000, v23
	v_pk_mul_f32 v[118:119], v[126:127], v[118:119]
	v_pk_mul_f32 v[120:121], v[126:127], v[120:121]
	v_rndne_f32_e32 v118, v118
	v_rndne_f32_e32 v119, v119
	v_rndne_f32_e32 v120, v120
	v_rndne_f32_e32 v121, v121
	v_cvt_i32_f32_e32 v118, v118
	v_cvt_i32_f32_e32 v119, v119
	v_cvt_i32_f32_e32 v120, v120
	v_cvt_i32_f32_e32 v121, v121
	v_perm_b32 v118, v119, v118, s16
	v_perm_b32 v120, v121, v120, s17
	v_or_b32_e32 v112, v118, v120
	v_lshlrev_b32_e32 v118, 16, v24
	v_and_b32_e32 v119, 0xffff0000, v24
	v_lshlrev_b32_e32 v120, 16, v25
	v_and_b32_e32 v121, 0xffff0000, v25
	v_pk_mul_f32 v[118:119], v[126:127], v[118:119]
	v_pk_mul_f32 v[120:121], v[126:127], v[120:121]
	v_rndne_f32_e32 v118, v118
	v_rndne_f32_e32 v119, v119
	v_rndne_f32_e32 v120, v120
	v_rndne_f32_e32 v121, v121
	v_cvt_i32_f32_e32 v118, v118
	v_cvt_i32_f32_e32 v119, v119
	v_cvt_i32_f32_e32 v120, v120
	v_cvt_i32_f32_e32 v121, v121
	v_perm_b32 v118, v119, v118, s16
	v_perm_b32 v120, v121, v120, s17
	v_or_b32_e32 v113, v118, v120
	global_store_dwordx2 v136, v[112:113], s[10:11] offset:2560
	s_waitcnt vmcnt(43)
	v_lshlrev_b32_e32 v118, 16, v26
	v_and_b32_e32 v119, 0xffff0000, v26
	v_lshlrev_b32_e32 v120, 16, v27
	v_and_b32_e32 v121, 0xffff0000, v27
	v_pk_mul_f32 v[118:119], v[126:127], v[118:119]
	v_pk_mul_f32 v[120:121], v[126:127], v[120:121]
	v_rndne_f32_e32 v118, v118
	v_rndne_f32_e32 v119, v119
	v_rndne_f32_e32 v120, v120
	v_rndne_f32_e32 v121, v121
	v_cvt_i32_f32_e32 v118, v118
	v_cvt_i32_f32_e32 v119, v119
	v_cvt_i32_f32_e32 v120, v120
	v_cvt_i32_f32_e32 v121, v121
	v_perm_b32 v118, v119, v118, s16
	v_perm_b32 v120, v121, v120, s17
	v_or_b32_e32 v114, v118, v120
	v_lshlrev_b32_e32 v118, 16, v28
	v_and_b32_e32 v119, 0xffff0000, v28
	v_lshlrev_b32_e32 v120, 16, v29
	v_and_b32_e32 v121, 0xffff0000, v29
	v_pk_mul_f32 v[118:119], v[126:127], v[118:119]
	v_pk_mul_f32 v[120:121], v[126:127], v[120:121]
	v_rndne_f32_e32 v118, v118
	v_rndne_f32_e32 v119, v119
	v_rndne_f32_e32 v120, v120
	v_rndne_f32_e32 v121, v121
	v_cvt_i32_f32_e32 v118, v118
	v_cvt_i32_f32_e32 v119, v119
	v_cvt_i32_f32_e32 v120, v120
	v_cvt_i32_f32_e32 v121, v121
	v_perm_b32 v118, v119, v118, s16
	v_perm_b32 v120, v121, v120, s17
	v_or_b32_e32 v115, v118, v120
	global_store_dwordx2 v136, v[114:115], s[10:11] offset:3072
	s_waitcnt vmcnt(43)
; __device__ __forceinline__ unsigned q8(float x) { return (unsigned)(int)__builtin_rintf(x) & 0xffu; }
; __device__ __forceinline__ void rows_bf16_to_i8(Frame& F, const bf16* XBp, const unsigned* rmax, unsigned* X8, float* sx, int pitch4 = D / 4) {
;     ...
;     if (m < M) { const v4u* src = (const v4u*)(XBp + (size_t)m * D) + lane; rb = rmax[m];
; #pragma unroll
;         for (int j = 0; j < 8; ++j) w[j] = src[64 * j]; }
;     for (; m < M; m += NGW) {
;         const int mn = m + NGW;
;         if (mn < M) { const v4u* src = (const v4u*)(XBp + (size_t)mn * D) + lane; rbn = rmax[mn];
; #pragma unroll
;             for (int j = 0; j < 8; ++j) wn[j] = src[64 * j]; }
;         const float mx = __builtin_bit_cast(float, rb), inv = mx > 0.f ? 127.0f / mx : 0.f;
;         v2u* dst = (v2u*)(X8 + (size_t)m * pitch4) + lane;
; #pragma unroll
;         for (int j = 0; j < 8; ++j) { v2u o;
;             o.x = q8(blo(w[j].x) * inv) | (q8(bhi(w[j].x) * inv) << 8) | (q8(blo(w[j].y) * inv) << 16) | (q8(bhi(w[j].y) * inv) << 24);
;             o.y = q8(blo(w[j].z) * inv) | (q8(bhi(w[j].z) * inv) << 8) | (q8(blo(w[j].w) * inv) << 16) | (q8(bhi(w[j].w) * inv) << 24);
;             dst[64 * j] = o; }
;         if (lane == 0) sx[m] = mx * (1.0f / 127.0f);
; #pragma unroll
;         for (int j = 0; j < 8; ++j) w[j] = wn[j];
;         rb = rbn;
;     }
; }
	v_lshlrev_b32_e32 v118, 16, v30
	v_and_b32_e32 v119, 0xffff0000, v30
	v_lshlrev_b32_e32 v120, 16, v31
	v_and_b32_e32 v121, 0xffff0000, v31
	v_pk_mul_f32 v[118:119], v[126:127], v[118:119]
	v_pk_mul_f32 v[120:121], v[126:127], v[120:121]
	v_rndne_f32_e32 v118, v118
	v_rndne_f32_e32 v119, v119
	v_rndne_f32_e32 v120, v120
	v_rndne_f32_e32 v121, v121
	v_cvt_i32_f32_e32 v118, v118
	v_cvt_i32_f32_e32 v119, v119
	v_cvt_i32_f32_e32 v120, v120
	v_cvt_i32_f32_e32 v121, v121
	v_perm_b32 v118, v119, v118, s16
	v_perm_b32 v120, v121, v120, s17
	v_or_b32_e32 v116, v118, v120
	v_lshlrev_b32_e32 v118, 16, v32
	v_and_b32_e32 v119, 0xffff0000, v32
	v_lshlrev_b32_e32 v120, 16, v33
	v_and_b32_e32 v121, 0xffff0000, v33
	v_pk_mul_f32 v[118:119], v[126:127], v[118:119]
	v_pk_mul_f32 v[120:121], v[126:127], v[120:121]
	v_rndne_f32_e32 v118, v118
	v_rndne_f32_e32 v119, v119
	v_rndne_f32_e32 v120, v120
	v_rndne_f32_e32 v121, v121
	v_cvt_i32_f32_e32 v118, v118
	v_cvt_i32_f32_e32 v119, v119
	v_cvt_i32_f32_e32 v120, v120
	v_cvt_i32_f32_e32 v121, v121
	v_perm_b32 v118, v119, v118, s16
	v_perm_b32 v120, v121, v120, s17
	v_or_b32_e32 v117, v118, v120
	global_store_dwordx2 v136, v[116:117], s[10:11] offset:3584
	s_mov_b64 exec, s[12:13]
	global_store_dword v137, v138, s[8:9]
	s_mov_b64 exec, -1
	s_add_u32 s10, s10, 0x800000
	s_addc_u32 s11, s11, 0
	s_add_u32 s8, s8, 0x2000
	s_addc_u32 s9, s9, 0
	global_load_dword v98, v137, s[6:7]
	global_load_dwordx4 v[2:5], v134, s[4:5] offset:0
	global_load_dwordx4 v[6:9], v134, s[4:5] offset:1024
	global_load_dwordx4 v[10:13], v134, s[4:5] offset:2048
	global_load_dwordx4 v[14:17], v134, s[4:5] offset:3072
	global_load_dwordx4 v[18:21], v135, s[4:5] offset:0
	global_load_dwordx4 v[22:25], v135, s[4:5] offset:1024
	global_load_dwordx4 v[26:29], v135, s[4:5] offset:2048
	global_load_dwordx4 v[30:33], v135, s[4:5] offset:3072
	s_add_u32 s4, s4, 0x1000000
	s_addc_u32 s5, s5, 0
	s_add_u32 s6, s6, 0x2000
	s_addc_u32 s7, s7, 0
	s_waitcnt vmcnt(44)
	v_div_scale_f32 v128, s[14:15], v99, v99, s3
	v_rcp_f32_e32 v129, v128
	v_div_scale_f32 v130, vcc, s3, v99, s3
	v_fma_f32 v131, -v128, v129, 1.0
	v_fmac_f32_e32 v129, v131, v129
	v_mul_f32_e32 v131, v130, v129
	v_fma_f32 v132, -v128, v131, v130
	v_fmac_f32_e32 v131, v132, v129
	v_fma_f32 v128, -v128, v131, v130
	v_div_fmas_f32 v128, v128, v129, v131
	v_div_fixup_f32 v128, v128, v99, s3
	v_cmp_lt_f32_e32 vcc, 0, v99
	v_mul_f32_e32 v138, 0x3c010204, v99
	v_cndmask_b32_e32 v126, 0, v128, vcc
	v_mov_b32_e32 v127, v126
	s_waitcnt vmcnt(43)
	v_lshlrev_b32_e32 v118, 16, v34
	v_and_b32_e32 v119, 0xffff0000, v34
	v_lshlrev_b32_e32 v120, 16, v35
	v_and_b32_e32 v121, 0xffff0000, v35
	v_pk_mul_f32 v[118:119], v[126:127], v[118:119]
	v_pk_mul_f32 v[120:121], v[126:127], v[120:121]
	v_rndne_f32_e32 v118, v118
	v_rndne_f32_e32 v119, v119
	v_rndne_f32_e32 v120, v120
	v_rndne_f32_e32 v121, v121
	v_cvt_i32_f32_e32 v118, v118
	v_cvt_i32_f32_e32 v119, v119
	v_cvt_i32_f32_e32 v120, v120
	v_cvt_i32_f32_e32 v121, v121
	v_perm_b32 v118, v119, v118, s16
	v_perm_b32 v120, v121, v120, s17
	v_or_b32_e32 v102, v118, v120
	v_lshlrev_b32_e32 v118, 16, v36
	v_and_b32_e32 v119, 0xffff0000, v36
	v_lshlrev_b32_e32 v120, 16, v37
	v_and_b32_e32 v121, 0xffff0000, v37
	v_pk_mul_f32 v[118:119], v[126:127], v[118:119]
	v_pk_mul_f32 v[120:121], v[126:127], v[120:121]
	v_rndne_f32_e32 v118, v118
	v_rndne_f32_e32 v119, v119
	v_rndne_f32_e32 v120, v120
	v_rndne_f32_e32 v121, v121
	v_cvt_i32_f32_e32 v118, v118
	v_cvt_i32_f32_e32 v119, v119
	v_cvt_i32_f32_e32 v120, v120
	v_cvt_i32_f32_e32 v121, v121
	v_perm_b32 v118, v119, v118, s16
	v_perm_b32 v120, v121, v120, s17
	v_or_b32_e32 v103, v118, v120
	global_store_dwordx2 v136, v[102:103], s[10:11] offset:0
	s_waitcnt vmcnt(43)
	v_lshlrev_b32_e32 v118, 16, v38
	v_and_b32_e32 v119, 0xffff0000, v38
	v_lshlrev_b32_e32 v120, 16, v39
	v_and_b32_e32 v121, 0xffff0000, v39
	v_pk_mul_f32 v[118:119], v[126:127], v[118:119]
	v_pk_mul_f32 v[120:121], v[126:127], v[120:121]
	v_rndne_f32_e32 v118, v118
	v_rndne_f32_e32 v119, v119
	v_rndne_f32_e32 v120, v120
	v_rndne_f32_e32 v121, v121
	v_cvt_i32_f32_e32 v118, v118
	v_cvt_i32_f32_e32 v119, v119
	v_cvt_i32_f32_e32 v120, v120
	v_cvt_i32_f32_e32 v121, v121
	v_perm_b32 v118, v119, v118, s16
	v_perm_b32 v120, v121, v120, s17
	v_or_b32_e32 v104, v118, v120
	v_lshlrev_b32_e32 v118, 16, v40
	v_and_b32_e32 v119, 0xffff0000, v40
	v_lshlrev_b32_e32 v120, 16, v41
	v_and_b32_e32 v121, 0xffff0000, v41
	v_pk_mul_f32 v[118:119], v[126:127], v[118:119]
	v_pk_mul_f32 v[120:121], v[126:127], v[120:121]
	v_rndne_f32_e32 v118, v118
	v_rndne_f32_e32 v119, v119
	v_rndne_f32_e32 v120, v120
	v_rndne_f32_e32 v121, v121
	v_cvt_i32_f32_e32 v118, v118
	v_cvt_i32_f32_e32 v119, v119
	v_cvt_i32_f32_e32 v120, v120
	v_cvt_i32_f32_e32 v121, v121
	v_perm_b32 v118, v119, v118, s16
	v_perm_b32 v120, v121, v120, s17
	v_or_b32_e32 v105, v118, v120
	global_store_dwordx2 v136, v[104:105], s[10:11] offset:512
	s_waitcnt vmcnt(43)
	v_lshlrev_b32_e32 v118, 16, v42
	v_and_b32_e32 v119, 0xffff0000, v42
	v_lshlrev_b32_e32 v120, 16, v43
	v_and_b32_e32 v121, 0xffff0000, v43
	v_pk_mul_f32 v[118:119], v[126:127], v[118:119]
	v_pk_mul_f32 v[120:121], v[126:127], v[120:121]
	v_rndne_f32_e32 v118, v118
	v_rndne_f32_e32 v119, v119
	v_rndne_f32_e32 v120, v120
	v_rndne_f32_e32 v121, v121
	v_cvt_i32_f32_e32 v118, v118
	v_cvt_i32_f32_e32 v119, v119
	v_cvt_i32_f32_e32 v120, v120
	v_cvt_i32_f32_e32 v121, v121
	v_perm_b32 v118, v119, v118, s16
	v_perm_b32 v120, v121, v120, s17
	v_or_b32_e32 v106, v118, v120
	v_lshlrev_b32_e32 v118, 16, v44
	v_and_b32_e32 v119, 0xffff0000, v44
	v_lshlrev_b32_e32 v120, 16, v45
	v_and_b32_e32 v121, 0xffff0000, v45
	v_pk_mul_f32 v[118:119], v[126:127], v[118:119]
	v_pk_mul_f32 v[120:121], v[126:127], v[120:121]
	v_rndne_f32_e32 v118, v118
	v_rndne_f32_e32 v119, v119
	v_rndne_f32_e32 v120, v120
	v_rndne_f32_e32 v121, v121
	v_cvt_i32_f32_e32 v118, v118
	v_cvt_i32_f32_e32 v119, v119
	v_cvt_i32_f32_e32 v120, v120
	v_cvt_i32_f32_e32 v121, v121
	v_perm_b32 v118, v119, v118, s16
	v_perm_b32 v120, v121, v120, s17
	v_or_b32_e32 v107, v118, v120
	global_store_dwordx2 v136, v[106:107], s[10:11] offset:1024
	s_waitcnt vmcnt(43)
; __device__ __forceinline__ unsigned q8(float x) { return (unsigned)(int)__builtin_rintf(x) & 0xffu; }
; __device__ __forceinline__ void rows_bf16_to_i8(Frame& F, const bf16* XBp, const unsigned* rmax, unsigned* X8, float* sx, int pitch4 = D / 4) {
;     ...
;         const float mx = __builtin_bit_cast(float, rb), inv = mx > 0.f ? 127.0f / mx : 0.f;
;         v2u* dst = (v2u*)(X8 + (size_t)m * pitch4) + lane;
; #pragma unroll
;         for (int j = 0; j < 8; ++j) { v2u o;
;             o.x = q8(blo(w[j].x) * inv) | (q8(bhi(w[j].x) * inv) << 8) | (q8(blo(w[j].y) * inv) << 16) | (q8(bhi(w[j].y) * inv) << 24);
;             o.y = q8(blo(w[j].z) * inv) | (q8(bhi(w[j].z) * inv) << 8) | (q8(blo(w[j].w) * inv) << 16) | (q8(bhi(w[j].w) * inv) << 24);
;             dst[64 * j] = o; }
	v_lshlrev_b32_e32 v118, 16, v46
	v_and_b32_e32 v119, 0xffff0000, v46
	v_lshlrev_b32_e32 v120, 16, v47
	v_and_b32_e32 v121, 0xffff0000, v47
	v_pk_mul_f32 v[118:119], v[126:127], v[118:119]
	v_pk_mul_f32 v[120:121], v[126:127], v[120:121]
	v_rndne_f32_e32 v118, v118
	v_rndne_f32_e32 v119, v119
	v_rndne_f32_e32 v120, v120
	v_rndne_f32_e32 v121, v121
	v_cvt_i32_f32_e32 v118, v118
	v_cvt_i32_f32_e32 v119, v119
	v_cvt_i32_f32_e32 v120, v120
	v_cvt_i32_f32_e32 v121, v121
	v_perm_b32 v118, v119, v118, s16
	v_perm_b32 v120, v121, v120, s17
	v_or_b32_e32 v108, v118, v120
	v_lshlrev_b32_e32 v118, 16, v48
	v_and_b32_e32 v119, 0xffff0000, v48
	v_lshlrev_b32_e32 v120, 16, v49
	v_and_b32_e32 v121, 0xffff0000, v49
	v_pk_mul_f32 v[118:119], v[126:127], v[118:119]
	v_pk_mul_f32 v[120:121], v[126:127], v[120:121]
	v_rndne_f32_e32 v118, v118
	v_rndne_f32_e32 v119, v119
	v_rndne_f32_e32 v120, v120
	v_rndne_f32_e32 v121, v121
	v_cvt_i32_f32_e32 v118, v118
	v_cvt_i32_f32_e32 v119, v119
	v_cvt_i32_f32_e32 v120, v120
	v_cvt_i32_f32_e32 v121, v121
	v_perm_b32 v118, v119, v118, s16
	v_perm_b32 v120, v121, v120, s17
	v_or_b32_e32 v109, v118, v120
	global_store_dwordx2 v136, v[108:109], s[10:11] offset:1536
	s_waitcnt vmcnt(43)
	v_lshlrev_b32_e32 v118, 16, v50
	v_and_b32_e32 v119, 0xffff0000, v50
	v_lshlrev_b32_e32 v120, 16, v51
	v_and_b32_e32 v121, 0xffff0000, v51
	v_pk_mul_f32 v[118:119], v[126:127], v[118:119]
	v_pk_mul_f32 v[120:121], v[126:127], v[120:121]
	v_rndne_f32_e32 v118, v118
	v_rndne_f32_e32 v119, v119
	v_rndne_f32_e32 v120, v120
	v_rndne_f32_e32 v121, v121
	v_cvt_i32_f32_e32 v118, v118
	v_cvt_i32_f32_e32 v119, v119
	v_cvt_i32_f32_e32 v120, v120
	v_cvt_i32_f32_e32 v121, v121
	v_perm_b32 v118, v119, v118, s16
	v_perm_b32 v120, v121, v120, s17
	v_or_b32_e32 v110, v118, v120
	v_lshlrev_b32_e32 v118, 16, v52
	v_and_b32_e32 v119, 0xffff0000, v52
	v_lshlrev_b32_e32 v120, 16, v53
	v_and_b32_e32 v121, 0xffff0000, v53
	v_pk_mul_f32 v[118:119], v[126:127], v[118:119]
	v_pk_mul_f32 v[120:121], v[126:127], v[120:121]
	v_rndne_f32_e32 v118, v118
	v_rndne_f32_e32 v119, v119
	v_rndne_f32_e32 v120, v120
	v_rndne_f32_e32 v121, v121
	v_cvt_i32_f32_e32 v118, v118
	v_cvt_i32_f32_e32 v119, v119
	v_cvt_i32_f32_e32 v120, v120
	v_cvt_i32_f32_e32 v121, v121
	v_perm_b32 v118, v119, v118, s16
	v_perm_b32 v120, v121, v120, s17
	v_or_b32_e32 v111, v118, v120
	global_store_dwordx2 v136, v[110:111], s[10:11] offset:2048
	s_waitcnt vmcnt(43)
	v_lshlrev_b32_e32 v118, 16, v54
	v_and_b32_e32 v119, 0xffff0000, v54
	v_lshlrev_b32_e32 v120, 16, v55
	v_and_b32_e32 v121, 0xffff0000, v55
	v_pk_mul_f32 v[118:119], v[126:127], v[118:119]
	v_pk_mul_f32 v[120:121], v[126:127], v[120:121]
	v_rndne_f32_e32 v118, v118
	v_rndne_f32_e32 v119, v119
	v_rndne_f32_e32 v120, v120
	v_rndne_f32_e32 v121, v121
	v_cvt_i32_f32_e32 v118, v118
	v_cvt_i32_f32_e32 v119, v119
	v_cvt_i32_f32_e32 v120, v120
	v_cvt_i32_f32_e32 v121, v121
	v_perm_b32 v118, v119, v118, s16
	v_perm_b32 v120, v121, v120, s17
	v_or_b32_e32 v112, v118, v120
	v_lshlrev_b32_e32 v118, 16, v56
	v_and_b32_e32 v119, 0xffff0000, v56
	v_lshlrev_b32_e32 v120, 16, v57
	v_and_b32_e32 v121, 0xffff0000, v57
	v_pk_mul_f32 v[118:119], v[126:127], v[118:119]
	v_pk_mul_f32 v[120:121], v[126:127], v[120:121]
	v_rndne_f32_e32 v118, v118
	v_rndne_f32_e32 v119, v119
	v_rndne_f32_e32 v120, v120
	v_rndne_f32_e32 v121, v121
	v_cvt_i32_f32_e32 v118, v118
	v_cvt_i32_f32_e32 v119, v119
	v_cvt_i32_f32_e32 v120, v120
	v_cvt_i32_f32_e32 v121, v121
	v_perm_b32 v118, v119, v118, s16
	v_perm_b32 v120, v121, v120, s17
	v_or_b32_e32 v113, v118, v120
	global_store_dwordx2 v136, v[112:113], s[10:11] offset:2560
	s_waitcnt vmcnt(43)
	v_lshlrev_b32_e32 v118, 16, v58
	v_and_b32_e32 v119, 0xffff0000, v58
	v_lshlrev_b32_e32 v120, 16, v59
	v_and_b32_e32 v121, 0xffff0000, v59
	v_pk_mul_f32 v[118:119], v[126:127], v[118:119]
	v_pk_mul_f32 v[120:121], v[126:127], v[120:121]
	v_rndne_f32_e32 v118, v118
	v_rndne_f32_e32 v119, v119
	v_rndne_f32_e32 v120, v120
	v_rndne_f32_e32 v121, v121
	v_cvt_i32_f32_e32 v118, v118
	v_cvt_i32_f32_e32 v119, v119
	v_cvt_i32_f32_e32 v120, v120
	v_cvt_i32_f32_e32 v121, v121
	v_perm_b32 v118, v119, v118, s16
	v_perm_b32 v120, v121, v120, s17
	v_or_b32_e32 v114, v118, v120
	v_lshlrev_b32_e32 v118, 16, v60
	v_and_b32_e32 v119, 0xffff0000, v60
	v_lshlrev_b32_e32 v120, 16, v61
	v_and_b32_e32 v121, 0xffff0000, v61
	v_pk_mul_f32 v[118:119], v[126:127], v[118:119]
	v_pk_mul_f32 v[120:121], v[126:127], v[120:121]
	v_rndne_f32_e32 v118, v118
	v_rndne_f32_e32 v119, v119
	v_rndne_f32_e32 v120, v120
	v_rndne_f32_e32 v121, v121
	v_cvt_i32_f32_e32 v118, v118
	v_cvt_i32_f32_e32 v119, v119
	v_cvt_i32_f32_e32 v120, v120
	v_cvt_i32_f32_e32 v121, v121
	v_perm_b32 v118, v119, v118, s16
	v_perm_b32 v120, v121, v120, s17
	v_or_b32_e32 v115, v118, v120
	global_store_dwordx2 v136, v[114:115], s[10:11] offset:3072
	s_waitcnt vmcnt(43)
; __device__ __forceinline__ unsigned q8(float x) { return (unsigned)(int)__builtin_rintf(x) & 0xffu; }
; __device__ __forceinline__ void rows_bf16_to_i8(Frame& F, const bf16* XBp, const unsigned* rmax, unsigned* X8, float* sx, int pitch4 = D / 4) {
;     ...
;     if (m < M) { const v4u* src = (const v4u*)(XBp + (size_t)m * D) + lane; rb = rmax[m];
; #pragma unroll
;         for (int j = 0; j < 8; ++j) w[j] = src[64 * j]; }
;     for (; m < M; m += NGW) {
;         const int mn = m + NGW;
;         if (mn < M) { const v4u* src = (const v4u*)(XBp + (size_t)mn * D) + lane; rbn = rmax[mn];
; #pragma unroll
;             for (int j = 0; j < 8; ++j) wn[j] = src[64 * j]; }
;         const float mx = __builtin_bit_cast(float, rb), inv = mx > 0.f ? 127.0f / mx : 0.f;
;         v2u* dst = (v2u*)(X8 + (size_t)m * pitch4) + lane;
; #pragma unroll
;         for (int j = 0; j < 8; ++j) { v2u o;
;             o.x = q8(blo(w[j].x) * inv) | (q8(bhi(w[j].x) * inv) << 8) | (q8(blo(w[j].y) * inv) << 16) | (q8(bhi(w[j].y) * inv) << 24);
;             o.y = q8(blo(w[j].z) * inv) | (q8(bhi(w[j].z) * inv) << 8) | (q8(blo(w[j].w) * inv) << 16) | (q8(bhi(w[j].w) * inv) << 24);
;             dst[64 * j] = o; }
;         if (lane == 0) sx[m] = mx * (1.0f / 127.0f);
; #pragma unroll
;         for (int j = 0; j < 8; ++j) w[j] = wn[j];
;         rb = rbn;
;     }
; }
	v_lshlrev_b32_e32 v118, 16, v62
	v_and_b32_e32 v119, 0xffff0000, v62
	v_lshlrev_b32_e32 v120, 16, v63
	v_and_b32_e32 v121, 0xffff0000, v63
	v_pk_mul_f32 v[118:119], v[126:127], v[118:119]
	v_pk_mul_f32 v[120:121], v[126:127], v[120:121]
	v_rndne_f32_e32 v118, v118
	v_rndne_f32_e32 v119, v119
	v_rndne_f32_e32 v120, v120
	v_rndne_f32_e32 v121, v121
	v_cvt_i32_f32_e32 v118, v118
	v_cvt_i32_f32_e32 v119, v119
	v_cvt_i32_f32_e32 v120, v120
	v_cvt_i32_f32_e32 v121, v121
	v_perm_b32 v118, v119, v118, s16
	v_perm_b32 v120, v121, v120, s17
	v_or_b32_e32 v116, v118, v120
	v_lshlrev_b32_e32 v118, 16, v64
	v_and_b32_e32 v119, 0xffff0000, v64
	v_lshlrev_b32_e32 v120, 16, v65
	v_and_b32_e32 v121, 0xffff0000, v65
	v_pk_mul_f32 v[118:119], v[126:127], v[118:119]
	v_pk_mul_f32 v[120:121], v[126:127], v[120:121]
	v_rndne_f32_e32 v118, v118
	v_rndne_f32_e32 v119, v119
	v_rndne_f32_e32 v120, v120
	v_rndne_f32_e32 v121, v121
	v_cvt_i32_f32_e32 v118, v118
	v_cvt_i32_f32_e32 v119, v119
	v_cvt_i32_f32_e32 v120, v120
	v_cvt_i32_f32_e32 v121, v121
	v_perm_b32 v118, v119, v118, s16
	v_perm_b32 v120, v121, v120, s17
	v_or_b32_e32 v117, v118, v120
	global_store_dwordx2 v136, v[116:117], s[10:11] offset:3584
	s_mov_b64 exec, s[12:13]
	global_store_dword v137, v138, s[8:9]
	s_mov_b64 exec, -1
	s_add_u32 s10, s10, 0x800000
	s_addc_u32 s11, s11, 0
	s_add_u32 s8, s8, 0x2000
	s_addc_u32 s9, s9, 0
	global_load_dword v99, v137, s[6:7]
	global_load_dwordx4 v[34:37], v134, s[4:5] offset:0
	global_load_dwordx4 v[38:41], v134, s[4:5] offset:1024
	global_load_dwordx4 v[42:45], v134, s[4:5] offset:2048
	global_load_dwordx4 v[46:49], v134, s[4:5] offset:3072
	global_load_dwordx4 v[50:53], v135, s[4:5] offset:0
	global_load_dwordx4 v[54:57], v135, s[4:5] offset:1024
	global_load_dwordx4 v[58:61], v135, s[4:5] offset:2048
	global_load_dwordx4 v[62:65], v135, s[4:5] offset:3072
	s_add_u32 s4, s4, 0x1000000
	s_addc_u32 s5, s5, 0
	s_add_u32 s6, s6, 0x2000
	s_addc_u32 s7, s7, 0
	s_waitcnt vmcnt(44)
	v_div_scale_f32 v128, s[14:15], v100, v100, s3
	v_rcp_f32_e32 v129, v128
	v_div_scale_f32 v130, vcc, s3, v100, s3
	v_fma_f32 v131, -v128, v129, 1.0
	v_fmac_f32_e32 v129, v131, v129
	v_mul_f32_e32 v131, v130, v129
	v_fma_f32 v132, -v128, v131, v130
	v_fmac_f32_e32 v131, v132, v129
	v_fma_f32 v128, -v128, v131, v130
	v_div_fmas_f32 v128, v128, v129, v131
	v_div_fixup_f32 v128, v128, v100, s3
	v_cmp_lt_f32_e32 vcc, 0, v100
	v_mul_f32_e32 v138, 0x3c010204, v100
	v_cndmask_b32_e32 v126, 0, v128, vcc
	v_mov_b32_e32 v127, v126
	s_waitcnt vmcnt(43)
	v_lshlrev_b32_e32 v118, 16, v66
	v_and_b32_e32 v119, 0xffff0000, v66
	v_lshlrev_b32_e32 v120, 16, v67
	v_and_b32_e32 v121, 0xffff0000, v67
	v_pk_mul_f32 v[118:119], v[126:127], v[118:119]
	v_pk_mul_f32 v[120:121], v[126:127], v[120:121]
	v_rndne_f32_e32 v118, v118
	v_rndne_f32_e32 v119, v119
	v_rndne_f32_e32 v120, v120
	v_rndne_f32_e32 v121, v121
	v_cvt_i32_f32_e32 v118, v118
	v_cvt_i32_f32_e32 v119, v119
	v_cvt_i32_f32_e32 v120, v120
	v_cvt_i32_f32_e32 v121, v121
	v_perm_b32 v118, v119, v118, s16
	v_perm_b32 v120, v121, v120, s17
	v_or_b32_e32 v102, v118, v120
	v_lshlrev_b32_e32 v118, 16, v68
	v_and_b32_e32 v119, 0xffff0000, v68
	v_lshlrev_b32_e32 v120, 16, v69
	v_and_b32_e32 v121, 0xffff0000, v69
	v_pk_mul_f32 v[118:119], v[126:127], v[118:119]
	v_pk_mul_f32 v[120:121], v[126:127], v[120:121]
	v_rndne_f32_e32 v118, v118
	v_rndne_f32_e32 v119, v119
	v_rndne_f32_e32 v120, v120
	v_rndne_f32_e32 v121, v121
	v_cvt_i32_f32_e32 v118, v118
	v_cvt_i32_f32_e32 v119, v119
	v_cvt_i32_f32_e32 v120, v120
	v_cvt_i32_f32_e32 v121, v121
	v_perm_b32 v118, v119, v118, s16
	v_perm_b32 v120, v121, v120, s17
	v_or_b32_e32 v103, v118, v120
	global_store_dwordx2 v136, v[102:103], s[10:11] offset:0
	s_waitcnt vmcnt(43)
	v_lshlrev_b32_e32 v118, 16, v70
	v_and_b32_e32 v119, 0xffff0000, v70
	v_lshlrev_b32_e32 v120, 16, v71
	v_and_b32_e32 v121, 0xffff0000, v71
	v_pk_mul_f32 v[118:119], v[126:127], v[118:119]
	v_pk_mul_f32 v[120:121], v[126:127], v[120:121]
	v_rndne_f32_e32 v118, v118
	v_rndne_f32_e32 v119, v119
	v_rndne_f32_e32 v120, v120
	v_rndne_f32_e32 v121, v121
	v_cvt_i32_f32_e32 v118, v118
	v_cvt_i32_f32_e32 v119, v119
	v_cvt_i32_f32_e32 v120, v120
	v_cvt_i32_f32_e32 v121, v121
	v_perm_b32 v118, v119, v118, s16
	v_perm_b32 v120, v121, v120, s17
	v_or_b32_e32 v104, v118, v120
	v_lshlrev_b32_e32 v118, 16, v72
	v_and_b32_e32 v119, 0xffff0000, v72
	v_lshlrev_b32_e32 v120, 16, v73
	v_and_b32_e32 v121, 0xffff0000, v73
	v_pk_mul_f32 v[118:119], v[126:127], v[118:119]
	v_pk_mul_f32 v[120:121], v[126:127], v[120:121]
	v_rndne_f32_e32 v118, v118
	v_rndne_f32_e32 v119, v119
	v_rndne_f32_e32 v120, v120
	v_rndne_f32_e32 v121, v121
	v_cvt_i32_f32_e32 v118, v118
	v_cvt_i32_f32_e32 v119, v119
	v_cvt_i32_f32_e32 v120, v120
	v_cvt_i32_f32_e32 v121, v121
	v_perm_b32 v118, v119, v118, s16
	v_perm_b32 v120, v121, v120, s17
	v_or_b32_e32 v105, v118, v120
	global_store_dwordx2 v136, v[104:105], s[10:11] offset:512
	s_waitcnt vmcnt(43)
	v_lshlrev_b32_e32 v118, 16, v74
	v_and_b32_e32 v119, 0xffff0000, v74
	v_lshlrev_b32_e32 v120, 16, v75
	v_and_b32_e32 v121, 0xffff0000, v75
	v_pk_mul_f32 v[118:119], v[126:127], v[118:119]
	v_pk_mul_f32 v[120:121], v[126:127], v[120:121]
	v_rndne_f32_e32 v118, v118
	v_rndne_f32_e32 v119, v119
	v_rndne_f32_e32 v120, v120
	v_rndne_f32_e32 v121, v121
	v_cvt_i32_f32_e32 v118, v118
	v_cvt_i32_f32_e32 v119, v119
	v_cvt_i32_f32_e32 v120, v120
	v_cvt_i32_f32_e32 v121, v121
	v_perm_b32 v118, v119, v118, s16
	v_perm_b32 v120, v121, v120, s17
	v_or_b32_e32 v106, v118, v120
	v_lshlrev_b32_e32 v118, 16, v76
	v_and_b32_e32 v119, 0xffff0000, v76
	v_lshlrev_b32_e32 v120, 16, v77
	v_and_b32_e32 v121, 0xffff0000, v77
	v_pk_mul_f32 v[118:119], v[126:127], v[118:119]
	v_pk_mul_f32 v[120:121], v[126:127], v[120:121]
	v_rndne_f32_e32 v118, v118
	v_rndne_f32_e32 v119, v119
	v_rndne_f32_e32 v120, v120
	v_rndne_f32_e32 v121, v121
	v_cvt_i32_f32_e32 v118, v118
	v_cvt_i32_f32_e32 v119, v119
	v_cvt_i32_f32_e32 v120, v120
	v_cvt_i32_f32_e32 v121, v121
	v_perm_b32 v118, v119, v118, s16
	v_perm_b32 v120, v121, v120, s17
	v_or_b32_e32 v107, v118, v120
	global_store_dwordx2 v136, v[106:107], s[10:11] offset:1024
	s_waitcnt vmcnt(43)
; __device__ __forceinline__ unsigned q8(float x) { return (unsigned)(int)__builtin_rintf(x) & 0xffu; }
; __device__ __forceinline__ void rows_bf16_to_i8(Frame& F, const bf16* XBp, const unsigned* rmax, unsigned* X8, float* sx, int pitch4 = D / 4) {
;     ...
;         const float mx = __builtin_bit_cast(float, rb), inv = mx > 0.f ? 127.0f / mx : 0.f;
;         v2u* dst = (v2u*)(X8 + (size_t)m * pitch4) + lane;
; #pragma unroll
;         for (int j = 0; j < 8; ++j) { v2u o;
;             o.x = q8(blo(w[j].x) * inv) | (q8(bhi(w[j].x) * inv) << 8) | (q8(blo(w[j].y) * inv) << 16) | (q8(bhi(w[j].y) * inv) << 24);
;             o.y = q8(blo(w[j].z) * inv) | (q8(bhi(w[j].z) * inv) << 8) | (q8(blo(w[j].w) * inv) << 16) | (q8(bhi(w[j].w) * inv) << 24);
;             dst[64 * j] = o; }
;         if (lane == 0) sx[m] = mx * (1.0f / 127.0f);
; #pragma unroll
;         for (int j = 0; j < 8; ++j) w[j] = wn[j];
;         rb = rbn;
;     }
; }
	v_lshlrev_b32_e32 v118, 16, v78
	v_and_b32_e32 v119, 0xffff0000, v78
	v_lshlrev_b32_e32 v120, 16, v79
	v_and_b32_e32 v121, 0xffff0000, v79
	v_pk_mul_f32 v[118:119], v[126:127], v[118:119]
	v_pk_mul_f32 v[120:121], v[126:127], v[120:121]
	v_rndne_f32_e32 v118, v118
	v_rndne_f32_e32 v119, v119
	v_rndne_f32_e32 v120, v120
	v_rndne_f32_e32 v121, v121
	v_cvt_i32_f32_e32 v118, v118
	v_cvt_i32_f32_e32 v119, v119
	v_cvt_i32_f32_e32 v120, v120
	v_cvt_i32_f32_e32 v121, v121
	v_perm_b32 v118, v119, v118, s16
	v_perm_b32 v120, v121, v120, s17
	v_or_b32_e32 v108, v118, v120
	v_lshlrev_b32_e32 v118, 16, v80
	v_and_b32_e32 v119, 0xffff0000, v80
	v_lshlrev_b32_e32 v120, 16, v81
	v_and_b32_e32 v121, 0xffff0000, v81
	v_pk_mul_f32 v[118:119], v[126:127], v[118:119]
	v_pk_mul_f32 v[120:121], v[126:127], v[120:121]
	v_rndne_f32_e32 v118, v118
	v_rndne_f32_e32 v119, v119
	v_rndne_f32_e32 v120, v120
	v_rndne_f32_e32 v121, v121
	v_cvt_i32_f32_e32 v118, v118
	v_cvt_i32_f32_e32 v119, v119
	v_cvt_i32_f32_e32 v120, v120
	v_cvt_i32_f32_e32 v121, v121
	v_perm_b32 v118, v119, v118, s16
	v_perm_b32 v120, v121, v120, s17
	v_or_b32_e32 v109, v118, v120
	global_store_dwordx2 v136, v[108:109], s[10:11] offset:1536
	s_waitcnt vmcnt(43)
	v_lshlrev_b32_e32 v118, 16, v82
	v_and_b32_e32 v119, 0xffff0000, v82
	v_lshlrev_b32_e32 v120, 16, v83
	v_and_b32_e32 v121, 0xffff0000, v83
	v_pk_mul_f32 v[118:119], v[126:127], v[118:119]
	v_pk_mul_f32 v[120:121], v[126:127], v[120:121]
	v_rndne_f32_e32 v118, v118
	v_rndne_f32_e32 v119, v119
	v_rndne_f32_e32 v120, v120
	v_rndne_f32_e32 v121, v121
	v_cvt_i32_f32_e32 v118, v118
	v_cvt_i32_f32_e32 v119, v119
	v_cvt_i32_f32_e32 v120, v120
	v_cvt_i32_f32_e32 v121, v121
	v_perm_b32 v118, v119, v118, s16
	v_perm_b32 v120, v121, v120, s17
	v_or_b32_e32 v110, v118, v120
	v_lshlrev_b32_e32 v118, 16, v84
	v_and_b32_e32 v119, 0xffff0000, v84
	v_lshlrev_b32_e32 v120, 16, v85
	v_and_b32_e32 v121, 0xffff0000, v85
	v_pk_mul_f32 v[118:119], v[126:127], v[118:119]
	v_pk_mul_f32 v[120:121], v[126:127], v[120:121]
	v_rndne_f32_e32 v118, v118
	v_rndne_f32_e32 v119, v119
	v_rndne_f32_e32 v120, v120
	v_rndne_f32_e32 v121, v121
	v_cvt_i32_f32_e32 v118, v118
	v_cvt_i32_f32_e32 v119, v119
	v_cvt_i32_f32_e32 v120, v120
	v_cvt_i32_f32_e32 v121, v121
	v_perm_b32 v118, v119, v118, s16
	v_perm_b32 v120, v121, v120, s17
	v_or_b32_e32 v111, v118, v120
	global_store_dwordx2 v136, v[110:111], s[10:11] offset:2048
	s_waitcnt vmcnt(43)
	v_lshlrev_b32_e32 v118, 16, v86
	v_and_b32_e32 v119, 0xffff0000, v86
	v_lshlrev_b32_e32 v120, 16, v87
	v_and_b32_e32 v121, 0xffff0000, v87
	v_pk_mul_f32 v[118:119], v[126:127], v[118:119]
	v_pk_mul_f32 v[120:121], v[126:127], v[120:121]
	v_rndne_f32_e32 v118, v118
	v_rndne_f32_e32 v119, v119
	v_rndne_f32_e32 v120, v120
	v_rndne_f32_e32 v121, v121
	v_cvt_i32_f32_e32 v118, v118
	v_cvt_i32_f32_e32 v119, v119
	v_cvt_i32_f32_e32 v120, v120
	v_cvt_i32_f32_e32 v121, v121
	v_perm_b32 v118, v119, v118, s16
	v_perm_b32 v120, v121, v120, s17
	v_or_b32_e32 v112, v118, v120
	v_lshlrev_b32_e32 v118, 16, v88
	v_and_b32_e32 v119, 0xffff0000, v88
	v_lshlrev_b32_e32 v120, 16, v89
	v_and_b32_e32 v121, 0xffff0000, v89
	v_pk_mul_f32 v[118:119], v[126:127], v[118:119]
	v_pk_mul_f32 v[120:121], v[126:127], v[120:121]
	v_rndne_f32_e32 v118, v118
	v_rndne_f32_e32 v119, v119
	v_rndne_f32_e32 v120, v120
	v_rndne_f32_e32 v121, v121
	v_cvt_i32_f32_e32 v118, v118
	v_cvt_i32_f32_e32 v119, v119
	v_cvt_i32_f32_e32 v120, v120
	v_cvt_i32_f32_e32 v121, v121
	v_perm_b32 v118, v119, v118, s16
	v_perm_b32 v120, v121, v120, s17
	v_or_b32_e32 v113, v118, v120
	global_store_dwordx2 v136, v[112:113], s[10:11] offset:2560
	s_waitcnt vmcnt(43)
	v_lshlrev_b32_e32 v118, 16, v90
	v_and_b32_e32 v119, 0xffff0000, v90
	v_lshlrev_b32_e32 v120, 16, v91
	v_and_b32_e32 v121, 0xffff0000, v91
	v_pk_mul_f32 v[118:119], v[126:127], v[118:119]
	v_pk_mul_f32 v[120:121], v[126:127], v[120:121]
	v_rndne_f32_e32 v118, v118
	v_rndne_f32_e32 v119, v119
	v_rndne_f32_e32 v120, v120
	v_rndne_f32_e32 v121, v121
	v_cvt_i32_f32_e32 v118, v118
	v_cvt_i32_f32_e32 v119, v119
	v_cvt_i32_f32_e32 v120, v120
	v_cvt_i32_f32_e32 v121, v121
	v_perm_b32 v118, v119, v118, s16
	v_perm_b32 v120, v121, v120, s17
	v_or_b32_e32 v114, v118, v120
	v_lshlrev_b32_e32 v118, 16, v92
	v_and_b32_e32 v119, 0xffff0000, v92
	v_lshlrev_b32_e32 v120, 16, v93
	v_and_b32_e32 v121, 0xffff0000, v93
	v_pk_mul_f32 v[118:119], v[126:127], v[118:119]
	v_pk_mul_f32 v[120:121], v[126:127], v[120:121]
	v_rndne_f32_e32 v118, v118
	v_rndne_f32_e32 v119, v119
	v_rndne_f32_e32 v120, v120
	v_rndne_f32_e32 v121, v121
	v_cvt_i32_f32_e32 v118, v118
	v_cvt_i32_f32_e32 v119, v119
	v_cvt_i32_f32_e32 v120, v120
	v_cvt_i32_f32_e32 v121, v121
	v_perm_b32 v118, v119, v118, s16
	v_perm_b32 v120, v121, v120, s17
	v_or_b32_e32 v115, v118, v120
	global_store_dwordx2 v136, v[114:115], s[10:11] offset:3072
	s_waitcnt vmcnt(43)
	v_lshlrev_b32_e32 v118, 16, v94
	v_and_b32_e32 v119, 0xffff0000, v94
	v_lshlrev_b32_e32 v120, 16, v95
	v_and_b32_e32 v121, 0xffff0000, v95
	v_pk_mul_f32 v[118:119], v[126:127], v[118:119]
	v_pk_mul_f32 v[120:121], v[126:127], v[120:121]
	v_rndne_f32_e32 v118, v118
	v_rndne_f32_e32 v119, v119
	v_rndne_f32_e32 v120, v120
	v_rndne_f32_e32 v121, v121
	v_cvt_i32_f32_e32 v118, v118
	v_cvt_i32_f32_e32 v119, v119
	v_cvt_i32_f32_e32 v120, v120
	v_cvt_i32_f32_e32 v121, v121
	v_perm_b32 v118, v119, v118, s16
	v_perm_b32 v120, v121, v120, s17
	v_or_b32_e32 v116, v118, v120
	v_lshlrev_b32_e32 v118, 16, v96
	v_and_b32_e32 v119, 0xffff0000, v96
	v_lshlrev_b32_e32 v120, 16, v97
	v_and_b32_e32 v121, 0xffff0000, v97
	v_pk_mul_f32 v[118:119], v[126:127], v[118:119]
	v_pk_mul_f32 v[120:121], v[126:127], v[120:121]
	v_rndne_f32_e32 v118, v118
	v_rndne_f32_e32 v119, v119
	v_rndne_f32_e32 v120, v120
	v_rndne_f32_e32 v121, v121
	v_cvt_i32_f32_e32 v118, v118
	v_cvt_i32_f32_e32 v119, v119
	v_cvt_i32_f32_e32 v120, v120
	v_cvt_i32_f32_e32 v121, v121
	v_perm_b32 v118, v119, v118, s16
	v_perm_b32 v120, v121, v120, s17
	v_or_b32_e32 v117, v118, v120
	global_store_dwordx2 v136, v[116:117], s[10:11] offset:3584
	s_mov_b64 exec, s[12:13]
	global_store_dword v137, v138, s[8:9]
	s_mov_b64 exec, -1
	s_add_u32 s10, s10, 0x800000
	s_addc_u32 s11, s11, 0
	s_add_u32 s8, s8, 0x2000
	s_addc_u32 s9, s9, 0
	s_waitcnt vmcnt(35)
; __device__ __forceinline__ unsigned q8(float x) { return (unsigned)(int)__builtin_rintf(x) & 0xffu; }
; __device__ __forceinline__ void rows_bf16_to_i8(Frame& F, const bf16* XBp, const unsigned* rmax, unsigned* X8, float* sx, int pitch4 = D / 4) {
;     ...
;         const float mx = __builtin_bit_cast(float, rb), inv = mx > 0.f ? 127.0f / mx : 0.f;
;         v2u* dst = (v2u*)(X8 + (size_t)m * pitch4) + lane;
; #pragma unroll
;         for (int j = 0; j < 8; ++j) { v2u o;
;             o.x = q8(blo(w[j].x) * inv) | (q8(bhi(w[j].x) * inv) << 8) | (q8(blo(w[j].y) * inv) << 16) | (q8(bhi(w[j].y) * inv) << 24);
;             o.y = q8(blo(w[j].z) * inv) | (q8(bhi(w[j].z) * inv) << 8) | (q8(blo(w[j].w) * inv) << 16) | (q8(bhi(w[j].w) * inv) << 24);
;             dst[64 * j] = o; }
	v_div_scale_f32 v128, s[14:15], v98, v98, s3
	v_rcp_f32_e32 v129, v128
	v_div_scale_f32 v130, vcc, s3, v98, s3
	v_fma_f32 v131, -v128, v129, 1.0
	v_fmac_f32_e32 v129, v131, v129
	v_mul_f32_e32 v131, v130, v129
	v_fma_f32 v132, -v128, v131, v130
	v_fmac_f32_e32 v131, v132, v129
	v_fma_f32 v128, -v128, v131, v130
	v_div_fmas_f32 v128, v128, v129, v131
	v_div_fixup_f32 v128, v128, v98, s3
	v_cmp_lt_f32_e32 vcc, 0, v98
	v_mul_f32_e32 v138, 0x3c010204, v98
	v_cndmask_b32_e32 v126, 0, v128, vcc
	v_mov_b32_e32 v127, v126
	s_waitcnt vmcnt(34)
	v_lshlrev_b32_e32 v118, 16, v2
	v_and_b32_e32 v119, 0xffff0000, v2
	v_lshlrev_b32_e32 v120, 16, v3
	v_and_b32_e32 v121, 0xffff0000, v3
	v_pk_mul_f32 v[118:119], v[126:127], v[118:119]
	v_pk_mul_f32 v[120:121], v[126:127], v[120:121]
	v_rndne_f32_e32 v118, v118
	v_rndne_f32_e32 v119, v119
	v_rndne_f32_e32 v120, v120
	v_rndne_f32_e32 v121, v121
	v_cvt_i32_f32_e32 v118, v118
	v_cvt_i32_f32_e32 v119, v119
	v_cvt_i32_f32_e32 v120, v120
	v_cvt_i32_f32_e32 v121, v121
	v_perm_b32 v118, v119, v118, s16
	v_perm_b32 v120, v121, v120, s17
	v_or_b32_e32 v102, v118, v120
	v_lshlrev_b32_e32 v118, 16, v4
	v_and_b32_e32 v119, 0xffff0000, v4
	v_lshlrev_b32_e32 v120, 16, v5
	v_and_b32_e32 v121, 0xffff0000, v5
	v_pk_mul_f32 v[118:119], v[126:127], v[118:119]
	v_pk_mul_f32 v[120:121], v[126:127], v[120:121]
	v_rndne_f32_e32 v118, v118
	v_rndne_f32_e32 v119, v119
	v_rndne_f32_e32 v120, v120
	v_rndne_f32_e32 v121, v121
	v_cvt_i32_f32_e32 v118, v118
	v_cvt_i32_f32_e32 v119, v119
	v_cvt_i32_f32_e32 v120, v120
	v_cvt_i32_f32_e32 v121, v121
	v_perm_b32 v118, v119, v118, s16
	v_perm_b32 v120, v121, v120, s17
	v_or_b32_e32 v103, v118, v120
	global_store_dwordx2 v136, v[102:103], s[10:11] offset:0
	s_waitcnt vmcnt(34)
	v_lshlrev_b32_e32 v118, 16, v6
	v_and_b32_e32 v119, 0xffff0000, v6
	v_lshlrev_b32_e32 v120, 16, v7
	v_and_b32_e32 v121, 0xffff0000, v7
	v_pk_mul_f32 v[118:119], v[126:127], v[118:119]
	v_pk_mul_f32 v[120:121], v[126:127], v[120:121]
	v_rndne_f32_e32 v118, v118
	v_rndne_f32_e32 v119, v119
	v_rndne_f32_e32 v120, v120
	v_rndne_f32_e32 v121, v121
	v_cvt_i32_f32_e32 v118, v118
	v_cvt_i32_f32_e32 v119, v119
	v_cvt_i32_f32_e32 v120, v120
	v_cvt_i32_f32_e32 v121, v121
	v_perm_b32 v118, v119, v118, s16
	v_perm_b32 v120, v121, v120, s17
	v_or_b32_e32 v104, v118, v120
	v_lshlrev_b32_e32 v118, 16, v8
	v_and_b32_e32 v119, 0xffff0000, v8
	v_lshlrev_b32_e32 v120, 16, v9
	v_and_b32_e32 v121, 0xffff0000, v9
	v_pk_mul_f32 v[118:119], v[126:127], v[118:119]
	v_pk_mul_f32 v[120:121], v[126:127], v[120:121]
	v_rndne_f32_e32 v118, v118
	v_rndne_f32_e32 v119, v119
	v_rndne_f32_e32 v120, v120
	v_rndne_f32_e32 v121, v121
	v_cvt_i32_f32_e32 v118, v118
	v_cvt_i32_f32_e32 v119, v119
	v_cvt_i32_f32_e32 v120, v120
	v_cvt_i32_f32_e32 v121, v121
	v_perm_b32 v118, v119, v118, s16
	v_perm_b32 v120, v121, v120, s17
	v_or_b32_e32 v105, v118, v120
	global_store_dwordx2 v136, v[104:105], s[10:11] offset:512
	s_waitcnt vmcnt(34)
	v_lshlrev_b32_e32 v118, 16, v10
	v_and_b32_e32 v119, 0xffff0000, v10
	v_lshlrev_b32_e32 v120, 16, v11
	v_and_b32_e32 v121, 0xffff0000, v11
	v_pk_mul_f32 v[118:119], v[126:127], v[118:119]
	v_pk_mul_f32 v[120:121], v[126:127], v[120:121]
	v_rndne_f32_e32 v118, v118
	v_rndne_f32_e32 v119, v119
	v_rndne_f32_e32 v120, v120
	v_rndne_f32_e32 v121, v121
	v_cvt_i32_f32_e32 v118, v118
	v_cvt_i32_f32_e32 v119, v119
	v_cvt_i32_f32_e32 v120, v120
	v_cvt_i32_f32_e32 v121, v121
	v_perm_b32 v118, v119, v118, s16
	v_perm_b32 v120, v121, v120, s17
	v_or_b32_e32 v106, v118, v120
	v_lshlrev_b32_e32 v118, 16, v12
	v_and_b32_e32 v119, 0xffff0000, v12
	v_lshlrev_b32_e32 v120, 16, v13
	v_and_b32_e32 v121, 0xffff0000, v13
	v_pk_mul_f32 v[118:119], v[126:127], v[118:119]
	v_pk_mul_f32 v[120:121], v[126:127], v[120:121]
	v_rndne_f32_e32 v118, v118
	v_rndne_f32_e32 v119, v119
	v_rndne_f32_e32 v120, v120
	v_rndne_f32_e32 v121, v121
	v_cvt_i32_f32_e32 v118, v118
	v_cvt_i32_f32_e32 v119, v119
	v_cvt_i32_f32_e32 v120, v120
	v_cvt_i32_f32_e32 v121, v121
	v_perm_b32 v118, v119, v118, s16
	v_perm_b32 v120, v121, v120, s17
	v_or_b32_e32 v107, v118, v120
	global_store_dwordx2 v136, v[106:107], s[10:11] offset:1024
	s_waitcnt vmcnt(34)
	v_lshlrev_b32_e32 v118, 16, v14
	v_and_b32_e32 v119, 0xffff0000, v14
	v_lshlrev_b32_e32 v120, 16, v15
	v_and_b32_e32 v121, 0xffff0000, v15
	v_pk_mul_f32 v[118:119], v[126:127], v[118:119]
	v_pk_mul_f32 v[120:121], v[126:127], v[120:121]
	v_rndne_f32_e32 v118, v118
	v_rndne_f32_e32 v119, v119
	v_rndne_f32_e32 v120, v120
	v_rndne_f32_e32 v121, v121
	v_cvt_i32_f32_e32 v118, v118
	v_cvt_i32_f32_e32 v119, v119
	v_cvt_i32_f32_e32 v120, v120
	v_cvt_i32_f32_e32 v121, v121
	v_perm_b32 v118, v119, v118, s16
	v_perm_b32 v120, v121, v120, s17
	v_or_b32_e32 v108, v118, v120
	v_lshlrev_b32_e32 v118, 16, v16
	v_and_b32_e32 v119, 0xffff0000, v16
	v_lshlrev_b32_e32 v120, 16, v17
	v_and_b32_e32 v121, 0xffff0000, v17
	v_pk_mul_f32 v[118:119], v[126:127], v[118:119]
	v_pk_mul_f32 v[120:121], v[126:127], v[120:121]
	v_rndne_f32_e32 v118, v118
	v_rndne_f32_e32 v119, v119
	v_rndne_f32_e32 v120, v120
	v_rndne_f32_e32 v121, v121
	v_cvt_i32_f32_e32 v118, v118
	v_cvt_i32_f32_e32 v119, v119
	v_cvt_i32_f32_e32 v120, v120
	v_cvt_i32_f32_e32 v121, v121
	v_perm_b32 v118, v119, v118, s16
	v_perm_b32 v120, v121, v120, s17
	v_or_b32_e32 v109, v118, v120
	global_store_dwordx2 v136, v[108:109], s[10:11] offset:1536
	s_waitcnt vmcnt(34)
; __device__ __forceinline__ unsigned q8(float x) { return (unsigned)(int)__builtin_rintf(x) & 0xffu; }
; __device__ __forceinline__ void rows_bf16_to_i8(Frame& F, const bf16* XBp, const unsigned* rmax, unsigned* X8, float* sx, int pitch4 = D / 4) {
;     ...
;         const float mx = __builtin_bit_cast(float, rb), inv = mx > 0.f ? 127.0f / mx : 0.f;
;         v2u* dst = (v2u*)(X8 + (size_t)m * pitch4) + lane;
; #pragma unroll
;         for (int j = 0; j < 8; ++j) { v2u o;
;             o.x = q8(blo(w[j].x) * inv) | (q8(bhi(w[j].x) * inv) << 8) | (q8(blo(w[j].y) * inv) << 16) | (q8(bhi(w[j].y) * inv) << 24);
;             o.y = q8(blo(w[j].z) * inv) | (q8(bhi(w[j].z) * inv) << 8) | (q8(blo(w[j].w) * inv) << 16) | (q8(bhi(w[j].w) * inv) << 24);
;             dst[64 * j] = o; }
;         if (lane == 0) sx[m] = mx * (1.0f / 127.0f);
; #pragma unroll
;         for (int j = 0; j < 8; ++j) w[j] = wn[j];
;         rb = rbn;
;     }
; }
	v_lshlrev_b32_e32 v118, 16, v18
	v_and_b32_e32 v119, 0xffff0000, v18
	v_lshlrev_b32_e32 v120, 16, v19
	v_and_b32_e32 v121, 0xffff0000, v19
	v_pk_mul_f32 v[118:119], v[126:127], v[118:119]
	v_pk_mul_f32 v[120:121], v[126:127], v[120:121]
	v_rndne_f32_e32 v118, v118
	v_rndne_f32_e32 v119, v119
	v_rndne_f32_e32 v120, v120
	v_rndne_f32_e32 v121, v121
	v_cvt_i32_f32_e32 v118, v118
	v_cvt_i32_f32_e32 v119, v119
	v_cvt_i32_f32_e32 v120, v120
	v_cvt_i32_f32_e32 v121, v121
	v_perm_b32 v118, v119, v118, s16
	v_perm_b32 v120, v121, v120, s17
	v_or_b32_e32 v110, v118, v120
	v_lshlrev_b32_e32 v118, 16, v20
	v_and_b32_e32 v119, 0xffff0000, v20
	v_lshlrev_b32_e32 v120, 16, v21
	v_and_b32_e32 v121, 0xffff0000, v21
	v_pk_mul_f32 v[118:119], v[126:127], v[118:119]
	v_pk_mul_f32 v[120:121], v[126:127], v[120:121]
	v_rndne_f32_e32 v118, v118
	v_rndne_f32_e32 v119, v119
	v_rndne_f32_e32 v120, v120
	v_rndne_f32_e32 v121, v121
	v_cvt_i32_f32_e32 v118, v118
	v_cvt_i32_f32_e32 v119, v119
	v_cvt_i32_f32_e32 v120, v120
	v_cvt_i32_f32_e32 v121, v121
	v_perm_b32 v118, v119, v118, s16
	v_perm_b32 v120, v121, v120, s17
	v_or_b32_e32 v111, v118, v120
	global_store_dwordx2 v136, v[110:111], s[10:11] offset:2048
	s_waitcnt vmcnt(34)
	v_lshlrev_b32_e32 v118, 16, v22
	v_and_b32_e32 v119, 0xffff0000, v22
	v_lshlrev_b32_e32 v120, 16, v23
	v_and_b32_e32 v121, 0xffff0000, v23
	v_pk_mul_f32 v[118:119], v[126:127], v[118:119]
	v_pk_mul_f32 v[120:121], v[126:127], v[120:121]
	v_rndne_f32_e32 v118, v118
	v_rndne_f32_e32 v119, v119
	v_rndne_f32_e32 v120, v120
	v_rndne_f32_e32 v121, v121
	v_cvt_i32_f32_e32 v118, v118
	v_cvt_i32_f32_e32 v119, v119
	v_cvt_i32_f32_e32 v120, v120
	v_cvt_i32_f32_e32 v121, v121
	v_perm_b32 v118, v119, v118, s16
	v_perm_b32 v120, v121, v120, s17
	v_or_b32_e32 v112, v118, v120
	v_lshlrev_b32_e32 v118, 16, v24
	v_and_b32_e32 v119, 0xffff0000, v24
	v_lshlrev_b32_e32 v120, 16, v25
	v_and_b32_e32 v121, 0xffff0000, v25
	v_pk_mul_f32 v[118:119], v[126:127], v[118:119]
	v_pk_mul_f32 v[120:121], v[126:127], v[120:121]
	v_rndne_f32_e32 v118, v118
	v_rndne_f32_e32 v119, v119
	v_rndne_f32_e32 v120, v120
	v_rndne_f32_e32 v121, v121
	v_cvt_i32_f32_e32 v118, v118
	v_cvt_i32_f32_e32 v119, v119
	v_cvt_i32_f32_e32 v120, v120
	v_cvt_i32_f32_e32 v121, v121
	v_perm_b32 v118, v119, v118, s16
	v_perm_b32 v120, v121, v120, s17
	v_or_b32_e32 v113, v118, v120
	global_store_dwordx2 v136, v[112:113], s[10:11] offset:2560
	s_waitcnt vmcnt(34)
	v_lshlrev_b32_e32 v118, 16, v26
	v_and_b32_e32 v119, 0xffff0000, v26
	v_lshlrev_b32_e32 v120, 16, v27
	v_and_b32_e32 v121, 0xffff0000, v27
	v_pk_mul_f32 v[118:119], v[126:127], v[118:119]
	v_pk_mul_f32 v[120:121], v[126:127], v[120:121]
	v_rndne_f32_e32 v118, v118
	v_rndne_f32_e32 v119, v119
	v_rndne_f32_e32 v120, v120
	v_rndne_f32_e32 v121, v121
	v_cvt_i32_f32_e32 v118, v118
	v_cvt_i32_f32_e32 v119, v119
	v_cvt_i32_f32_e32 v120, v120
	v_cvt_i32_f32_e32 v121, v121
	v_perm_b32 v118, v119, v118, s16
	v_perm_b32 v120, v121, v120, s17
	v_or_b32_e32 v114, v118, v120
	v_lshlrev_b32_e32 v118, 16, v28
	v_and_b32_e32 v119, 0xffff0000, v28
	v_lshlrev_b32_e32 v120, 16, v29
	v_and_b32_e32 v121, 0xffff0000, v29
	v_pk_mul_f32 v[118:119], v[126:127], v[118:119]
	v_pk_mul_f32 v[120:121], v[126:127], v[120:121]
	v_rndne_f32_e32 v118, v118
	v_rndne_f32_e32 v119, v119
	v_rndne_f32_e32 v120, v120
	v_rndne_f32_e32 v121, v121
	v_cvt_i32_f32_e32 v118, v118
	v_cvt_i32_f32_e32 v119, v119
	v_cvt_i32_f32_e32 v120, v120
	v_cvt_i32_f32_e32 v121, v121
	v_perm_b32 v118, v119, v118, s16
	v_perm_b32 v120, v121, v120, s17
	v_or_b32_e32 v115, v118, v120
	global_store_dwordx2 v136, v[114:115], s[10:11] offset:3072
	s_waitcnt vmcnt(34)
	v_lshlrev_b32_e32 v118, 16, v30
	v_and_b32_e32 v119, 0xffff0000, v30
	v_lshlrev_b32_e32 v120, 16, v31
	v_and_b32_e32 v121, 0xffff0000, v31
	v_pk_mul_f32 v[118:119], v[126:127], v[118:119]
	v_pk_mul_f32 v[120:121], v[126:127], v[120:121]
	v_rndne_f32_e32 v118, v118
	v_rndne_f32_e32 v119, v119
	v_rndne_f32_e32 v120, v120
	v_rndne_f32_e32 v121, v121
	v_cvt_i32_f32_e32 v118, v118
	v_cvt_i32_f32_e32 v119, v119
	v_cvt_i32_f32_e32 v120, v120
	v_cvt_i32_f32_e32 v121, v121
	v_perm_b32 v118, v119, v118, s16
	v_perm_b32 v120, v121, v120, s17
	v_or_b32_e32 v116, v118, v120
	v_lshlrev_b32_e32 v118, 16, v32
	v_and_b32_e32 v119, 0xffff0000, v32
	v_lshlrev_b32_e32 v120, 16, v33
	v_and_b32_e32 v121, 0xffff0000, v33
	v_pk_mul_f32 v[118:119], v[126:127], v[118:119]
	v_pk_mul_f32 v[120:121], v[126:127], v[120:121]
	v_rndne_f32_e32 v118, v118
	v_rndne_f32_e32 v119, v119
	v_rndne_f32_e32 v120, v120
	v_rndne_f32_e32 v121, v121
	v_cvt_i32_f32_e32 v118, v118
	v_cvt_i32_f32_e32 v119, v119
	v_cvt_i32_f32_e32 v120, v120
	v_cvt_i32_f32_e32 v121, v121
	v_perm_b32 v118, v119, v118, s16
	v_perm_b32 v120, v121, v120, s17
	v_or_b32_e32 v117, v118, v120
	global_store_dwordx2 v136, v[116:117], s[10:11] offset:3584
	s_mov_b64 exec, s[12:13]
	global_store_dword v137, v138, s[8:9]
	s_mov_b64 exec, -1
	s_add_u32 s10, s10, 0x800000
	s_addc_u32 s11, s11, 0
	s_add_u32 s8, s8, 0x2000
	s_addc_u32 s9, s9, 0
	s_waitcnt vmcnt(26)
	v_div_scale_f32 v128, s[14:15], v99, v99, s3
	v_rcp_f32_e32 v129, v128
	v_div_scale_f32 v130, vcc, s3, v99, s3
	v_fma_f32 v131, -v128, v129, 1.0
	v_fmac_f32_e32 v129, v131, v129
	v_mul_f32_e32 v131, v130, v129
	v_fma_f32 v132, -v128, v131, v130
	v_fmac_f32_e32 v131, v132, v129
	v_fma_f32 v128, -v128, v131, v130
	v_div_fmas_f32 v128, v128, v129, v131
	v_div_fixup_f32 v128, v128, v99, s3
	v_cmp_lt_f32_e32 vcc, 0, v99
	v_mul_f32_e32 v138, 0x3c010204, v99
	v_cndmask_b32_e32 v126, 0, v128, vcc
	v_mov_b32_e32 v127, v126
	s_waitcnt vmcnt(25)
; __device__ __forceinline__ unsigned q8(float x) { return (unsigned)(int)__builtin_rintf(x) & 0xffu; }
; __device__ __forceinline__ void rows_bf16_to_i8(Frame& F, const bf16* XBp, const unsigned* rmax, unsigned* X8, float* sx, int pitch4 = D / 4) {
;     ...
;         const float mx = __builtin_bit_cast(float, rb), inv = mx > 0.f ? 127.0f / mx : 0.f;
;         v2u* dst = (v2u*)(X8 + (size_t)m * pitch4) + lane;
; #pragma unroll
;         for (int j = 0; j < 8; ++j) { v2u o;
;             o.x = q8(blo(w[j].x) * inv) | (q8(bhi(w[j].x) * inv) << 8) | (q8(blo(w[j].y) * inv) << 16) | (q8(bhi(w[j].y) * inv) << 24);
;             o.y = q8(blo(w[j].z) * inv) | (q8(bhi(w[j].z) * inv) << 8) | (q8(blo(w[j].w) * inv) << 16) | (q8(bhi(w[j].w) * inv) << 24);
;             dst[64 * j] = o; }
	v_lshlrev_b32_e32 v118, 16, v34
	v_and_b32_e32 v119, 0xffff0000, v34
	v_lshlrev_b32_e32 v120, 16, v35
	v_and_b32_e32 v121, 0xffff0000, v35
	v_pk_mul_f32 v[118:119], v[126:127], v[118:119]
	v_pk_mul_f32 v[120:121], v[126:127], v[120:121]
	v_rndne_f32_e32 v118, v118
	v_rndne_f32_e32 v119, v119
	v_rndne_f32_e32 v120, v120
	v_rndne_f32_e32 v121, v121
	v_cvt_i32_f32_e32 v118, v118
	v_cvt_i32_f32_e32 v119, v119
	v_cvt_i32_f32_e32 v120, v120
	v_cvt_i32_f32_e32 v121, v121
	v_perm_b32 v118, v119, v118, s16
	v_perm_b32 v120, v121, v120, s17
	v_or_b32_e32 v102, v118, v120
	v_lshlrev_b32_e32 v118, 16, v36
	v_and_b32_e32 v119, 0xffff0000, v36
	v_lshlrev_b32_e32 v120, 16, v37
	v_and_b32_e32 v121, 0xffff0000, v37
	v_pk_mul_f32 v[118:119], v[126:127], v[118:119]
	v_pk_mul_f32 v[120:121], v[126:127], v[120:121]
	v_rndne_f32_e32 v118, v118
	v_rndne_f32_e32 v119, v119
	v_rndne_f32_e32 v120, v120
	v_rndne_f32_e32 v121, v121
	v_cvt_i32_f32_e32 v118, v118
	v_cvt_i32_f32_e32 v119, v119
	v_cvt_i32_f32_e32 v120, v120
	v_cvt_i32_f32_e32 v121, v121
	v_perm_b32 v118, v119, v118, s16
	v_perm_b32 v120, v121, v120, s17
	v_or_b32_e32 v103, v118, v120
	global_store_dwordx2 v136, v[102:103], s[10:11] offset:0
	s_waitcnt vmcnt(25)
	v_lshlrev_b32_e32 v118, 16, v38
	v_and_b32_e32 v119, 0xffff0000, v38
	v_lshlrev_b32_e32 v120, 16, v39
	v_and_b32_e32 v121, 0xffff0000, v39
	v_pk_mul_f32 v[118:119], v[126:127], v[118:119]
	v_pk_mul_f32 v[120:121], v[126:127], v[120:121]
	v_rndne_f32_e32 v118, v118
	v_rndne_f32_e32 v119, v119
	v_rndne_f32_e32 v120, v120
	v_rndne_f32_e32 v121, v121
	v_cvt_i32_f32_e32 v118, v118
	v_cvt_i32_f32_e32 v119, v119
	v_cvt_i32_f32_e32 v120, v120
	v_cvt_i32_f32_e32 v121, v121
	v_perm_b32 v118, v119, v118, s16
	v_perm_b32 v120, v121, v120, s17
	v_or_b32_e32 v104, v118, v120
	v_lshlrev_b32_e32 v118, 16, v40
	v_and_b32_e32 v119, 0xffff0000, v40
	v_lshlrev_b32_e32 v120, 16, v41
	v_and_b32_e32 v121, 0xffff0000, v41
	v_pk_mul_f32 v[118:119], v[126:127], v[118:119]
	v_pk_mul_f32 v[120:121], v[126:127], v[120:121]
	v_rndne_f32_e32 v118, v118
	v_rndne_f32_e32 v119, v119
	v_rndne_f32_e32 v120, v120
	v_rndne_f32_e32 v121, v121
	v_cvt_i32_f32_e32 v118, v118
	v_cvt_i32_f32_e32 v119, v119
	v_cvt_i32_f32_e32 v120, v120
	v_cvt_i32_f32_e32 v121, v121
	v_perm_b32 v118, v119, v118, s16
	v_perm_b32 v120, v121, v120, s17
	v_or_b32_e32 v105, v118, v120
	global_store_dwordx2 v136, v[104:105], s[10:11] offset:512
	s_waitcnt vmcnt(25)
	v_lshlrev_b32_e32 v118, 16, v42
	v_and_b32_e32 v119, 0xffff0000, v42
	v_lshlrev_b32_e32 v120, 16, v43
	v_and_b32_e32 v121, 0xffff0000, v43
	v_pk_mul_f32 v[118:119], v[126:127], v[118:119]
	v_pk_mul_f32 v[120:121], v[126:127], v[120:121]
	v_rndne_f32_e32 v118, v118
	v_rndne_f32_e32 v119, v119
	v_rndne_f32_e32 v120, v120
	v_rndne_f32_e32 v121, v121
	v_cvt_i32_f32_e32 v118, v118
	v_cvt_i32_f32_e32 v119, v119
	v_cvt_i32_f32_e32 v120, v120
	v_cvt_i32_f32_e32 v121, v121
	v_perm_b32 v118, v119, v118, s16
	v_perm_b32 v120, v121, v120, s17
	v_or_b32_e32 v106, v118, v120
	v_lshlrev_b32_e32 v118, 16, v44
	v_and_b32_e32 v119, 0xffff0000, v44
	v_lshlrev_b32_e32 v120, 16, v45
	v_and_b32_e32 v121, 0xffff0000, v45
	v_pk_mul_f32 v[118:119], v[126:127], v[118:119]
	v_pk_mul_f32 v[120:121], v[126:127], v[120:121]
	v_rndne_f32_e32 v118, v118
	v_rndne_f32_e32 v119, v119
	v_rndne_f32_e32 v120, v120
	v_rndne_f32_e32 v121, v121
	v_cvt_i32_f32_e32 v118, v118
	v_cvt_i32_f32_e32 v119, v119
	v_cvt_i32_f32_e32 v120, v120
	v_cvt_i32_f32_e32 v121, v121
	v_perm_b32 v118, v119, v118, s16
	v_perm_b32 v120, v121, v120, s17
	v_or_b32_e32 v107, v118, v120
	global_store_dwordx2 v136, v[106:107], s[10:11] offset:1024
	s_waitcnt vmcnt(25)
	v_lshlrev_b32_e32 v118, 16, v46
	v_and_b32_e32 v119, 0xffff0000, v46
	v_lshlrev_b32_e32 v120, 16, v47
	v_and_b32_e32 v121, 0xffff0000, v47
	v_pk_mul_f32 v[118:119], v[126:127], v[118:119]
	v_pk_mul_f32 v[120:121], v[126:127], v[120:121]
	v_rndne_f32_e32 v118, v118
	v_rndne_f32_e32 v119, v119
	v_rndne_f32_e32 v120, v120
	v_rndne_f32_e32 v121, v121
	v_cvt_i32_f32_e32 v118, v118
	v_cvt_i32_f32_e32 v119, v119
	v_cvt_i32_f32_e32 v120, v120
	v_cvt_i32_f32_e32 v121, v121
	v_perm_b32 v118, v119, v118, s16
	v_perm_b32 v120, v121, v120, s17
	v_or_b32_e32 v108, v118, v120
	v_lshlrev_b32_e32 v118, 16, v48
	v_and_b32_e32 v119, 0xffff0000, v48
	v_lshlrev_b32_e32 v120, 16, v49
	v_and_b32_e32 v121, 0xffff0000, v49
	v_pk_mul_f32 v[118:119], v[126:127], v[118:119]
	v_pk_mul_f32 v[120:121], v[126:127], v[120:121]
	v_rndne_f32_e32 v118, v118
	v_rndne_f32_e32 v119, v119
	v_rndne_f32_e32 v120, v120
	v_rndne_f32_e32 v121, v121
	v_cvt_i32_f32_e32 v118, v118
	v_cvt_i32_f32_e32 v119, v119
	v_cvt_i32_f32_e32 v120, v120
	v_cvt_i32_f32_e32 v121, v121
	v_perm_b32 v118, v119, v118, s16
	v_perm_b32 v120, v121, v120, s17
	v_or_b32_e32 v109, v118, v120
	global_store_dwordx2 v136, v[108:109], s[10:11] offset:1536
	s_waitcnt vmcnt(25)
	v_lshlrev_b32_e32 v118, 16, v50
	v_and_b32_e32 v119, 0xffff0000, v50
	v_lshlrev_b32_e32 v120, 16, v51
	v_and_b32_e32 v121, 0xffff0000, v51
	v_pk_mul_f32 v[118:119], v[126:127], v[118:119]
	v_pk_mul_f32 v[120:121], v[126:127], v[120:121]
	v_rndne_f32_e32 v118, v118
	v_rndne_f32_e32 v119, v119
	v_rndne_f32_e32 v120, v120
	v_rndne_f32_e32 v121, v121
	v_cvt_i32_f32_e32 v118, v118
	v_cvt_i32_f32_e32 v119, v119
	v_cvt_i32_f32_e32 v120, v120
	v_cvt_i32_f32_e32 v121, v121
	v_perm_b32 v118, v119, v118, s16
	v_perm_b32 v120, v121, v120, s17
	v_or_b32_e32 v110, v118, v120
	v_lshlrev_b32_e32 v118, 16, v52
	v_and_b32_e32 v119, 0xffff0000, v52
	v_lshlrev_b32_e32 v120, 16, v53
	v_and_b32_e32 v121, 0xffff0000, v53
	v_pk_mul_f32 v[118:119], v[126:127], v[118:119]
	v_pk_mul_f32 v[120:121], v[126:127], v[120:121]
	v_rndne_f32_e32 v118, v118
	v_rndne_f32_e32 v119, v119
	v_rndne_f32_e32 v120, v120
	v_rndne_f32_e32 v121, v121
	v_cvt_i32_f32_e32 v118, v118
	v_cvt_i32_f32_e32 v119, v119
	v_cvt_i32_f32_e32 v120, v120
	v_cvt_i32_f32_e32 v121, v121
	v_perm_b32 v118, v119, v118, s16
	v_perm_b32 v120, v121, v120, s17
	v_or_b32_e32 v111, v118, v120
	global_store_dwordx2 v136, v[110:111], s[10:11] offset:2048
	s_waitcnt vmcnt(25)
; __device__ __forceinline__ unsigned q8(float x) { return (unsigned)(int)__builtin_rintf(x) & 0xffu; }
; __device__ __forceinline__ void rows_bf16_to_i8(Frame& F, const bf16* XBp, const unsigned* rmax, unsigned* X8, float* sx, int pitch4 = D / 4) {
;     const int gw = F.vcu * NWAVES + F.wave, NGW = F.G * NWAVES, lane = F.lane;
;     v4u w[8], wn[8]; unsigned rb = 0, rbn = 0;
;     int m = gw;
;     if (m < M) { const v4u* src = (const v4u*)(XBp + (size_t)m * D) + lane; rb = rmax[m];
; #pragma unroll
;         for (int j = 0; j < 8; ++j) w[j] = src[64 * j]; }
;     for (; m < M; m += NGW) {
;         const int mn = m + NGW;
;         if (mn < M) { const v4u* src = (const v4u*)(XBp + (size_t)mn * D) + lane; rbn = rmax[mn];
;     ...
;         const float mx = __builtin_bit_cast(float, rb), inv = mx > 0.f ? 127.0f / mx : 0.f;
;         v2u* dst = (v2u*)(X8 + (size_t)m * pitch4) + lane;
; #pragma unroll
;         for (int j = 0; j < 8; ++j) { v2u o;
;             o.x = q8(blo(w[j].x) * inv) | (q8(bhi(w[j].x) * inv) << 8) | (q8(blo(w[j].y) * inv) << 16) | (q8(bhi(w[j].y) * inv) << 24);
;             o.y = q8(blo(w[j].z) * inv) | (q8(bhi(w[j].z) * inv) << 8) | (q8(blo(w[j].w) * inv) << 16) | (q8(bhi(w[j].w) * inv) << 24);
;             dst[64 * j] = o; }
;         if (lane == 0) sx[m] = mx * (1.0f / 127.0f);
; #pragma unroll
;         for (int j = 0; j < 8; ++j) w[j] = wn[j];
;         rb = rbn;
;     }
; }
	v_lshlrev_b32_e32 v118, 16, v54
	v_and_b32_e32 v119, 0xffff0000, v54
	v_lshlrev_b32_e32 v120, 16, v55
	v_and_b32_e32 v121, 0xffff0000, v55
	v_pk_mul_f32 v[118:119], v[126:127], v[118:119]
	v_pk_mul_f32 v[120:121], v[126:127], v[120:121]
	v_rndne_f32_e32 v118, v118
	v_rndne_f32_e32 v119, v119
	v_rndne_f32_e32 v120, v120
	v_rndne_f32_e32 v121, v121
	v_cvt_i32_f32_e32 v118, v118
	v_cvt_i32_f32_e32 v119, v119
	v_cvt_i32_f32_e32 v120, v120
	v_cvt_i32_f32_e32 v121, v121
	v_perm_b32 v118, v119, v118, s16
	v_perm_b32 v120, v121, v120, s17
	v_or_b32_e32 v112, v118, v120
	v_lshlrev_b32_e32 v118, 16, v56
	v_and_b32_e32 v119, 0xffff0000, v56
	v_lshlrev_b32_e32 v120, 16, v57
	v_and_b32_e32 v121, 0xffff0000, v57
	v_pk_mul_f32 v[118:119], v[126:127], v[118:119]
	v_pk_mul_f32 v[120:121], v[126:127], v[120:121]
	v_rndne_f32_e32 v118, v118
	v_rndne_f32_e32 v119, v119
	v_rndne_f32_e32 v120, v120
	v_rndne_f32_e32 v121, v121
	v_cvt_i32_f32_e32 v118, v118
	v_cvt_i32_f32_e32 v119, v119
	v_cvt_i32_f32_e32 v120, v120
	v_cvt_i32_f32_e32 v121, v121
	v_perm_b32 v118, v119, v118, s16
	v_perm_b32 v120, v121, v120, s17
	v_or_b32_e32 v113, v118, v120
	global_store_dwordx2 v136, v[112:113], s[10:11] offset:2560
	s_waitcnt vmcnt(25)
	v_lshlrev_b32_e32 v118, 16, v58
	v_and_b32_e32 v119, 0xffff0000, v58
	v_lshlrev_b32_e32 v120, 16, v59
	v_and_b32_e32 v121, 0xffff0000, v59
	v_pk_mul_f32 v[118:119], v[126:127], v[118:119]
	v_pk_mul_f32 v[120:121], v[126:127], v[120:121]
	v_rndne_f32_e32 v118, v118
	v_rndne_f32_e32 v119, v119
	v_rndne_f32_e32 v120, v120
	v_rndne_f32_e32 v121, v121
	v_cvt_i32_f32_e32 v118, v118
	v_cvt_i32_f32_e32 v119, v119
	v_cvt_i32_f32_e32 v120, v120
	v_cvt_i32_f32_e32 v121, v121
	v_perm_b32 v118, v119, v118, s16
	v_perm_b32 v120, v121, v120, s17
	v_or_b32_e32 v114, v118, v120
	v_lshlrev_b32_e32 v118, 16, v60
	v_and_b32_e32 v119, 0xffff0000, v60
	v_lshlrev_b32_e32 v120, 16, v61
	v_and_b32_e32 v121, 0xffff0000, v61
	v_pk_mul_f32 v[118:119], v[126:127], v[118:119]
	v_pk_mul_f32 v[120:121], v[126:127], v[120:121]
	v_rndne_f32_e32 v118, v118
	v_rndne_f32_e32 v119, v119
	v_rndne_f32_e32 v120, v120
	v_rndne_f32_e32 v121, v121
	v_cvt_i32_f32_e32 v118, v118
	v_cvt_i32_f32_e32 v119, v119
	v_cvt_i32_f32_e32 v120, v120
	v_cvt_i32_f32_e32 v121, v121
	v_perm_b32 v118, v119, v118, s16
	v_perm_b32 v120, v121, v120, s17
	v_or_b32_e32 v115, v118, v120
	global_store_dwordx2 v136, v[114:115], s[10:11] offset:3072
	s_waitcnt vmcnt(25)
	v_lshlrev_b32_e32 v118, 16, v62
	v_and_b32_e32 v119, 0xffff0000, v62
	v_lshlrev_b32_e32 v120, 16, v63
	v_and_b32_e32 v121, 0xffff0000, v63
	v_pk_mul_f32 v[118:119], v[126:127], v[118:119]
	v_pk_mul_f32 v[120:121], v[126:127], v[120:121]
	v_rndne_f32_e32 v118, v118
	v_rndne_f32_e32 v119, v119
	v_rndne_f32_e32 v120, v120
	v_rndne_f32_e32 v121, v121
	v_cvt_i32_f32_e32 v118, v118
	v_cvt_i32_f32_e32 v119, v119
	v_cvt_i32_f32_e32 v120, v120
	v_cvt_i32_f32_e32 v121, v121
	v_perm_b32 v118, v119, v118, s16
	v_perm_b32 v120, v121, v120, s17
	v_or_b32_e32 v116, v118, v120
	v_lshlrev_b32_e32 v118, 16, v64
	v_and_b32_e32 v119, 0xffff0000, v64
	v_lshlrev_b32_e32 v120, 16, v65
	v_and_b32_e32 v121, 0xffff0000, v65
	v_pk_mul_f32 v[118:119], v[126:127], v[118:119]
	v_pk_mul_f32 v[120:121], v[126:127], v[120:121]
	v_rndne_f32_e32 v118, v118
	v_rndne_f32_e32 v119, v119
	v_rndne_f32_e32 v120, v120
	v_rndne_f32_e32 v121, v121
	v_cvt_i32_f32_e32 v118, v118
	v_cvt_i32_f32_e32 v119, v119
	v_cvt_i32_f32_e32 v120, v120
	v_cvt_i32_f32_e32 v121, v121
	v_perm_b32 v118, v119, v118, s16
	v_perm_b32 v120, v121, v120, s17
	v_or_b32_e32 v117, v118, v120
	global_store_dwordx2 v136, v[116:117], s[10:11] offset:3584
	s_mov_b64 exec, s[12:13]
	global_store_dword v137, v138, s[8:9]
	s_mov_b64 exec, -1
	s_add_u32 s10, s10, 0x800000
	s_addc_u32 s11, s11, 0
	s_add_u32 s8, s8, 0x2000
	s_addc_u32 s9, s9, 0
	s_branch .LBB0_2228
.Lrows3_fb_gpp:
	v_readlane_b32 s0, v254, 5
	s_lshl_b32 s0, s0, 3
	v_readlane_b32 s1, v254, 39
	s_add_i32 s0, s0, s1
	s_cmpk_gt_i32 s0, 0x3fff
	s_cbranch_scc1 .LBB0_2228
	s_ashr_i32 s1, s0, 31
	s_lshl_b32 s2, s70, 3
	s_lshl_b64 s[4:5], s[0:1], 13
	v_readlane_b32 s6, v254, 40
	v_readlane_b32 s7, v254, 41
	s_add_u32 s4, s6, s4
	s_addc_u32 s5, s7, s5
	v_lshlrev_b32_e32 v66, 4, v232
	v_mov_b32_e32 v67, 0
	s_lshl_b64 s[6:7], s[0:1], 2
	s_waitcnt vmcnt(0) lgkmcnt(0)
	v_lshl_add_u64 v[2:3], s[4:5], 0, v[66:67]
	s_add_u32 s8, s96, s6
	s_movk_i32 s3, 0x1000
	s_addc_u32 s9, s97, s7
	v_mov_b32_e32 v4, 0xd0000
	v_add_co_u32_e32 v2, vcc, s3, v2
	global_load_dwordx4 v[58:61], v66, s[4:5] offset:1024
	global_load_dwordx4 v[54:57], v66, s[4:5] offset:2048
	global_load_dwordx4 v[50:53], v66, s[4:5] offset:3072
	v_addc_co_u32_e32 v3, vcc, 0, v3, vcc
	global_load_dword v1, v4, s[8:9]
	global_load_dwordx4 v[46:49], v[2:3], off
	global_load_dwordx4 v[42:45], v[2:3], off offset:1024
	global_load_dwordx4 v[38:41], v[2:3], off offset:2048
	global_load_dwordx4 v[62:65], v66, s[4:5]
	global_load_dwordx4 v[34:37], v[2:3], off offset:3072
	s_add_u32 s16, s6, 0x4d4c0000
	s_addc_u32 s17, s7, 0
	s_add_i32 s10, s0, s2
	s_ashr_i32 s3, s2, 31
	s_lshl_b64 s[8:9], s[0:1], 12
	s_ashr_i32 s11, s10, 31
	s_lshl_b64 s[6:7], s[2:3], 2
	v_lshl_or_b32 v68, v232, 3, s8
	v_mov_b32_e32 v69, s9
	s_lshl_b64 s[8:9], s[2:3], 12
	s_lshl_b64 s[12:13], s[10:11], 2
	s_add_u32 s1, s12, 0xd0000
	s_addc_u32 s18, s13, 0
	s_lshl_b64 s[10:11], s[10:11], 13
	v_cmp_eq_u32_e64 s[4:5], 0, v232
	v_or_b32_e32 v70, s10, v66
	v_mov_b32_e32 v71, s11
	s_lshl_b64 s[10:11], s[2:3], 13
	s_mov_b32 s3, 0x42fe0000
	s_mov_b32 s19, 0xc0c0500
	s_mov_b32 s20, 0x40c0c00
	s_mov_b32 s21, 0x8200000
	v_mov_b32_e32 v66, 0
	s_branch .LBB0_2224
